# baseline (speedup 1.0000x reference)
.LBB0_380:
	v_lshl_or_b32 v152, s30, 7, v156
	v_readlane_b32 s16, v253, 20
	v_ashrrev_i32_e32 v153, 31, v152
	v_readlane_b32 s17, v253, 21
	v_mul_f32_e32 v118, 0xbfb8aa3b, v118
	v_mul_f32_e32 v114, 0xbfb8aa3b, v114
	v_lshl_add_u64 v[140:141], v[152:153], 2, s[16:17]
	global_load_dwordx4 v[148:151], v[140:141], off offset:16
	s_nop 0
	global_load_dwordx4 v[140:143], v[140:141], off
	v_lshlrev_b64 v[152:153], 1, v[152:153]
	v_mul_f32_e32 v119, 0xbfb8aa3b, v119
	v_mul_f32_e32 v115, 0xbfb8aa3b, v115
	v_mul_f32_e32 v120, 0xbfb8aa3b, v120
	v_mul_f32_e32 v116, 0xbfb8aa3b, v116
	v_mul_f32_e32 v121, 0xbfb8aa3b, v121
	v_mul_f32_e32 v117, 0xbfb8aa3b, v117
	v_exp_f32_e32 v118, v118
	v_exp_f32_e32 v114, v114
	v_exp_f32_e32 v119, v119
	v_exp_f32_e32 v115, v115
	v_exp_f32_e32 v120, v120
	v_exp_f32_e32 v116, v116
	v_exp_f32_e32 v121, v121
	v_exp_f32_e32 v117, v117
	v_add_f32_e32 v118, 1.0, v118
	v_add_f32_e32 v114, 1.0, v114
	v_add_f32_e32 v119, 1.0, v119
	v_add_f32_e32 v115, 1.0, v115
	v_add_f32_e32 v120, 1.0, v120
	v_add_f32_e32 v116, 1.0, v116
	v_add_f32_e32 v121, 1.0, v121
	v_add_f32_e32 v117, 1.0, v117
	v_rcp_f32_e32 v118, v118
	v_rcp_f32_e32 v114, v114
	v_rcp_f32_e32 v119, v119
	v_rcp_f32_e32 v115, v115
	v_rcp_f32_e32 v120, v120
	v_rcp_f32_e32 v116, v116
	v_rcp_f32_e32 v121, v121
	v_rcp_f32_e32 v117, v117
	v_pk_mul_f32 v[118:119], v[126:127], v[118:119]
	v_pk_mul_f32 v[114:115], v[122:123], v[114:115]
	v_pk_mul_f32 v[120:121], v[128:129], v[120:121]
	v_pk_mul_f32 v[116:117], v[124:125], v[116:117]
	v_mul_f32_e32 v102, 0xbfb8aa3b, v102
	v_mul_f32_e32 v98, 0xbfb8aa3b, v98
	v_mul_f32_e32 v103, 0xbfb8aa3b, v103
	v_mul_f32_e32 v99, 0xbfb8aa3b, v99
	v_mul_f32_e32 v104, 0xbfb8aa3b, v104
	v_mul_f32_e32 v100, 0xbfb8aa3b, v100
	v_mul_f32_e32 v105, 0xbfb8aa3b, v105
	v_mul_f32_e32 v101, 0xbfb8aa3b, v101
	v_exp_f32_e32 v102, v102
	v_exp_f32_e32 v98, v98
	v_exp_f32_e32 v103, v103
	v_exp_f32_e32 v99, v99
	v_exp_f32_e32 v104, v104
	v_exp_f32_e32 v100, v100
	v_exp_f32_e32 v105, v105
	v_exp_f32_e32 v101, v101
	v_add_f32_e32 v102, 1.0, v102
	v_add_f32_e32 v98, 1.0, v98
	v_add_f32_e32 v103, 1.0, v103
	v_add_f32_e32 v99, 1.0, v99
	v_add_f32_e32 v104, 1.0, v104
	v_add_f32_e32 v100, 1.0, v100
	v_add_f32_e32 v105, 1.0, v105
	v_add_f32_e32 v101, 1.0, v101
	v_rcp_f32_e32 v102, v102
	v_rcp_f32_e32 v98, v98
	v_rcp_f32_e32 v103, v103
	v_rcp_f32_e32 v99, v99
	v_rcp_f32_e32 v104, v104
	v_rcp_f32_e32 v100, v100
	v_rcp_f32_e32 v105, v105
	v_rcp_f32_e32 v101, v101
	v_pk_mul_f32 v[102:103], v[110:111], v[102:103]
	v_pk_mul_f32 v[98:99], v[106:107], v[98:99]
	v_pk_mul_f32 v[104:105], v[112:113], v[104:105]
	v_pk_mul_f32 v[100:101], v[108:109], v[100:101]
	v_mul_f32_e32 v86, 0xbfb8aa3b, v86
	v_mul_f32_e32 v82, 0xbfb8aa3b, v82
	v_mul_f32_e32 v87, 0xbfb8aa3b, v87
	v_mul_f32_e32 v83, 0xbfb8aa3b, v83
	v_mul_f32_e32 v88, 0xbfb8aa3b, v88
	v_mul_f32_e32 v84, 0xbfb8aa3b, v84
	v_mul_f32_e32 v89, 0xbfb8aa3b, v89
	v_mul_f32_e32 v85, 0xbfb8aa3b, v85
	s_waitcnt vmcnt(0)
	v_pk_add_f32 v[146:147], v[140:141], 1.0 op_sel_hi:[1,0]
	v_pk_add_f32 v[140:141], v[150:151], 1.0 op_sel_hi:[1,0]
	v_lshl_add_u32 v150, s29, 8, v154
	v_ashrrev_i32_e32 v151, 31, v150
	v_pk_add_f32 v[144:145], v[142:143], 1.0 op_sel_hi:[1,0]
	v_pk_add_f32 v[142:143], v[148:149], 1.0 op_sel_hi:[1,0]
	v_lshlrev_b64 v[148:149], 12, v[150:151]
	v_lshl_add_u64 v[148:149], s[50:51], 0, v[148:149]
	v_lshl_add_u64 v[148:149], v[148:149], 0, v[152:153]
	global_load_dwordx4 v[158:161], v[148:149], off
	v_exp_f32_e32 v86, v86
	v_exp_f32_e32 v82, v82
	v_exp_f32_e32 v87, v87
	v_exp_f32_e32 v83, v83
	v_exp_f32_e32 v88, v88
	v_exp_f32_e32 v84, v84
	v_exp_f32_e32 v89, v89
	v_exp_f32_e32 v85, v85
	v_add_f32_e32 v86, 1.0, v86
	v_add_f32_e32 v82, 1.0, v82
	v_add_f32_e32 v87, 1.0, v87
	v_add_f32_e32 v83, 1.0, v83
	v_add_f32_e32 v88, 1.0, v88
	v_add_f32_e32 v84, 1.0, v84
	v_add_f32_e32 v89, 1.0, v89
	v_add_f32_e32 v85, 1.0, v85
	v_rcp_f32_e32 v86, v86
	v_rcp_f32_e32 v82, v82
	v_rcp_f32_e32 v87, v87
	v_rcp_f32_e32 v83, v83
	v_rcp_f32_e32 v88, v88
	v_rcp_f32_e32 v84, v84
	v_rcp_f32_e32 v89, v89
	v_rcp_f32_e32 v85, v85
	v_pk_mul_f32 v[86:87], v[94:95], v[86:87]
	v_pk_mul_f32 v[82:83], v[90:91], v[82:83]
	v_pk_mul_f32 v[88:89], v[96:97], v[88:89]
	v_pk_mul_f32 v[84:85], v[92:93], v[84:85]
	v_mul_f32_e32 v70, 0xbfb8aa3b, v70
	v_mul_f32_e32 v66, 0xbfb8aa3b, v66
	v_mul_f32_e32 v71, 0xbfb8aa3b, v71
	v_mul_f32_e32 v67, 0xbfb8aa3b, v67
	v_mul_f32_e32 v72, 0xbfb8aa3b, v72
	v_mul_f32_e32 v68, 0xbfb8aa3b, v68
	v_mul_f32_e32 v73, 0xbfb8aa3b, v73
	v_mul_f32_e32 v69, 0xbfb8aa3b, v69
	v_exp_f32_e32 v70, v70
	v_exp_f32_e32 v66, v66
	v_exp_f32_e32 v71, v71
	v_exp_f32_e32 v67, v67
	v_exp_f32_e32 v72, v72
	v_exp_f32_e32 v68, v68
	v_exp_f32_e32 v73, v73
	v_exp_f32_e32 v69, v69
	v_add_f32_e32 v70, 1.0, v70
	v_add_f32_e32 v66, 1.0, v66
	v_add_f32_e32 v71, 1.0, v71
	v_add_f32_e32 v67, 1.0, v67
	v_add_f32_e32 v72, 1.0, v72
	v_add_f32_e32 v68, 1.0, v68
	v_add_f32_e32 v73, 1.0, v73
	v_add_f32_e32 v69, 1.0, v69
	v_rcp_f32_e32 v70, v70
	v_rcp_f32_e32 v66, v66
	v_rcp_f32_e32 v71, v71
	v_rcp_f32_e32 v67, v67
	v_rcp_f32_e32 v72, v72
	v_rcp_f32_e32 v68, v68
	v_rcp_f32_e32 v73, v73
	v_rcp_f32_e32 v69, v69
	v_pk_mul_f32 v[70:71], v[78:79], v[70:71]
	v_pk_mul_f32 v[66:67], v[74:75], v[66:67]
	v_pk_mul_f32 v[72:73], v[80:81], v[72:73]
	v_pk_mul_f32 v[68:69], v[76:77], v[68:69]
	s_mov_b32 s3, 0x80000
	v_mul_f32_e32 v54, 0xbfb8aa3b, v54
	v_mul_f32_e32 v50, 0xbfb8aa3b, v50
	v_mul_f32_e32 v55, 0xbfb8aa3b, v55
	v_mul_f32_e32 v51, 0xbfb8aa3b, v51
	v_mul_f32_e32 v56, 0xbfb8aa3b, v56
	v_mul_f32_e32 v52, 0xbfb8aa3b, v52
	v_mul_f32_e32 v57, 0xbfb8aa3b, v57
	v_mul_f32_e32 v53, 0xbfb8aa3b, v53
	v_exp_f32_e32 v54, v54
	v_exp_f32_e32 v50, v50
	v_exp_f32_e32 v55, v55
	v_exp_f32_e32 v51, v51
	v_exp_f32_e32 v56, v56
	v_exp_f32_e32 v52, v52
	s_waitcnt vmcnt(0)
	v_lshlrev_b32_e32 v162, 16, v158
	v_and_b32_e32 v163, 0xffff0000, v158
	v_lshlrev_b32_e32 v158, 16, v159
	v_and_b32_e32 v159, 0xffff0000, v159
	v_lshlrev_b32_e32 v164, 16, v160
	v_and_b32_e32 v165, 0xffff0000, v160
	v_lshlrev_b32_e32 v160, 16, v161
	v_and_b32_e32 v161, 0xffff0000, v161
	v_pk_mul_f32 v[122:123], v[162:163], s[60:61] op_sel_hi:[1,0]
	v_pk_mul_f32 v[124:125], v[158:159], s[60:61] op_sel_hi:[1,0]
	v_pk_fma_f32 v[118:119], v[118:119], v[146:147], v[122:123]
	v_pk_fma_f32 v[120:121], v[120:121], v[144:145], v[124:125]
	v_pk_mul_f32 v[122:123], v[164:165], s[60:61] op_sel_hi:[1,0]
	v_pk_mul_f32 v[124:125], v[160:161], s[60:61] op_sel_hi:[1,0]
	v_exp_f32_e32 v57, v57
	v_pk_fma_f32 v[124:125], v[116:117], v[140:141], v[124:125]
	v_pk_fma_f32 v[116:117], v[114:115], v[142:143], v[122:123]
	v_cvt_pk_bf16_f32 v114, v118, v119
	v_cvt_pk_bf16_f32 v115, v120, v121
	v_cvt_pk_bf16_f32 v116, v116, v117
	v_cvt_pk_bf16_f32 v117, v124, v125
	global_store_dwordx4 v[148:149], v[114:117], off sc0 sc1
	v_exp_f32_e32 v53, v53
	v_add_f32_e32 v54, 1.0, v54
	v_or_b32_e32 v114, 16, v150
	v_ashrrev_i32_e32 v115, 31, v114
	v_lshlrev_b64 v[114:115], 12, v[114:115]
	v_lshl_add_u64 v[114:115], s[50:51], 0, v[114:115]
	v_lshl_add_u64 v[118:119], v[114:115], 0, v[152:153]
	global_load_dwordx4 v[114:117], v[118:119], off
	v_add_f32_e32 v50, 1.0, v50
	v_add_f32_e32 v55, 1.0, v55
	v_add_f32_e32 v51, 1.0, v51
	v_add_f32_e32 v56, 1.0, v56
	v_add_f32_e32 v52, 1.0, v52
	v_add_f32_e32 v57, 1.0, v57
	v_add_f32_e32 v53, 1.0, v53
	v_rcp_f32_e32 v54, v54
	v_rcp_f32_e32 v50, v50
	v_rcp_f32_e32 v55, v55
	v_rcp_f32_e32 v51, v51
	v_rcp_f32_e32 v56, v56
	v_rcp_f32_e32 v52, v52
	v_rcp_f32_e32 v57, v57
	v_rcp_f32_e32 v53, v53
	v_pk_mul_f32 v[54:55], v[62:63], v[54:55]
	v_pk_mul_f32 v[50:51], v[58:59], v[50:51]
	v_pk_mul_f32 v[56:57], v[64:65], v[56:57]
	v_pk_mul_f32 v[52:53], v[60:61], v[52:53]
	v_mul_f32_e32 v38, 0xbfb8aa3b, v38
	v_mul_f32_e32 v34, 0xbfb8aa3b, v34
	v_mul_f32_e32 v39, 0xbfb8aa3b, v39
	v_mul_f32_e32 v35, 0xbfb8aa3b, v35
	v_mul_f32_e32 v40, 0xbfb8aa3b, v40
	v_mul_f32_e32 v36, 0xbfb8aa3b, v36
	v_mul_f32_e32 v41, 0xbfb8aa3b, v41
	v_mul_f32_e32 v37, 0xbfb8aa3b, v37
	v_exp_f32_e32 v38, v38
	v_exp_f32_e32 v34, v34
	v_exp_f32_e32 v39, v39
	v_exp_f32_e32 v35, v35
	v_exp_f32_e32 v40, v40
	v_exp_f32_e32 v36, v36
	v_exp_f32_e32 v41, v41
	v_exp_f32_e32 v37, v37
	v_add_f32_e32 v38, 1.0, v38
	v_add_f32_e32 v34, 1.0, v34
	v_add_f32_e32 v39, 1.0, v39
	v_add_f32_e32 v35, 1.0, v35
	v_add_f32_e32 v40, 1.0, v40
	v_add_f32_e32 v36, 1.0, v36
	v_add_f32_e32 v41, 1.0, v41
	v_add_f32_e32 v37, 1.0, v37
	v_rcp_f32_e32 v38, v38
	v_rcp_f32_e32 v34, v34
	v_rcp_f32_e32 v39, v39
	v_rcp_f32_e32 v35, v35
	v_rcp_f32_e32 v40, v40
	v_rcp_f32_e32 v36, v36
	v_rcp_f32_e32 v41, v41
	v_rcp_f32_e32 v37, v37
	v_pk_mul_f32 v[38:39], v[46:47], v[38:39]
	v_pk_mul_f32 v[34:35], v[42:43], v[34:35]
	v_pk_mul_f32 v[40:41], v[48:49], v[40:41]
	v_pk_mul_f32 v[36:37], v[44:45], v[36:37]
	v_mul_f32_e32 v22, 0xbfb8aa3b, v22
	v_mul_f32_e32 v18, 0xbfb8aa3b, v18
	v_mul_f32_e32 v23, 0xbfb8aa3b, v23
	v_mul_f32_e32 v19, 0xbfb8aa3b, v19
	v_mul_f32_e32 v24, 0xbfb8aa3b, v24
	v_mul_f32_e32 v20, 0xbfb8aa3b, v20
	v_mul_f32_e32 v25, 0xbfb8aa3b, v25
	v_mul_f32_e32 v21, 0xbfb8aa3b, v21
	v_exp_f32_e32 v22, v22
	v_exp_f32_e32 v18, v18
	v_exp_f32_e32 v23, v23
	v_exp_f32_e32 v19, v19
	v_exp_f32_e32 v24, v24
	v_exp_f32_e32 v20, v20
	v_exp_f32_e32 v25, v25
	v_exp_f32_e32 v21, v21
	v_add_f32_e32 v22, 1.0, v22
	v_add_f32_e32 v18, 1.0, v18
	v_add_f32_e32 v23, 1.0, v23
	v_add_f32_e32 v19, 1.0, v19
	v_add_f32_e32 v24, 1.0, v24
	v_add_f32_e32 v20, 1.0, v20
	v_add_f32_e32 v25, 1.0, v25
	v_add_f32_e32 v21, 1.0, v21
	s_waitcnt vmcnt(0)
	v_lshlrev_b32_e32 v120, 16, v114
	v_and_b32_e32 v121, 0xffff0000, v114
	v_lshlrev_b32_e32 v114, 16, v115
	v_and_b32_e32 v115, 0xffff0000, v115
	v_lshlrev_b32_e32 v122, 16, v116
	v_and_b32_e32 v123, 0xffff0000, v116
	v_lshlrev_b32_e32 v116, 16, v117
	v_and_b32_e32 v117, 0xffff0000, v117
	v_pk_mul_f32 v[106:107], v[120:121], s[60:61] op_sel_hi:[1,0]
	v_pk_mul_f32 v[108:109], v[114:115], s[60:61] op_sel_hi:[1,0]
	v_pk_fma_f32 v[102:103], v[102:103], v[146:147], v[106:107]
	v_pk_fma_f32 v[104:105], v[104:105], v[144:145], v[108:109]
	v_pk_mul_f32 v[106:107], v[122:123], s[60:61] op_sel_hi:[1,0]
	v_pk_mul_f32 v[108:109], v[116:117], s[60:61] op_sel_hi:[1,0]
	v_rcp_f32_e32 v22, v22
	v_pk_fma_f32 v[108:109], v[100:101], v[140:141], v[108:109]
	v_pk_fma_f32 v[100:101], v[98:99], v[142:143], v[106:107]
	v_cvt_pk_bf16_f32 v98, v102, v103
	v_cvt_pk_bf16_f32 v99, v104, v105
	v_cvt_pk_bf16_f32 v100, v100, v101
	v_cvt_pk_bf16_f32 v101, v108, v109
	global_store_dwordx4 v[118:119], v[98:101], off sc0 sc1
	v_rcp_f32_e32 v18, v18
	v_rcp_f32_e32 v23, v23
	v_or_b32_e32 v98, 32, v150
	v_ashrrev_i32_e32 v99, 31, v98
	v_lshlrev_b64 v[98:99], 12, v[98:99]
	v_lshl_add_u64 v[98:99], s[50:51], 0, v[98:99]
	v_lshl_add_u64 v[102:103], v[98:99], 0, v[152:153]
	global_load_dwordx4 v[98:101], v[102:103], off
	v_rcp_f32_e32 v19, v19
	v_rcp_f32_e32 v24, v24
	v_rcp_f32_e32 v20, v20
	v_rcp_f32_e32 v25, v25
	v_rcp_f32_e32 v21, v21
	v_pk_mul_f32 v[22:23], v[30:31], v[22:23]
	v_pk_mul_f32 v[18:19], v[26:27], v[18:19]
	v_pk_mul_f32 v[24:25], v[32:33], v[24:25]
	v_pk_mul_f32 v[20:21], v[28:29], v[20:21]
	v_mul_f32_e32 v10, 0xbfb8aa3b, v10
	v_mul_f32_e32 v2, 0xbfb8aa3b, v2
	v_mul_f32_e32 v11, 0xbfb8aa3b, v11
	v_mul_f32_e32 v3, 0xbfb8aa3b, v3
	v_mul_f32_e32 v12, 0xbfb8aa3b, v12
	v_mul_f32_e32 v4, 0xbfb8aa3b, v4
	v_mul_f32_e32 v13, 0xbfb8aa3b, v13
	v_mul_f32_e32 v5, 0xbfb8aa3b, v5
	v_exp_f32_e32 v10, v10
	v_exp_f32_e32 v2, v2
	v_exp_f32_e32 v11, v11
	v_exp_f32_e32 v3, v3
	v_exp_f32_e32 v12, v12
	v_exp_f32_e32 v4, v4
	v_exp_f32_e32 v13, v13
	v_exp_f32_e32 v5, v5
	v_add_f32_e32 v10, 1.0, v10
	v_add_f32_e32 v2, 1.0, v2
	v_add_f32_e32 v11, 1.0, v11
	v_add_f32_e32 v3, 1.0, v3
	v_add_f32_e32 v12, 1.0, v12
	v_add_f32_e32 v4, 1.0, v4
	v_add_f32_e32 v13, 1.0, v13
	v_add_f32_e32 v5, 1.0, v5
	v_rcp_f32_e32 v10, v10
	v_rcp_f32_e32 v2, v2
	v_rcp_f32_e32 v11, v11
	v_rcp_f32_e32 v3, v3
	v_rcp_f32_e32 v12, v12
	v_rcp_f32_e32 v4, v4
	v_rcp_f32_e32 v13, v13
	v_rcp_f32_e32 v5, v5
	v_pk_mul_f32 v[10:11], v[14:15], v[10:11]
	v_pk_mul_f32 v[2:3], v[6:7], v[2:3]
	v_pk_mul_f32 v[12:13], v[16:17], v[12:13]
	v_pk_mul_f32 v[4:5], v[8:9], v[4:5]
	s_mov_b64 s[16:17], -1
	s_mov_b32 s44, 0x8000
	s_mov_b32 s45, 0xa000
	s_waitcnt vmcnt(0)
	v_lshlrev_b32_e32 v104, 16, v98
	v_and_b32_e32 v105, 0xffff0000, v98
	v_lshlrev_b32_e32 v98, 16, v99
	v_and_b32_e32 v99, 0xffff0000, v99
	v_lshlrev_b32_e32 v106, 16, v100
	v_and_b32_e32 v107, 0xffff0000, v100
	v_lshlrev_b32_e32 v100, 16, v101
	v_and_b32_e32 v101, 0xffff0000, v101
	v_pk_mul_f32 v[90:91], v[104:105], s[60:61] op_sel_hi:[1,0]
	v_pk_mul_f32 v[92:93], v[98:99], s[60:61] op_sel_hi:[1,0]
	v_pk_fma_f32 v[86:87], v[86:87], v[146:147], v[90:91]
	v_pk_fma_f32 v[88:89], v[88:89], v[144:145], v[92:93]
	v_pk_mul_f32 v[90:91], v[106:107], s[60:61] op_sel_hi:[1,0]
	v_pk_mul_f32 v[92:93], v[100:101], s[60:61] op_sel_hi:[1,0]
	s_nop 0
	v_pk_fma_f32 v[92:93], v[84:85], v[140:141], v[92:93]
	v_pk_fma_f32 v[84:85], v[82:83], v[142:143], v[90:91]
	v_cvt_pk_bf16_f32 v82, v86, v87
	v_cvt_pk_bf16_f32 v83, v88, v89
	v_cvt_pk_bf16_f32 v84, v84, v85
	v_cvt_pk_bf16_f32 v85, v92, v93
	global_store_dwordx4 v[102:103], v[82:85], off sc0 sc1
	s_nop 1
	v_or_b32_e32 v82, 48, v150
	v_ashrrev_i32_e32 v83, 31, v82
	v_lshlrev_b64 v[82:83], 12, v[82:83]
	v_lshl_add_u64 v[82:83], s[50:51], 0, v[82:83]
	v_lshl_add_u64 v[86:87], v[82:83], 0, v[152:153]
	global_load_dwordx4 v[82:85], v[86:87], off
	s_waitcnt vmcnt(0)
	v_lshlrev_b32_e32 v88, 16, v82
	v_and_b32_e32 v89, 0xffff0000, v82
	v_lshlrev_b32_e32 v82, 16, v83
	v_and_b32_e32 v83, 0xffff0000, v83
	v_lshlrev_b32_e32 v90, 16, v84
	v_and_b32_e32 v91, 0xffff0000, v84
	v_lshlrev_b32_e32 v84, 16, v85
	v_and_b32_e32 v85, 0xffff0000, v85
	v_pk_mul_f32 v[74:75], v[88:89], s[60:61] op_sel_hi:[1,0]
	v_pk_mul_f32 v[76:77], v[82:83], s[60:61] op_sel_hi:[1,0]
	v_pk_fma_f32 v[70:71], v[70:71], v[146:147], v[74:75]
	v_pk_fma_f32 v[72:73], v[72:73], v[144:145], v[76:77]
	v_pk_mul_f32 v[74:75], v[90:91], s[60:61] op_sel_hi:[1,0]
	v_pk_mul_f32 v[76:77], v[84:85], s[60:61] op_sel_hi:[1,0]
	s_nop 0
	v_pk_fma_f32 v[76:77], v[68:69], v[140:141], v[76:77]
	v_pk_fma_f32 v[68:69], v[66:67], v[142:143], v[74:75]
	v_cvt_pk_bf16_f32 v66, v70, v71
	v_add_co_u32_e32 v70, vcc, s3, v148
	v_cvt_pk_bf16_f32 v67, v72, v73
	v_cvt_pk_bf16_f32 v68, v68, v69
	v_cvt_pk_bf16_f32 v69, v76, v77
	v_addc_co_u32_e32 v71, vcc, 0, v149, vcc
	global_store_dwordx4 v[86:87], v[66:69], off sc0 sc1
	global_load_dwordx4 v[66:69], v[70:71], off
	s_mov_b32 s3, 0x90000
	s_waitcnt vmcnt(0)
	v_lshlrev_b32_e32 v72, 16, v66
	v_and_b32_e32 v73, 0xffff0000, v66
	v_lshlrev_b32_e32 v66, 16, v67
	v_and_b32_e32 v67, 0xffff0000, v67
	v_lshlrev_b32_e32 v74, 16, v68
	v_and_b32_e32 v75, 0xffff0000, v68
	v_lshlrev_b32_e32 v68, 16, v69
	v_and_b32_e32 v69, 0xffff0000, v69
	v_pk_mul_f32 v[58:59], v[72:73], s[60:61] op_sel_hi:[1,0]
	v_pk_mul_f32 v[60:61], v[66:67], s[60:61] op_sel_hi:[1,0]
	v_pk_fma_f32 v[54:55], v[54:55], v[146:147], v[58:59]
	v_pk_fma_f32 v[56:57], v[56:57], v[144:145], v[60:61]
	v_pk_mul_f32 v[58:59], v[74:75], s[60:61] op_sel_hi:[1,0]
	v_pk_mul_f32 v[60:61], v[68:69], s[60:61] op_sel_hi:[1,0]
	s_nop 0
	v_pk_fma_f32 v[60:61], v[52:53], v[140:141], v[60:61]
	v_pk_fma_f32 v[52:53], v[50:51], v[142:143], v[58:59]
	v_cvt_pk_bf16_f32 v50, v54, v55
	v_add_co_u32_e32 v54, vcc, s3, v148
	v_cvt_pk_bf16_f32 v51, v56, v57
	v_cvt_pk_bf16_f32 v52, v52, v53
	v_cvt_pk_bf16_f32 v53, v60, v61
	v_addc_co_u32_e32 v55, vcc, 0, v149, vcc
	global_store_dwordx4 v[70:71], v[50:53], off sc0 sc1
	global_load_dwordx4 v[50:53], v[54:55], off
	s_mov_b32 s3, 0xa0000
	s_waitcnt vmcnt(0)
	v_lshlrev_b32_e32 v56, 16, v50
	v_and_b32_e32 v57, 0xffff0000, v50
	v_lshlrev_b32_e32 v50, 16, v51
	v_and_b32_e32 v51, 0xffff0000, v51
	v_lshlrev_b32_e32 v58, 16, v52
	v_and_b32_e32 v59, 0xffff0000, v52
	v_lshlrev_b32_e32 v52, 16, v53
	v_and_b32_e32 v53, 0xffff0000, v53
	v_pk_mul_f32 v[42:43], v[56:57], s[60:61] op_sel_hi:[1,0]
	v_pk_mul_f32 v[44:45], v[50:51], s[60:61] op_sel_hi:[1,0]
	v_pk_fma_f32 v[38:39], v[38:39], v[146:147], v[42:43]
	v_pk_fma_f32 v[40:41], v[40:41], v[144:145], v[44:45]
	v_pk_mul_f32 v[42:43], v[58:59], s[60:61] op_sel_hi:[1,0]
	v_pk_mul_f32 v[44:45], v[52:53], s[60:61] op_sel_hi:[1,0]
	s_nop 0
	v_pk_fma_f32 v[44:45], v[36:37], v[140:141], v[44:45]
	v_pk_fma_f32 v[36:37], v[34:35], v[142:143], v[42:43]
	v_cvt_pk_bf16_f32 v34, v38, v39
	v_add_co_u32_e32 v38, vcc, s3, v148
	v_cvt_pk_bf16_f32 v35, v40, v41
	v_cvt_pk_bf16_f32 v36, v36, v37
	v_cvt_pk_bf16_f32 v37, v44, v45
	v_addc_co_u32_e32 v39, vcc, 0, v149, vcc
	global_store_dwordx4 v[54:55], v[34:37], off sc0 sc1
	global_load_dwordx4 v[34:37], v[38:39], off
	s_mov_b32 s3, 0xb0000
	s_waitcnt vmcnt(0)
	v_lshlrev_b32_e32 v40, 16, v34
	v_and_b32_e32 v41, 0xffff0000, v34
	v_lshlrev_b32_e32 v34, 16, v35
	v_and_b32_e32 v35, 0xffff0000, v35
	v_lshlrev_b32_e32 v42, 16, v36
	v_and_b32_e32 v43, 0xffff0000, v36
	v_lshlrev_b32_e32 v36, 16, v37
	v_and_b32_e32 v37, 0xffff0000, v37
	v_pk_mul_f32 v[26:27], v[40:41], s[60:61] op_sel_hi:[1,0]
	v_pk_mul_f32 v[28:29], v[34:35], s[60:61] op_sel_hi:[1,0]
	v_pk_fma_f32 v[22:23], v[22:23], v[146:147], v[26:27]
	v_pk_fma_f32 v[24:25], v[24:25], v[144:145], v[28:29]
	v_pk_mul_f32 v[26:27], v[42:43], s[60:61] op_sel_hi:[1,0]
	v_pk_mul_f32 v[28:29], v[36:37], s[60:61] op_sel_hi:[1,0]
	s_nop 0
	v_pk_fma_f32 v[28:29], v[20:21], v[140:141], v[28:29]
	v_pk_fma_f32 v[20:21], v[18:19], v[142:143], v[26:27]
	v_cvt_pk_bf16_f32 v18, v22, v23
	v_add_co_u32_e32 v22, vcc, s3, v148
	v_cvt_pk_bf16_f32 v19, v24, v25
	v_cvt_pk_bf16_f32 v20, v20, v21
	v_cvt_pk_bf16_f32 v21, v28, v29
	v_addc_co_u32_e32 v23, vcc, 0, v149, vcc
	global_store_dwordx4 v[38:39], v[18:21], off sc0 sc1
	global_load_dwordx4 v[18:21], v[22:23], off
	s_andn2_b64 vcc, exec, s[0:1]
	s_waitcnt vmcnt(0)
	v_lshlrev_b32_e32 v24, 16, v18
	v_and_b32_e32 v25, 0xffff0000, v18
	v_lshlrev_b32_e32 v18, 16, v19
	v_and_b32_e32 v19, 0xffff0000, v19
	v_lshlrev_b32_e32 v26, 16, v20
	v_and_b32_e32 v27, 0xffff0000, v20
	v_lshlrev_b32_e32 v20, 16, v21
	v_and_b32_e32 v21, 0xffff0000, v21
	v_pk_mul_f32 v[6:7], v[24:25], s[60:61] op_sel_hi:[1,0]
	v_pk_mul_f32 v[8:9], v[18:19], s[60:61] op_sel_hi:[1,0]
	v_pk_fma_f32 v[6:7], v[10:11], v[146:147], v[6:7]
	v_pk_fma_f32 v[8:9], v[12:13], v[144:145], v[8:9]
	v_pk_mul_f32 v[10:11], v[26:27], s[60:61] op_sel_hi:[1,0]
	v_pk_mul_f32 v[12:13], v[20:21], s[60:61] op_sel_hi:[1,0]
	s_nop 0
	v_pk_fma_f32 v[12:13], v[4:5], v[140:141], v[12:13]
	v_pk_fma_f32 v[4:5], v[2:3], v[142:143], v[10:11]
	v_cvt_pk_bf16_f32 v2, v6, v7
	v_cvt_pk_bf16_f32 v3, v8, v9
	v_cvt_pk_bf16_f32 v4, v4, v5
	v_cvt_pk_bf16_f32 v5, v12, v13
	global_store_dwordx4 v[22:23], v[2:5], off sc0 sc1
	s_cbranch_vccnz .LBB0_369
	s_andn2_b64 vcc, exec, s[4:5]
	s_cbranch_vccnz .LBB0_368
	s_barrier
	s_branch .LBB0_368

.LBB0_415:
	s_ashr_i32 s1, s0, 31
	s_lshl_b64 s[0:1], s[0:1], 25
	v_or_b32_e32 v0, s19, v207
	s_add_u32 s0, s48, s0
	s_addc_u32 s1, s49, s1
	v_lshlrev_b32_e32 v0, 1, v0
	v_ashrrev_i32_e32 v197, 31, v196
	v_lshl_add_u64 v[198:199], s[0:1], 0, v[0:1]
	v_lshlrev_b64 v[154:155], 11, v[196:197]
	v_lshl_add_u64 v[160:161], v[198:199], 0, v[154:155]
	v_cvt_pk_bf16_f32 v146, v146, v147
	v_cvt_pk_bf16_f32 v147, v148, v149
	v_cvt_pk_bf16_f32 v148, v150, v151
	v_cvt_pk_bf16_f32 v149, v152, v153
	global_store_dwordx4 v[160:161], v[146:149], off sc0 sc1
	v_mov_b64_e32 v[152:153], v[92:93]
	s_and_b64 vcc, exec, s[4:5]
	v_mov_b64_e32 v[148:149], v[96:97]
	v_mov_b64_e32 v[150:151], v[90:91]
	v_mov_b64_e32 v[146:147], v[94:95]
	s_cbranch_vccnz .LBB0_423
	v_and_b32_e32 v146, 64, v215
	v_xor_b32_e32 v0, 16, v215
	v_add_u32_e32 v146, 64, v146
	v_cmp_lt_i32_e32 vcc, v0, v146
	s_nop 1
	v_cndmask_b32_e32 v0, v215, v0, vcc
	v_lshlrev_b32_e32 v0, 2, v0
	ds_bpermute_b32 v156, v0, v94
	ds_bpermute_b32 v154, v0, v90
	ds_bpermute_b32 v157, v0, v95
	ds_bpermute_b32 v155, v0, v91
	ds_bpermute_b32 v202, v0, v96
	ds_bpermute_b32 v200, v0, v92
	ds_bpermute_b32 v203, v0, v97
	ds_bpermute_b32 v201, v0, v93
	v_cmp_lt_i32_e32 vcc, 0, v204
	s_and_saveexec_b64 s[0:1], vcc
	s_xor_b64 s[0:1], exec, s[0:1]
	s_cbranch_execz .LBB0_420
	v_mov_b64_e32 v[152:153], v[92:93]
	v_mov_b64_e32 v[148:149], v[96:97]
	v_cmp_eq_u32_e32 vcc, 1, v204
	v_mov_b64_e32 v[150:151], v[90:91]
	v_mov_b64_e32 v[146:147], v[94:95]
	s_and_saveexec_b64 s[8:9], vcc
	s_cbranch_execz .LBB0_419
	s_waitcnt vmcnt(0) lgkmcnt(0)
	v_pk_mul_f32 v[144:145], v[144:145], v[202:203]
	v_pk_mul_f32 v[142:143], v[142:143], v[156:157]
	v_pk_fma_f32 v[148:149], v[96:97], v[136:137], v[144:145]
	v_pk_fma_f32 v[146:147], v[94:95], v[134:135], v[142:143]
	v_pk_mul_f32 v[134:135], v[140:141], v[200:201]
	v_pk_mul_f32 v[136:137], v[138:139], v[154:155]
	v_pk_fma_f32 v[152:153], v[92:93], v[132:133], v[134:135]
	v_pk_fma_f32 v[150:151], v[90:91], v[130:131], v[136:137]

.LBB0_425:
	v_cvt_pk_bf16_f32 v138, v132, v133
	v_cvt_pk_bf16_f32 v139, v130, v131
	v_cvt_pk_bf16_f32 v140, v136, v137
	v_cvt_pk_bf16_f32 v141, v134, v135
	global_store_dwordx4 v[160:161], v[138:141], off offset:256 sc0 sc1
	s_waitcnt lgkmcnt(2)
	v_or_b32_e32 v200, 16, v196
	v_mov_b32_e32 v134, 0
	s_and_b64 vcc, exec, s[4:5]
	v_mov_b32_e32 v135, 0
	v_mov_b32_e32 v136, 0
	v_mov_b32_e32 v137, 0
	v_mov_b32_e32 v130, 0
	v_mov_b32_e32 v131, 0
	v_mov_b32_e32 v132, 0
	v_mov_b32_e32 v133, 0
	v_mov_b32_e32 v142, 0
	v_mov_b32_e32 v143, 0
	v_mov_b32_e32 v144, 0
	v_mov_b32_e32 v145, 0
	v_mov_b32_e32 v138, 0
	v_mov_b32_e32 v139, 0
	v_mov_b32_e32 v140, 0
	v_mov_b32_e32 v141, 0
	s_cbranch_vccnz .LBB0_427
	v_lshlrev_b32_e32 v130, 3, v200
	v_ashrrev_i32_e32 v131, 31, v130
	v_lshlrev_b64 v[130:131], 2, v[130:131]
	v_lshl_add_u64 v[138:139], s[68:69], 0, v[130:131]
	v_lshl_add_u64 v[130:131], s[66:67], 0, v[130:131]
	global_load_dwordx4 v[134:137], v[130:131], off
	s_nop 0
	global_load_dwordx4 v[130:133], v[130:131], off offset:16
	s_nop 0
	global_load_dwordx4 v[142:145], v[138:139], off
	s_nop 0
	global_load_dwordx4 v[138:141], v[138:139], off offset:16

.LBB0_437:
	v_ashrrev_i32_e32 v201, 31, v200
	v_lshlrev_b64 v[154:155], 11, v[200:201]
	v_lshl_add_u64 v[160:161], v[198:199], 0, v[154:155]
	v_cvt_pk_bf16_f32 v146, v146, v147
	v_cvt_pk_bf16_f32 v147, v148, v149
	v_cvt_pk_bf16_f32 v148, v150, v151
	v_cvt_pk_bf16_f32 v149, v152, v153
	global_store_dwordx4 v[160:161], v[146:149], off sc0 sc1
	v_mov_b64_e32 v[152:153], v[84:85]
	s_and_b64 vcc, exec, s[4:5]
	v_mov_b64_e32 v[148:149], v[88:89]
	v_mov_b64_e32 v[150:151], v[82:83]
	v_mov_b64_e32 v[146:147], v[86:87]
	s_cbranch_vccnz .LBB0_445
	v_and_b32_e32 v146, 64, v215
	v_xor_b32_e32 v0, 16, v215
	v_add_u32_e32 v146, 64, v146
	v_cmp_lt_i32_e32 vcc, v0, v146
	s_nop 1
	v_cndmask_b32_e32 v0, v215, v0, vcc
	v_lshlrev_b32_e32 v0, 2, v0
	ds_bpermute_b32 v156, v0, v86
	ds_bpermute_b32 v154, v0, v82
	ds_bpermute_b32 v157, v0, v87
	ds_bpermute_b32 v155, v0, v83
	ds_bpermute_b32 v202, v0, v88
	ds_bpermute_b32 v200, v0, v84
	ds_bpermute_b32 v203, v0, v89
	ds_bpermute_b32 v201, v0, v85
	v_cmp_lt_i32_e32 vcc, 0, v204
	s_and_saveexec_b64 s[0:1], vcc
	s_xor_b64 s[0:1], exec, s[0:1]
	s_cbranch_execz .LBB0_442
	v_mov_b64_e32 v[152:153], v[84:85]
	v_mov_b64_e32 v[148:149], v[88:89]
	v_cmp_eq_u32_e32 vcc, 1, v204
	v_mov_b64_e32 v[150:151], v[82:83]
	v_mov_b64_e32 v[146:147], v[86:87]
	s_and_saveexec_b64 s[26:27], vcc
	s_cbranch_execz .LBB0_441
	s_waitcnt vmcnt(2) lgkmcnt(1)
	v_pk_mul_f32 v[144:145], v[144:145], v[202:203]
	v_pk_mul_f32 v[142:143], v[142:143], v[156:157]
	v_pk_fma_f32 v[148:149], v[88:89], v[136:137], v[144:145]
	v_pk_fma_f32 v[146:147], v[86:87], v[134:135], v[142:143]
	s_waitcnt vmcnt(1) lgkmcnt(0)
	v_pk_mul_f32 v[134:135], v[140:141], v[200:201]
	v_pk_mul_f32 v[136:137], v[138:139], v[154:155]
	v_pk_fma_f32 v[152:153], v[84:85], v[132:133], v[134:135]
	v_pk_fma_f32 v[150:151], v[82:83], v[130:131], v[136:137]

.LBB0_447:
	s_waitcnt vmcnt(1)
	v_cvt_pk_bf16_f32 v138, v132, v133
	v_cvt_pk_bf16_f32 v139, v130, v131
	v_cvt_pk_bf16_f32 v140, v136, v137
	v_cvt_pk_bf16_f32 v141, v134, v135
	global_store_dwordx4 v[160:161], v[138:141], off offset:256 sc0 sc1
	s_waitcnt lgkmcnt(2)
	v_or_b32_e32 v200, 32, v196
	v_mov_b32_e32 v134, 0
	s_and_b64 vcc, exec, s[4:5]
	v_mov_b32_e32 v135, 0
	v_mov_b32_e32 v136, 0
	v_mov_b32_e32 v137, 0
	v_mov_b32_e32 v130, 0
	v_mov_b32_e32 v131, 0
	v_mov_b32_e32 v132, 0
	v_mov_b32_e32 v133, 0
	v_mov_b32_e32 v142, 0
	v_mov_b32_e32 v143, 0
	v_mov_b32_e32 v144, 0
	v_mov_b32_e32 v145, 0
	v_mov_b32_e32 v138, 0
	v_mov_b32_e32 v139, 0
	v_mov_b32_e32 v140, 0
	v_mov_b32_e32 v141, 0
	s_cbranch_vccnz .LBB0_449
	v_lshlrev_b32_e32 v130, 3, v200
	v_ashrrev_i32_e32 v131, 31, v130
	v_lshlrev_b64 v[130:131], 2, v[130:131]
	v_lshl_add_u64 v[138:139], s[68:69], 0, v[130:131]
	v_lshl_add_u64 v[130:131], s[66:67], 0, v[130:131]
	global_load_dwordx4 v[134:137], v[130:131], off
	s_nop 0
	global_load_dwordx4 v[130:133], v[130:131], off offset:16
	s_nop 0
	global_load_dwordx4 v[142:145], v[138:139], off
	s_nop 0
	global_load_dwordx4 v[138:141], v[138:139], off offset:16

.LBB0_459:
	v_ashrrev_i32_e32 v201, 31, v200
	v_lshlrev_b64 v[154:155], 11, v[200:201]
	v_lshl_add_u64 v[160:161], v[198:199], 0, v[154:155]
	v_cvt_pk_bf16_f32 v146, v146, v147
	v_cvt_pk_bf16_f32 v147, v148, v149
	v_cvt_pk_bf16_f32 v148, v150, v151
	v_cvt_pk_bf16_f32 v149, v152, v153
	global_store_dwordx4 v[160:161], v[146:149], off sc0 sc1
	v_mov_b64_e32 v[152:153], v[76:77]
	s_and_b64 vcc, exec, s[4:5]
	v_mov_b64_e32 v[148:149], v[80:81]
	v_mov_b64_e32 v[150:151], v[74:75]
	v_mov_b64_e32 v[146:147], v[78:79]
	s_cbranch_vccnz .LBB0_467
	v_and_b32_e32 v146, 64, v215
	v_xor_b32_e32 v0, 16, v215
	v_add_u32_e32 v146, 64, v146
	v_cmp_lt_i32_e32 vcc, v0, v146
	s_nop 1
	v_cndmask_b32_e32 v0, v215, v0, vcc
	v_lshlrev_b32_e32 v0, 2, v0
	ds_bpermute_b32 v156, v0, v78
	ds_bpermute_b32 v154, v0, v74
	ds_bpermute_b32 v157, v0, v79
	ds_bpermute_b32 v155, v0, v75
	ds_bpermute_b32 v202, v0, v80
	ds_bpermute_b32 v200, v0, v76
	ds_bpermute_b32 v203, v0, v81
	ds_bpermute_b32 v201, v0, v77
	v_cmp_lt_i32_e32 vcc, 0, v204
	s_and_saveexec_b64 s[0:1], vcc
	s_xor_b64 s[0:1], exec, s[0:1]
	s_cbranch_execz .LBB0_464
	v_mov_b64_e32 v[152:153], v[76:77]
	v_mov_b64_e32 v[148:149], v[80:81]
	v_cmp_eq_u32_e32 vcc, 1, v204
	v_mov_b64_e32 v[150:151], v[74:75]
	v_mov_b64_e32 v[146:147], v[78:79]
	s_and_saveexec_b64 s[26:27], vcc
	s_cbranch_execz .LBB0_463
	s_waitcnt vmcnt(2) lgkmcnt(1)
	v_pk_mul_f32 v[144:145], v[144:145], v[202:203]
	v_pk_mul_f32 v[142:143], v[142:143], v[156:157]
	v_pk_fma_f32 v[148:149], v[80:81], v[136:137], v[144:145]
	v_pk_fma_f32 v[146:147], v[78:79], v[134:135], v[142:143]
	s_waitcnt vmcnt(1) lgkmcnt(0)
	v_pk_mul_f32 v[134:135], v[140:141], v[200:201]
	v_pk_mul_f32 v[136:137], v[138:139], v[154:155]
	v_pk_fma_f32 v[152:153], v[76:77], v[132:133], v[134:135]
	v_pk_fma_f32 v[150:151], v[74:75], v[130:131], v[136:137]

.LBB0_469:
	s_waitcnt vmcnt(1)
	v_cvt_pk_bf16_f32 v138, v132, v133
	v_cvt_pk_bf16_f32 v139, v130, v131
	v_cvt_pk_bf16_f32 v140, v136, v137
	v_cvt_pk_bf16_f32 v141, v134, v135
	global_store_dwordx4 v[160:161], v[138:141], off offset:256 sc0 sc1
	s_waitcnt lgkmcnt(2)
	v_or_b32_e32 v200, 48, v196
	v_mov_b32_e32 v134, 0
	s_and_b64 vcc, exec, s[4:5]
	v_mov_b32_e32 v135, 0
	v_mov_b32_e32 v136, 0
	v_mov_b32_e32 v137, 0
	v_mov_b32_e32 v130, 0
	v_mov_b32_e32 v131, 0
	v_mov_b32_e32 v132, 0
	v_mov_b32_e32 v133, 0
	v_mov_b32_e32 v142, 0
	v_mov_b32_e32 v143, 0
	v_mov_b32_e32 v144, 0
	v_mov_b32_e32 v145, 0
	v_mov_b32_e32 v138, 0
	v_mov_b32_e32 v139, 0
	v_mov_b32_e32 v140, 0
	v_mov_b32_e32 v141, 0
	s_cbranch_vccnz .LBB0_471
	v_lshlrev_b32_e32 v130, 3, v200
	v_ashrrev_i32_e32 v131, 31, v130
	v_lshlrev_b64 v[130:131], 2, v[130:131]
	v_lshl_add_u64 v[138:139], s[68:69], 0, v[130:131]
	v_lshl_add_u64 v[130:131], s[66:67], 0, v[130:131]
	global_load_dwordx4 v[134:137], v[130:131], off
	s_nop 0
	global_load_dwordx4 v[130:133], v[130:131], off offset:16
	s_nop 0
	global_load_dwordx4 v[142:145], v[138:139], off
	s_nop 0
	global_load_dwordx4 v[138:141], v[138:139], off offset:16

.LBB0_481:
	v_ashrrev_i32_e32 v201, 31, v200
	v_lshlrev_b64 v[154:155], 11, v[200:201]
	v_lshl_add_u64 v[160:161], v[198:199], 0, v[154:155]
	v_cvt_pk_bf16_f32 v146, v146, v147
	v_cvt_pk_bf16_f32 v147, v148, v149
	v_cvt_pk_bf16_f32 v148, v150, v151
	v_cvt_pk_bf16_f32 v149, v152, v153
	global_store_dwordx4 v[160:161], v[146:149], off sc0 sc1
	v_mov_b64_e32 v[152:153], v[68:69]
	s_and_b64 vcc, exec, s[4:5]
	v_mov_b64_e32 v[148:149], v[72:73]
	v_mov_b64_e32 v[150:151], v[66:67]
	v_mov_b64_e32 v[146:147], v[70:71]
	s_cbranch_vccnz .LBB0_489
	v_and_b32_e32 v146, 64, v215
	v_xor_b32_e32 v0, 16, v215
	v_add_u32_e32 v146, 64, v146
	v_cmp_lt_i32_e32 vcc, v0, v146
	s_nop 1
	v_cndmask_b32_e32 v0, v215, v0, vcc
	v_lshlrev_b32_e32 v0, 2, v0
	ds_bpermute_b32 v156, v0, v70
	ds_bpermute_b32 v154, v0, v66
	ds_bpermute_b32 v157, v0, v71
	ds_bpermute_b32 v155, v0, v67
	ds_bpermute_b32 v202, v0, v72
	ds_bpermute_b32 v200, v0, v68
	ds_bpermute_b32 v203, v0, v73
	ds_bpermute_b32 v201, v0, v69
	v_cmp_lt_i32_e32 vcc, 0, v204
	s_and_saveexec_b64 s[0:1], vcc
	s_xor_b64 s[0:1], exec, s[0:1]
	s_cbranch_execz .LBB0_486
	v_mov_b64_e32 v[152:153], v[68:69]
	v_mov_b64_e32 v[148:149], v[72:73]
	v_cmp_eq_u32_e32 vcc, 1, v204
	v_mov_b64_e32 v[150:151], v[66:67]
	v_mov_b64_e32 v[146:147], v[70:71]
	s_and_saveexec_b64 s[26:27], vcc
	s_cbranch_execz .LBB0_485
	s_waitcnt vmcnt(2) lgkmcnt(1)
	v_pk_mul_f32 v[144:145], v[144:145], v[202:203]
	v_pk_mul_f32 v[142:143], v[142:143], v[156:157]
	v_pk_fma_f32 v[148:149], v[72:73], v[136:137], v[144:145]
	v_pk_fma_f32 v[146:147], v[70:71], v[134:135], v[142:143]
	s_waitcnt vmcnt(1) lgkmcnt(0)
	v_pk_mul_f32 v[134:135], v[140:141], v[200:201]
	v_pk_mul_f32 v[136:137], v[138:139], v[154:155]
	v_pk_fma_f32 v[152:153], v[68:69], v[132:133], v[134:135]
	v_pk_fma_f32 v[150:151], v[66:67], v[130:131], v[136:137]

.LBB0_491:
	s_waitcnt vmcnt(1)
	v_cvt_pk_bf16_f32 v138, v132, v133
	v_cvt_pk_bf16_f32 v139, v130, v131
	v_cvt_pk_bf16_f32 v140, v136, v137
	v_cvt_pk_bf16_f32 v141, v134, v135
	global_store_dwordx4 v[160:161], v[138:141], off offset:256 sc0 sc1
	s_waitcnt lgkmcnt(2)
	v_add_u32_e32 v200, 0x80, v196
	v_mov_b32_e32 v134, 0
	s_and_b64 vcc, exec, s[4:5]
	v_mov_b32_e32 v135, 0
	v_mov_b32_e32 v136, 0
	v_mov_b32_e32 v137, 0
	v_mov_b32_e32 v130, 0
	v_mov_b32_e32 v131, 0
	v_mov_b32_e32 v132, 0
	v_mov_b32_e32 v133, 0
	v_mov_b32_e32 v142, 0
	v_mov_b32_e32 v143, 0
	v_mov_b32_e32 v144, 0
	v_mov_b32_e32 v145, 0
	v_mov_b32_e32 v138, 0
	v_mov_b32_e32 v139, 0
	v_mov_b32_e32 v140, 0
	v_mov_b32_e32 v141, 0
	s_cbranch_vccnz .LBB0_493
	v_lshlrev_b32_e32 v130, 3, v200
	v_ashrrev_i32_e32 v131, 31, v130
	v_lshlrev_b64 v[130:131], 2, v[130:131]
	v_lshl_add_u64 v[138:139], s[68:69], 0, v[130:131]
	v_lshl_add_u64 v[130:131], s[66:67], 0, v[130:131]
	global_load_dwordx4 v[134:137], v[130:131], off
	s_nop 0
	global_load_dwordx4 v[130:133], v[130:131], off offset:16
	s_nop 0
	global_load_dwordx4 v[142:145], v[138:139], off
	s_nop 0
	global_load_dwordx4 v[138:141], v[138:139], off offset:16

.LBB0_503:
	v_ashrrev_i32_e32 v201, 31, v200
	v_lshlrev_b64 v[154:155], 11, v[200:201]
	v_lshl_add_u64 v[160:161], v[198:199], 0, v[154:155]
	v_cvt_pk_bf16_f32 v146, v146, v147
	v_cvt_pk_bf16_f32 v147, v148, v149
	v_cvt_pk_bf16_f32 v148, v150, v151
	v_cvt_pk_bf16_f32 v149, v152, v153
	global_store_dwordx4 v[160:161], v[146:149], off sc0 sc1
	v_mov_b64_e32 v[152:153], v[28:29]
	s_and_b64 vcc, exec, s[4:5]
	v_mov_b64_e32 v[148:149], v[32:33]
	v_mov_b64_e32 v[150:151], v[26:27]
	v_mov_b64_e32 v[146:147], v[30:31]
	s_cbranch_vccnz .LBB0_511
	v_and_b32_e32 v146, 64, v215
	v_xor_b32_e32 v0, 16, v215
	v_add_u32_e32 v146, 64, v146
	v_cmp_lt_i32_e32 vcc, v0, v146
	s_nop 1
	v_cndmask_b32_e32 v0, v215, v0, vcc
	v_lshlrev_b32_e32 v0, 2, v0
	ds_bpermute_b32 v156, v0, v30
	ds_bpermute_b32 v154, v0, v26
	ds_bpermute_b32 v157, v0, v31
	ds_bpermute_b32 v155, v0, v27
	ds_bpermute_b32 v202, v0, v32
	ds_bpermute_b32 v200, v0, v28
	ds_bpermute_b32 v203, v0, v33
	ds_bpermute_b32 v201, v0, v29
	v_cmp_lt_i32_e32 vcc, 0, v204
	s_and_saveexec_b64 s[0:1], vcc
	s_xor_b64 s[0:1], exec, s[0:1]
	s_cbranch_execz .LBB0_508
	v_mov_b64_e32 v[152:153], v[28:29]
	v_mov_b64_e32 v[148:149], v[32:33]
	v_cmp_eq_u32_e32 vcc, 1, v204
	v_mov_b64_e32 v[150:151], v[26:27]
	v_mov_b64_e32 v[146:147], v[30:31]
	s_and_saveexec_b64 s[26:27], vcc
	s_cbranch_execz .LBB0_507
	s_waitcnt vmcnt(2) lgkmcnt(1)
	v_pk_mul_f32 v[144:145], v[144:145], v[202:203]
	v_pk_mul_f32 v[142:143], v[142:143], v[156:157]
	v_pk_fma_f32 v[148:149], v[32:33], v[136:137], v[144:145]
	v_pk_fma_f32 v[146:147], v[30:31], v[134:135], v[142:143]
	s_waitcnt vmcnt(1) lgkmcnt(0)
	v_pk_mul_f32 v[134:135], v[140:141], v[200:201]
	v_pk_mul_f32 v[136:137], v[138:139], v[154:155]
	v_pk_fma_f32 v[152:153], v[28:29], v[132:133], v[134:135]
	v_pk_fma_f32 v[150:151], v[26:27], v[130:131], v[136:137]

.LBB0_513:
	s_waitcnt vmcnt(1)
	v_cvt_pk_bf16_f32 v138, v132, v133
	v_cvt_pk_bf16_f32 v139, v130, v131
	v_cvt_pk_bf16_f32 v140, v136, v137
	v_cvt_pk_bf16_f32 v141, v134, v135
	global_store_dwordx4 v[160:161], v[138:141], off offset:256 sc0 sc1
	s_waitcnt lgkmcnt(2)
	v_add_u32_e32 v200, 0x90, v196
	v_mov_b32_e32 v134, 0
	s_and_b64 vcc, exec, s[4:5]
	v_mov_b32_e32 v135, 0
	v_mov_b32_e32 v136, 0
	v_mov_b32_e32 v137, 0
	v_mov_b32_e32 v130, 0
	v_mov_b32_e32 v131, 0
	v_mov_b32_e32 v132, 0
	v_mov_b32_e32 v133, 0
	v_mov_b32_e32 v142, 0
	v_mov_b32_e32 v143, 0
	v_mov_b32_e32 v144, 0
	v_mov_b32_e32 v145, 0
	v_mov_b32_e32 v138, 0
	v_mov_b32_e32 v139, 0
	v_mov_b32_e32 v140, 0
	v_mov_b32_e32 v141, 0
	s_cbranch_vccnz .LBB0_515
	v_lshlrev_b32_e32 v130, 3, v200
	v_ashrrev_i32_e32 v131, 31, v130
	v_lshlrev_b64 v[130:131], 2, v[130:131]
	v_lshl_add_u64 v[138:139], s[68:69], 0, v[130:131]
	v_lshl_add_u64 v[130:131], s[66:67], 0, v[130:131]
	global_load_dwordx4 v[134:137], v[130:131], off
	s_nop 0
	global_load_dwordx4 v[130:133], v[130:131], off offset:16
	s_nop 0
	global_load_dwordx4 v[142:145], v[138:139], off
	s_nop 0
	global_load_dwordx4 v[138:141], v[138:139], off offset:16

.LBB0_525:
	v_ashrrev_i32_e32 v201, 31, v200
	v_lshlrev_b64 v[154:155], 11, v[200:201]
	v_lshl_add_u64 v[160:161], v[198:199], 0, v[154:155]
	v_cvt_pk_bf16_f32 v146, v146, v147
	v_cvt_pk_bf16_f32 v147, v148, v149
	v_cvt_pk_bf16_f32 v148, v150, v151
	v_cvt_pk_bf16_f32 v149, v152, v153
	global_store_dwordx4 v[160:161], v[146:149], off sc0 sc1
	v_mov_b64_e32 v[152:153], v[20:21]
	s_and_b64 vcc, exec, s[4:5]
	v_mov_b64_e32 v[148:149], v[24:25]
	v_mov_b64_e32 v[150:151], v[18:19]
	v_mov_b64_e32 v[146:147], v[22:23]
	s_cbranch_vccnz .LBB0_533
	v_and_b32_e32 v146, 64, v215
	v_xor_b32_e32 v0, 16, v215
	v_add_u32_e32 v146, 64, v146
	v_cmp_lt_i32_e32 vcc, v0, v146
	s_nop 1
	v_cndmask_b32_e32 v0, v215, v0, vcc
	v_lshlrev_b32_e32 v0, 2, v0
	ds_bpermute_b32 v156, v0, v22
	ds_bpermute_b32 v154, v0, v18
	ds_bpermute_b32 v157, v0, v23
	ds_bpermute_b32 v155, v0, v19
	ds_bpermute_b32 v202, v0, v24
	ds_bpermute_b32 v200, v0, v20
	ds_bpermute_b32 v203, v0, v25
	ds_bpermute_b32 v201, v0, v21
	v_cmp_lt_i32_e32 vcc, 0, v204
	s_and_saveexec_b64 s[0:1], vcc
	s_xor_b64 s[0:1], exec, s[0:1]
	s_cbranch_execz .LBB0_530
	v_mov_b64_e32 v[152:153], v[20:21]
	v_mov_b64_e32 v[148:149], v[24:25]
	v_cmp_eq_u32_e32 vcc, 1, v204
	v_mov_b64_e32 v[150:151], v[18:19]
	v_mov_b64_e32 v[146:147], v[22:23]
	s_and_saveexec_b64 s[26:27], vcc
	s_cbranch_execz .LBB0_529
	s_waitcnt vmcnt(2) lgkmcnt(1)
	v_pk_mul_f32 v[144:145], v[144:145], v[202:203]
	v_pk_mul_f32 v[142:143], v[142:143], v[156:157]
	v_pk_fma_f32 v[148:149], v[24:25], v[136:137], v[144:145]
	v_pk_fma_f32 v[146:147], v[22:23], v[134:135], v[142:143]
	s_waitcnt vmcnt(1) lgkmcnt(0)
	v_pk_mul_f32 v[134:135], v[140:141], v[200:201]
	v_pk_mul_f32 v[136:137], v[138:139], v[154:155]
	v_pk_fma_f32 v[152:153], v[20:21], v[132:133], v[134:135]
	v_pk_fma_f32 v[150:151], v[18:19], v[130:131], v[136:137]

.LBB0_535:
	s_waitcnt vmcnt(1)
	v_cvt_pk_bf16_f32 v138, v132, v133
	v_cvt_pk_bf16_f32 v139, v130, v131
	v_cvt_pk_bf16_f32 v140, v136, v137
	v_cvt_pk_bf16_f32 v141, v134, v135
	global_store_dwordx4 v[160:161], v[138:141], off offset:256 sc0 sc1
	s_waitcnt lgkmcnt(2)
	v_add_u32_e32 v200, 0xa0, v196
	v_mov_b32_e32 v134, 0
	s_and_b64 vcc, exec, s[4:5]
	v_mov_b32_e32 v135, 0
	v_mov_b32_e32 v136, 0
	v_mov_b32_e32 v137, 0
	v_mov_b32_e32 v130, 0
	v_mov_b32_e32 v131, 0
	v_mov_b32_e32 v132, 0
	v_mov_b32_e32 v133, 0
	v_mov_b32_e32 v142, 0
	v_mov_b32_e32 v143, 0
	v_mov_b32_e32 v144, 0
	v_mov_b32_e32 v145, 0
	v_mov_b32_e32 v138, 0
	v_mov_b32_e32 v139, 0
	v_mov_b32_e32 v140, 0
	v_mov_b32_e32 v141, 0
	s_cbranch_vccnz .LBB0_537
	v_lshlrev_b32_e32 v130, 3, v200
	v_ashrrev_i32_e32 v131, 31, v130
	v_lshlrev_b64 v[130:131], 2, v[130:131]
	v_lshl_add_u64 v[138:139], s[68:69], 0, v[130:131]
	v_lshl_add_u64 v[130:131], s[66:67], 0, v[130:131]
	global_load_dwordx4 v[134:137], v[130:131], off
	s_nop 0
	global_load_dwordx4 v[130:133], v[130:131], off offset:16
	s_nop 0
	global_load_dwordx4 v[142:145], v[138:139], off
	s_nop 0
	global_load_dwordx4 v[138:141], v[138:139], off offset:16

.LBB0_547:
	v_ashrrev_i32_e32 v201, 31, v200
	v_lshlrev_b64 v[154:155], 11, v[200:201]
	v_lshl_add_u64 v[160:161], v[198:199], 0, v[154:155]
	v_cvt_pk_bf16_f32 v146, v146, v147
	v_cvt_pk_bf16_f32 v147, v148, v149
	v_cvt_pk_bf16_f32 v148, v150, v151
	v_cvt_pk_bf16_f32 v149, v152, v153
	global_store_dwordx4 v[160:161], v[146:149], off sc0 sc1
	v_mov_b64_e32 v[152:153], v[12:13]
	s_and_b64 vcc, exec, s[4:5]
	v_mov_b64_e32 v[148:149], v[16:17]
	v_mov_b64_e32 v[150:151], v[10:11]
	v_mov_b64_e32 v[146:147], v[14:15]
	s_cbranch_vccnz .LBB0_555
	v_and_b32_e32 v146, 64, v215
	v_xor_b32_e32 v0, 16, v215
	v_add_u32_e32 v146, 64, v146
	v_cmp_lt_i32_e32 vcc, v0, v146
	s_nop 1
	v_cndmask_b32_e32 v0, v215, v0, vcc
	v_lshlrev_b32_e32 v0, 2, v0
	ds_bpermute_b32 v156, v0, v14
	ds_bpermute_b32 v154, v0, v10
	ds_bpermute_b32 v157, v0, v15
	ds_bpermute_b32 v155, v0, v11
	ds_bpermute_b32 v202, v0, v16
	ds_bpermute_b32 v200, v0, v12
	ds_bpermute_b32 v203, v0, v17
	ds_bpermute_b32 v201, v0, v13
	v_cmp_lt_i32_e32 vcc, 0, v204
	s_and_saveexec_b64 s[0:1], vcc
	s_xor_b64 s[0:1], exec, s[0:1]
	s_cbranch_execz .LBB0_552
	v_mov_b64_e32 v[152:153], v[12:13]
	v_mov_b64_e32 v[148:149], v[16:17]
	v_cmp_eq_u32_e32 vcc, 1, v204
	v_mov_b64_e32 v[150:151], v[10:11]
	v_mov_b64_e32 v[146:147], v[14:15]
	s_and_saveexec_b64 s[26:27], vcc
	s_cbranch_execz .LBB0_551
	s_waitcnt vmcnt(2) lgkmcnt(1)
	v_pk_mul_f32 v[144:145], v[144:145], v[202:203]
	v_pk_mul_f32 v[142:143], v[142:143], v[156:157]
	v_pk_fma_f32 v[148:149], v[16:17], v[136:137], v[144:145]
	v_pk_fma_f32 v[146:147], v[14:15], v[134:135], v[142:143]
	s_waitcnt vmcnt(1) lgkmcnt(0)
	v_pk_mul_f32 v[134:135], v[140:141], v[200:201]
	v_pk_mul_f32 v[136:137], v[138:139], v[154:155]
	v_pk_fma_f32 v[152:153], v[12:13], v[132:133], v[134:135]
	v_pk_fma_f32 v[150:151], v[10:11], v[130:131], v[136:137]

.LBB0_557:
	s_waitcnt vmcnt(1)
	v_cvt_pk_bf16_f32 v138, v132, v133
	v_cvt_pk_bf16_f32 v139, v130, v131
	v_cvt_pk_bf16_f32 v140, v136, v137
	v_cvt_pk_bf16_f32 v141, v134, v135
	global_store_dwordx4 v[160:161], v[138:141], off offset:256 sc0 sc1
	v_add_u32_e32 v196, 0xb0, v196
	v_mov_b32_e32 v134, 0
	s_and_b64 vcc, exec, s[4:5]
	v_mov_b32_e32 v135, 0
	v_mov_b32_e32 v136, 0
	v_mov_b32_e32 v137, 0
	v_mov_b32_e32 v130, 0
	v_mov_b32_e32 v131, 0
	v_mov_b32_e32 v132, 0
	v_mov_b32_e32 v133, 0
	v_mov_b32_e32 v142, 0
	v_mov_b32_e32 v143, 0
	v_mov_b32_e32 v144, 0
	v_mov_b32_e32 v145, 0
	v_mov_b32_e32 v138, 0
	v_mov_b32_e32 v139, 0
	v_mov_b32_e32 v140, 0
	v_mov_b32_e32 v141, 0
	s_cbranch_vccnz .LBB0_559
	v_lshlrev_b32_e32 v130, 3, v196
	v_ashrrev_i32_e32 v131, 31, v130
	v_lshlrev_b64 v[130:131], 2, v[130:131]
	v_lshl_add_u64 v[138:139], s[68:69], 0, v[130:131]
	v_lshl_add_u64 v[130:131], s[66:67], 0, v[130:131]
	global_load_dwordx4 v[134:137], v[130:131], off
	s_nop 0
	global_load_dwordx4 v[130:133], v[130:131], off offset:16
	s_nop 0
	global_load_dwordx4 v[142:145], v[138:139], off
	s_nop 0
	global_load_dwordx4 v[138:141], v[138:139], off offset:16

.LBB0_569:
	v_ashrrev_i32_e32 v197, 31, v196
	v_lshlrev_b64 v[154:155], 11, v[196:197]
	v_lshl_add_u64 v[160:161], v[198:199], 0, v[154:155]
	v_cvt_pk_bf16_f32 v146, v146, v147
	v_cvt_pk_bf16_f32 v147, v148, v149
	v_cvt_pk_bf16_f32 v148, v150, v151
	v_cvt_pk_bf16_f32 v149, v152, v153
	global_store_dwordx4 v[160:161], v[146:149], off sc0 sc1
	v_mov_b64_e32 v[152:153], v[4:5]
	s_and_b64 vcc, exec, s[4:5]
	v_mov_b64_e32 v[148:149], v[8:9]
	v_mov_b64_e32 v[150:151], v[2:3]
	v_mov_b64_e32 v[146:147], v[6:7]
	s_cbranch_vccnz .LBB0_577
	v_and_b32_e32 v146, 64, v215
	v_xor_b32_e32 v0, 16, v215
	v_add_u32_e32 v146, 64, v146
	v_cmp_lt_i32_e32 vcc, v0, v146
	s_nop 1
	v_cndmask_b32_e32 v0, v215, v0, vcc
	v_lshlrev_b32_e32 v0, 2, v0
	ds_bpermute_b32 v156, v0, v6
	ds_bpermute_b32 v154, v0, v2
	ds_bpermute_b32 v157, v0, v7
	ds_bpermute_b32 v155, v0, v3
	ds_bpermute_b32 v198, v0, v8
	ds_bpermute_b32 v196, v0, v4
	ds_bpermute_b32 v199, v0, v9
	ds_bpermute_b32 v197, v0, v5
	v_cmp_lt_i32_e32 vcc, 0, v204
	s_and_saveexec_b64 s[0:1], vcc
	s_xor_b64 s[0:1], exec, s[0:1]
	s_cbranch_execz .LBB0_574
	v_mov_b64_e32 v[152:153], v[4:5]
	v_mov_b64_e32 v[148:149], v[8:9]
	v_cmp_eq_u32_e32 vcc, 1, v204
	v_mov_b64_e32 v[150:151], v[2:3]
	v_mov_b64_e32 v[146:147], v[6:7]
	s_and_saveexec_b64 s[4:5], vcc
	s_cbranch_execz .LBB0_573
	s_waitcnt vmcnt(2) lgkmcnt(1)
	v_pk_mul_f32 v[144:145], v[144:145], v[198:199]
	v_pk_mul_f32 v[142:143], v[142:143], v[156:157]
	v_pk_fma_f32 v[148:149], v[8:9], v[136:137], v[144:145]
	v_pk_fma_f32 v[146:147], v[6:7], v[134:135], v[142:143]
	s_waitcnt vmcnt(1) lgkmcnt(0)
	v_pk_mul_f32 v[134:135], v[140:141], v[196:197]
	v_pk_mul_f32 v[136:137], v[138:139], v[154:155]
	v_pk_fma_f32 v[152:153], v[4:5], v[132:133], v[134:135]
	v_pk_fma_f32 v[150:151], v[2:3], v[130:131], v[136:137]

.LBB0_579:
	s_waitcnt vmcnt(1)
	v_cvt_pk_bf16_f32 v138, v132, v133
	v_cvt_pk_bf16_f32 v139, v130, v131
	v_cvt_pk_bf16_f32 v140, v136, v137
	v_cvt_pk_bf16_f32 v141, v134, v135
	global_store_dwordx4 v[160:161], v[138:141], off offset:256 sc0 sc1

.LBB0_581:
	s_and_b64 vcc, exec, s[4:5]
	s_cbranch_vccz .LBB0_580
	v_cvt_pk_bf16_f32 v0, v126, s0
	ds_write_b16 v217, v0
	v_cvt_pk_bf16_f32 v0, v127, s0
	ds_write_b16 v217, v0 offset:72
	v_cvt_pk_bf16_f32 v0, v128, s0
	ds_write_b16 v217, v0 offset:144
	v_cvt_pk_bf16_f32 v0, v129, s0
	ds_write_b16 v217, v0 offset:216
	v_cvt_pk_bf16_f32 v0, v122, s0
	ds_write_b16 v217, v0 offset:288
	v_cvt_pk_bf16_f32 v0, v123, s0
	ds_write_b16 v217, v0 offset:360
	v_cvt_pk_bf16_f32 v0, v124, s0
	ds_write_b16 v217, v0 offset:432
	v_cvt_pk_bf16_f32 v0, v125, s0
	ds_write_b16 v217, v0 offset:504
	v_cvt_pk_bf16_f32 v0, v118, s0
	ds_write_b16 v217, v0 offset:32
	v_cvt_pk_bf16_f32 v0, v119, s0
	ds_write_b16 v217, v0 offset:104
	v_cvt_pk_bf16_f32 v0, v120, s0
	ds_write_b16 v217, v0 offset:176
	v_cvt_pk_bf16_f32 v0, v121, s0
	ds_write_b16 v217, v0 offset:248
	v_cvt_pk_bf16_f32 v0, v114, s0
	ds_write_b16 v217, v0 offset:320
	v_cvt_pk_bf16_f32 v0, v115, s0
	ds_write_b16 v217, v0 offset:392
	v_cvt_pk_bf16_f32 v0, v116, s0
	s_lshl_b32 s1, s45, 2
	ds_write_b16 v217, v0 offset:464
	v_cvt_pk_bf16_f32 v0, v117, s0
	s_lshl_b32 s0, s19, 1
	s_add_i32 s1, s1, s34
	s_add_i32 s4, s1, s0
	s_ashr_i32 s5, s4, 31
	ds_write_b16 v217, v0 offset:536
	s_lshl_b64 s[4:5], s[4:5], 14
	s_waitcnt lgkmcnt(0)
	s_add_u32 s4, s71, s4
	ds_read2_b64 v[114:117], v219 offset1:1
	s_addc_u32 s5, s72, s5
	v_mov_b32_e32 v175, v1
	v_lshl_add_u64 v[118:119], s[4:5], 0, v[174:175]
	v_mov_b32_e32 v189, v1
	v_lshl_add_u64 v[122:123], v[118:119], 0, v[188:189]
	ds_read2_b64 v[118:121], v219 offset0:144 offset1:145
	v_mov_b32_e32 v191, v1
	s_waitcnt lgkmcnt(0)
	global_store_dwordx4 v[122:123], v[114:117], off sc0 sc1
	v_cvt_pk_bf16_f32 v0, v110, s0
	v_mov_b32_e32 v193, v1
	v_lshl_add_u64 v[114:115], s[4:5], 0, v[190:191]
	v_lshl_add_u64 v[114:115], v[114:115], 0, v[188:189]
	global_store_dwordx4 v[114:115], v[118:121], off sc0 sc1
	s_waitcnt lgkmcnt(0)
	ds_write_b16 v217, v0
	v_cvt_pk_bf16_f32 v0, v111, s0
	ds_write_b16 v217, v0 offset:72
	v_cvt_pk_bf16_f32 v0, v112, s0
	ds_write_b16 v217, v0 offset:144
	v_cvt_pk_bf16_f32 v0, v113, s0
	ds_write_b16 v217, v0 offset:216
	v_cvt_pk_bf16_f32 v0, v106, s0
	ds_write_b16 v217, v0 offset:288
	v_cvt_pk_bf16_f32 v0, v107, s0
	ds_write_b16 v217, v0 offset:360
	v_cvt_pk_bf16_f32 v0, v108, s0
	ds_write_b16 v217, v0 offset:432
	v_cvt_pk_bf16_f32 v0, v109, s0
	ds_write_b16 v217, v0 offset:504
	v_cvt_pk_bf16_f32 v0, v102, s0
	ds_write_b16 v217, v0 offset:32
	v_cvt_pk_bf16_f32 v0, v103, s0
	ds_write_b16 v217, v0 offset:104
	v_cvt_pk_bf16_f32 v0, v104, s0
	ds_write_b16 v217, v0 offset:176
	v_cvt_pk_bf16_f32 v0, v105, s0
	ds_write_b16 v217, v0 offset:248
	v_cvt_pk_bf16_f32 v0, v98, s0
	ds_write_b16 v217, v0 offset:320
	v_cvt_pk_bf16_f32 v0, v99, s0
	ds_write_b16 v217, v0 offset:392
	v_cvt_pk_bf16_f32 v0, v100, s0
	ds_write_b16 v217, v0 offset:464
	v_cvt_pk_bf16_f32 v0, v101, s0
	ds_write_b16 v217, v0 offset:536
	s_waitcnt lgkmcnt(0)
	ds_read2_b64 v[98:101], v219 offset1:1
	v_lshl_add_u64 v[102:103], s[4:5], 0, v[192:193]
	v_lshl_add_u64 v[106:107], v[102:103], 0, v[188:189]
	ds_read2_b64 v[102:105], v219 offset0:144 offset1:145
	v_mov_b32_e32 v195, v1
	s_waitcnt lgkmcnt(0)
	global_store_dwordx4 v[106:107], v[98:101], off offset:64 sc0 sc1
	v_cvt_pk_bf16_f32 v0, v94, s0
	s_lshl_b32 s3, s44, 9
	v_lshl_add_u64 v[98:99], s[4:5], 0, v[194:195]
	v_lshl_add_u64 v[98:99], v[98:99], 0, v[188:189]
	global_store_dwordx4 v[98:99], v[102:105], off offset:64 sc0 sc1
	s_waitcnt lgkmcnt(0)
	ds_write_b16 v217, v0
	v_cvt_pk_bf16_f32 v0, v95, s0
	ds_write_b16 v217, v0 offset:72
	v_cvt_pk_bf16_f32 v0, v96, s0
	ds_write_b16 v217, v0 offset:144
	v_cvt_pk_bf16_f32 v0, v97, s0
	ds_write_b16 v217, v0 offset:216
	v_cvt_pk_bf16_f32 v0, v90, s0
	ds_write_b16 v217, v0 offset:288
	v_cvt_pk_bf16_f32 v0, v91, s0
	ds_write_b16 v217, v0 offset:360
	v_cvt_pk_bf16_f32 v0, v92, s0
	ds_write_b16 v217, v0 offset:432
	v_cvt_pk_bf16_f32 v0, v93, s0
	ds_write_b16 v217, v0 offset:504
	v_cvt_pk_bf16_f32 v0, v86, s0
	ds_write_b16 v217, v0 offset:32
	v_cvt_pk_bf16_f32 v0, v87, s0
	ds_write_b16 v217, v0 offset:104
	v_cvt_pk_bf16_f32 v0, v88, s0
	ds_write_b16 v217, v0 offset:176
	v_cvt_pk_bf16_f32 v0, v89, s0
	ds_write_b16 v217, v0 offset:248
	v_cvt_pk_bf16_f32 v0, v82, s0
	ds_write_b16 v217, v0 offset:320
	v_cvt_pk_bf16_f32 v0, v83, s0
	ds_write_b16 v217, v0 offset:392
	v_cvt_pk_bf16_f32 v0, v84, s0
	s_and_b32 s3, s3, 0x600
	ds_write_b16 v217, v0 offset:464
	v_cvt_pk_bf16_f32 v0, v85, s0
	s_bitset1_b32 s3, 8
	ds_write_b16 v217, v0 offset:536
	s_add_i32 s4, s1, s3
	s_waitcnt lgkmcnt(0)
	s_ashr_i32 s5, s4, 31
	ds_read2_b64 v[82:85], v219 offset1:1
	ds_read2_b64 v[86:89], v219 offset0:144 offset1:145
	s_lshl_b64 s[4:5], s[4:5], 14
	s_add_u32 s4, s71, s4
	s_addc_u32 s5, s72, s5
	v_lshl_add_u64 v[90:91], s[4:5], 0, v[174:175]
	v_lshl_add_u64 v[90:91], v[90:91], 0, v[188:189]
	s_waitcnt lgkmcnt(0)
	global_store_dwordx4 v[90:91], v[82:85], off sc0 sc1
	v_cvt_pk_bf16_f32 v0, v78, s0
	s_nop 0
	v_lshl_add_u64 v[82:83], s[4:5], 0, v[190:191]
	v_lshl_add_u64 v[82:83], v[82:83], 0, v[188:189]
	global_store_dwordx4 v[82:83], v[86:89], off sc0 sc1
	s_waitcnt lgkmcnt(0)
	ds_write_b16 v217, v0
	v_cvt_pk_bf16_f32 v0, v79, s0
	ds_write_b16 v217, v0 offset:72
	v_cvt_pk_bf16_f32 v0, v80, s0
	ds_write_b16 v217, v0 offset:144
	v_cvt_pk_bf16_f32 v0, v81, s0
	ds_write_b16 v217, v0 offset:216
	v_cvt_pk_bf16_f32 v0, v74, s0
	ds_write_b16 v217, v0 offset:288
	v_cvt_pk_bf16_f32 v0, v75, s0
	ds_write_b16 v217, v0 offset:360
	v_cvt_pk_bf16_f32 v0, v76, s0
	ds_write_b16 v217, v0 offset:432
	v_cvt_pk_bf16_f32 v0, v77, s0
	ds_write_b16 v217, v0 offset:504
	v_cvt_pk_bf16_f32 v0, v70, s0
	ds_write_b16 v217, v0 offset:32
	v_cvt_pk_bf16_f32 v0, v71, s0
	ds_write_b16 v217, v0 offset:104
	v_cvt_pk_bf16_f32 v0, v72, s0
	ds_write_b16 v217, v0 offset:176
	v_cvt_pk_bf16_f32 v0, v73, s0
	ds_write_b16 v217, v0 offset:248
	v_cvt_pk_bf16_f32 v0, v66, s0
	ds_write_b16 v217, v0 offset:320
	v_cvt_pk_bf16_f32 v0, v67, s0
	ds_write_b16 v217, v0 offset:392
	v_cvt_pk_bf16_f32 v0, v68, s0
	ds_write_b16 v217, v0 offset:464
	v_cvt_pk_bf16_f32 v0, v69, s0
	ds_write_b16 v217, v0 offset:536
	s_waitcnt lgkmcnt(0)
	ds_read2_b64 v[66:69], v219 offset1:1
	ds_read2_b64 v[70:73], v219 offset0:144 offset1:145
	v_lshl_add_u64 v[74:75], s[4:5], 0, v[192:193]
	v_lshl_add_u64 v[74:75], v[74:75], 0, v[188:189]
	v_cvt_pk_bf16_f32 v0, v62, s0
	s_waitcnt lgkmcnt(0)
	global_store_dwordx4 v[74:75], v[66:69], off offset:64 sc0 sc1
	s_nop 1
	v_lshl_add_u64 v[66:67], s[4:5], 0, v[194:195]
	v_lshl_add_u64 v[66:67], v[66:67], 0, v[188:189]
	global_store_dwordx4 v[66:67], v[70:73], off offset:64 sc0 sc1
	s_waitcnt lgkmcnt(0)
	ds_write_b16 v217, v0
	v_cvt_pk_bf16_f32 v0, v63, s0
	ds_write_b16 v217, v0 offset:72
	v_cvt_pk_bf16_f32 v0, v64, s0
	ds_write_b16 v217, v0 offset:144
	v_cvt_pk_bf16_f32 v0, v65, s0
	ds_write_b16 v217, v0 offset:216
	v_cvt_pk_bf16_f32 v0, v58, s0
	ds_write_b16 v217, v0 offset:288
	v_cvt_pk_bf16_f32 v0, v59, s0
	ds_write_b16 v217, v0 offset:360
	v_cvt_pk_bf16_f32 v0, v60, s0
	ds_write_b16 v217, v0 offset:432
	v_cvt_pk_bf16_f32 v0, v61, s0
	ds_write_b16 v217, v0 offset:504
	v_cvt_pk_bf16_f32 v0, v54, s0
	ds_write_b16 v217, v0 offset:32
	v_cvt_pk_bf16_f32 v0, v55, s0
	ds_write_b16 v217, v0 offset:104
	v_cvt_pk_bf16_f32 v0, v56, s0
	ds_write_b16 v217, v0 offset:176
	v_cvt_pk_bf16_f32 v0, v57, s0
	ds_write_b16 v217, v0 offset:248
	v_cvt_pk_bf16_f32 v0, v50, s0
	ds_write_b16 v217, v0 offset:320
	v_cvt_pk_bf16_f32 v0, v51, s0
	ds_write_b16 v217, v0 offset:392
	v_cvt_pk_bf16_f32 v0, v52, s0
	ds_write_b16 v217, v0 offset:464
	v_cvt_pk_bf16_f32 v0, v53, s0
	s_add_i32 s4, s1, 2
	ds_write_b16 v217, v0 offset:536
	s_add_i32 s0, s4, s0
	s_waitcnt lgkmcnt(0)
	s_ashr_i32 s1, s0, 31
	ds_read2_b64 v[50:53], v219 offset1:1
	ds_read2_b64 v[54:57], v219 offset0:144 offset1:145
	s_lshl_b64 s[0:1], s[0:1], 14
	s_add_u32 s0, s71, s0
	s_addc_u32 s1, s72, s1
	v_lshl_add_u64 v[58:59], s[0:1], 0, v[174:175]
	v_lshl_add_u64 v[58:59], v[58:59], 0, v[188:189]
	s_waitcnt lgkmcnt(0)
	global_store_dwordx4 v[58:59], v[50:53], off sc0 sc1
	v_cvt_pk_bf16_f32 v0, v46, s0
	s_nop 0
	v_lshl_add_u64 v[50:51], s[0:1], 0, v[190:191]
	v_lshl_add_u64 v[50:51], v[50:51], 0, v[188:189]
	global_store_dwordx4 v[50:51], v[54:57], off sc0 sc1
	s_waitcnt lgkmcnt(0)
	ds_write_b16 v217, v0
	v_cvt_pk_bf16_f32 v0, v47, s0
	ds_write_b16 v217, v0 offset:72
	v_cvt_pk_bf16_f32 v0, v48, s0
	ds_write_b16 v217, v0 offset:144
	v_cvt_pk_bf16_f32 v0, v49, s0
	ds_write_b16 v217, v0 offset:216
	v_cvt_pk_bf16_f32 v0, v42, s0
	ds_write_b16 v217, v0 offset:288
	v_cvt_pk_bf16_f32 v0, v43, s0
	ds_write_b16 v217, v0 offset:360
	v_cvt_pk_bf16_f32 v0, v44, s0
	ds_write_b16 v217, v0 offset:432
	v_cvt_pk_bf16_f32 v0, v45, s0
	ds_write_b16 v217, v0 offset:504
	v_cvt_pk_bf16_f32 v0, v38, s0
	ds_write_b16 v217, v0 offset:32
	v_cvt_pk_bf16_f32 v0, v39, s0
	ds_write_b16 v217, v0 offset:104
	v_cvt_pk_bf16_f32 v0, v40, s0
	ds_write_b16 v217, v0 offset:176
	v_cvt_pk_bf16_f32 v0, v41, s0
	ds_write_b16 v217, v0 offset:248
	v_cvt_pk_bf16_f32 v0, v34, s0
	ds_write_b16 v217, v0 offset:320
	v_cvt_pk_bf16_f32 v0, v35, s0
	ds_write_b16 v217, v0 offset:392
	v_cvt_pk_bf16_f32 v0, v36, s0
	ds_write_b16 v217, v0 offset:464
	v_cvt_pk_bf16_f32 v0, v37, s0
	ds_write_b16 v217, v0 offset:536
	s_waitcnt lgkmcnt(0)
	ds_read2_b64 v[34:37], v219 offset1:1
	ds_read2_b64 v[38:41], v219 offset0:144 offset1:145
	v_lshl_add_u64 v[42:43], s[0:1], 0, v[192:193]
	v_lshl_add_u64 v[42:43], v[42:43], 0, v[188:189]
	v_cvt_pk_bf16_f32 v0, v30, s0
	s_waitcnt lgkmcnt(0)
	global_store_dwordx4 v[42:43], v[34:37], off offset:64 sc0 sc1
	s_nop 1
	v_lshl_add_u64 v[34:35], s[0:1], 0, v[194:195]
	v_lshl_add_u64 v[34:35], v[34:35], 0, v[188:189]
	global_store_dwordx4 v[34:35], v[38:41], off offset:64 sc0 sc1
	s_waitcnt lgkmcnt(0)
	ds_write_b16 v217, v0
	v_cvt_pk_bf16_f32 v0, v31, s0
	ds_write_b16 v217, v0 offset:72
	v_cvt_pk_bf16_f32 v0, v32, s0
	ds_write_b16 v217, v0 offset:144
	v_cvt_pk_bf16_f32 v0, v33, s0
	ds_write_b16 v217, v0 offset:216
	v_cvt_pk_bf16_f32 v0, v26, s0
	ds_write_b16 v217, v0 offset:288
	v_cvt_pk_bf16_f32 v0, v27, s0
	ds_write_b16 v217, v0 offset:360
	v_cvt_pk_bf16_f32 v0, v28, s0
	ds_write_b16 v217, v0 offset:432
	v_cvt_pk_bf16_f32 v0, v29, s0
	ds_write_b16 v217, v0 offset:504
	v_cvt_pk_bf16_f32 v0, v22, s0
	ds_write_b16 v217, v0 offset:32
	v_cvt_pk_bf16_f32 v0, v23, s0
	ds_write_b16 v217, v0 offset:104
	v_cvt_pk_bf16_f32 v0, v24, s0
	ds_write_b16 v217, v0 offset:176
	v_cvt_pk_bf16_f32 v0, v25, s0
	ds_write_b16 v217, v0 offset:248
	v_cvt_pk_bf16_f32 v0, v18, s0
	ds_write_b16 v217, v0 offset:320
	v_cvt_pk_bf16_f32 v0, v19, s0
	ds_write_b16 v217, v0 offset:392
	v_cvt_pk_bf16_f32 v0, v20, s0
	ds_write_b16 v217, v0 offset:464
	v_cvt_pk_bf16_f32 v0, v21, s0
	ds_write_b16 v217, v0 offset:536
	s_add_i32 s0, s4, s3
	s_waitcnt lgkmcnt(0)
	s_ashr_i32 s1, s0, 31
	ds_read2_b64 v[18:21], v219 offset1:1
	ds_read2_b64 v[22:25], v219 offset0:144 offset1:145
	s_lshl_b64 s[0:1], s[0:1], 14
	s_add_u32 s0, s71, s0
	s_addc_u32 s1, s72, s1
	v_lshl_add_u64 v[26:27], s[0:1], 0, v[174:175]
	v_lshl_add_u64 v[26:27], v[26:27], 0, v[188:189]
	s_waitcnt lgkmcnt(0)
	global_store_dwordx4 v[26:27], v[18:21], off sc0 sc1
	v_cvt_pk_bf16_f32 v0, v14, s0
	s_nop 0
	v_lshl_add_u64 v[18:19], s[0:1], 0, v[190:191]
	v_lshl_add_u64 v[18:19], v[18:19], 0, v[188:189]
	global_store_dwordx4 v[18:19], v[22:25], off sc0 sc1
	s_waitcnt lgkmcnt(0)
	ds_write_b16 v217, v0
	v_cvt_pk_bf16_f32 v0, v15, s0
	ds_write_b16 v217, v0 offset:72
	v_cvt_pk_bf16_f32 v0, v16, s0
	ds_write_b16 v217, v0 offset:144
	v_cvt_pk_bf16_f32 v0, v17, s0
	ds_write_b16 v217, v0 offset:216
	v_cvt_pk_bf16_f32 v0, v10, s0
	ds_write_b16 v217, v0 offset:288
	v_cvt_pk_bf16_f32 v0, v11, s0
	ds_write_b16 v217, v0 offset:360
	v_cvt_pk_bf16_f32 v0, v12, s0
	ds_write_b16 v217, v0 offset:432
	v_cvt_pk_bf16_f32 v0, v13, s0
	ds_write_b16 v217, v0 offset:504
	v_cvt_pk_bf16_f32 v0, v6, s0
	ds_write_b16 v217, v0 offset:32
	v_cvt_pk_bf16_f32 v0, v7, s0
	ds_write_b16 v217, v0 offset:104
	v_cvt_pk_bf16_f32 v0, v8, s0
	ds_write_b16 v217, v0 offset:176
	v_cvt_pk_bf16_f32 v0, v9, s0
	ds_write_b16 v217, v0 offset:248
	v_cvt_pk_bf16_f32 v0, v2, s0
	ds_write_b16 v217, v0 offset:320
	v_cvt_pk_bf16_f32 v0, v3, s0
	ds_write_b16 v217, v0 offset:392
	v_cvt_pk_bf16_f32 v0, v4, s0
	ds_write_b16 v217, v0 offset:464
	v_cvt_pk_bf16_f32 v0, v5, s0
	ds_write_b16 v217, v0 offset:536
	s_waitcnt lgkmcnt(0)
	ds_read2_b64 v[2:5], v219 offset1:1
	ds_read2_b64 v[6:9], v219 offset0:144 offset1:145
	v_lshl_add_u64 v[10:11], s[0:1], 0, v[192:193]
	v_lshl_add_u64 v[10:11], v[10:11], 0, v[188:189]
	s_waitcnt lgkmcnt(0)
	global_store_dwordx4 v[10:11], v[2:5], off offset:64 sc0 sc1
	s_nop 1
	v_lshl_add_u64 v[2:3], s[0:1], 0, v[194:195]
	v_lshl_add_u64 v[2:3], v[2:3], 0, v[188:189]
	global_store_dwordx4 v[2:3], v[6:9], off offset:64 sc0 sc1
	s_waitcnt lgkmcnt(0)
	s_andn2_b64 vcc, exec, s[10:11]
	s_mov_b64 s[0:1], -1
	s_cbranch_vccnz .LBB0_391

.LBB0_849:
	v_lshl_or_b32 v158, s30, 8, v164
	v_readlane_b32 s0, v253, 50
	v_ashrrev_i32_e32 v159, 31, v158
	v_readlane_b32 s1, v253, 51
	v_lshl_add_u32 v160, s29, 8, v162
	v_ashrrev_i32_e32 v161, 31, v160
	v_lshl_add_u64 v[156:157], v[158:159], 2, s[0:1]
	global_load_dwordx4 v[140:143], v[156:157], off offset:16
	global_load_dwordx4 v[144:147], v[156:157], off
	v_readlane_b32 s0, v253, 58
	v_readlane_b32 s1, v253, 59
	s_mov_b64 s[18:19], 0x40000
	s_andn2_b64 vcc, exec, s[4:5]
	s_mov_b32 s44, 0x8000
	s_mov_b32 s45, 0xa000
	s_waitcnt vmcnt(0)
	v_pk_add_f32 v[148:149], v[142:143], 1.0 op_sel_hi:[1,0]
	v_pk_add_f32 v[150:151], v[140:141], 1.0 op_sel_hi:[1,0]
	global_load_dwordx4 v[166:169], v[156:157], off offset:528
	global_load_dwordx4 v[140:143], v[156:157], off offset:512
	v_lshlrev_b64 v[156:157], 11, v[160:161]
	v_lshl_add_u64 v[156:157], v[156:157], 0, v[158:159]
	v_lshl_add_u64 v[174:175], v[156:157], 2, s[0:1]
	v_pk_add_f32 v[152:153], v[146:147], 1.0 op_sel_hi:[1,0]
	v_pk_add_f32 v[154:155], v[144:145], 1.0 op_sel_hi:[1,0]
	s_waitcnt vmcnt(0)
	v_pk_add_f32 v[144:145], v[142:143], 1.0 op_sel_hi:[1,0]
	v_pk_add_f32 v[146:147], v[140:141], 1.0 op_sel_hi:[1,0]
	v_pk_add_f32 v[140:141], v[168:169], 1.0 op_sel_hi:[1,0]
	v_pk_add_f32 v[142:143], v[166:167], 1.0 op_sel_hi:[1,0]
	global_load_dwordx4 v[166:169], v[174:175], off offset:16
	global_load_dwordx4 v[170:173], v[174:175], off
	s_waitcnt vmcnt(1)
	v_pk_mul_f32 v[168:169], v[168:169], s[60:61] op_sel_hi:[1,0]
	s_waitcnt vmcnt(0)
	v_pk_mul_f32 v[172:173], v[172:173], s[60:61] op_sel_hi:[1,0]
	v_pk_mul_f32 v[170:171], v[170:171], s[60:61] op_sel_hi:[1,0]
	v_pk_mul_f32 v[166:167], v[166:167], s[60:61] op_sel_hi:[1,0]
	v_pk_fma_f32 v[128:129], v[128:129], v[152:153], v[172:173]
	v_pk_fma_f32 v[126:127], v[126:127], v[154:155], v[170:171]
	v_pk_fma_f32 v[168:169], v[124:125], v[148:149], v[168:169]
	v_pk_fma_f32 v[124:125], v[122:123], v[150:151], v[166:167]
	v_lshlrev_b64 v[166:167], 1, v[156:157]
	v_cvt_pk_bf16_f32 v122, v126, v127
	v_cvt_pk_bf16_f32 v123, v128, v129
	v_cvt_pk_bf16_f32 v124, v124, v125
	v_cvt_pk_bf16_f32 v125, v168, v169
	v_lshl_add_u64 v[126:127], s[50:51], 0, v[166:167]
	global_store_dwordx4 v[126:127], v[122:125], off sc0 sc1
	global_load_dwordx4 v[122:125], v[174:175], off offset:528
	s_nop 0
	global_load_dwordx4 v[126:129], v[174:175], off offset:512
	v_or_b32_e32 v166, 0x100, v166
	s_waitcnt vmcnt(1)
	v_pk_mul_f32 v[124:125], v[124:125], s[60:61] op_sel_hi:[1,0]
	s_waitcnt vmcnt(0)
	v_pk_mul_f32 v[128:129], v[128:129], s[60:61] op_sel_hi:[1,0]
	v_pk_mul_f32 v[126:127], v[126:127], s[60:61] op_sel_hi:[1,0]
	v_pk_mul_f32 v[122:123], v[122:123], s[60:61] op_sel_hi:[1,0]
	v_pk_fma_f32 v[120:121], v[120:121], v[144:145], v[128:129]
	v_pk_fma_f32 v[118:119], v[118:119], v[146:147], v[126:127]
	v_pk_fma_f32 v[124:125], v[116:117], v[140:141], v[124:125]
	v_pk_fma_f32 v[116:117], v[114:115], v[142:143], v[122:123]
	v_cvt_pk_bf16_f32 v114, v118, v119
	v_cvt_pk_bf16_f32 v115, v120, v121
	v_cvt_pk_bf16_f32 v116, v116, v117
	v_cvt_pk_bf16_f32 v117, v124, v125
	v_lshl_add_u64 v[118:119], s[50:51], 0, v[166:167]
	global_store_dwordx4 v[118:119], v[114:117], off sc0 sc1
	s_nop 1
	v_or_b32_e32 v114, 16, v160
	v_ashrrev_i32_e32 v115, 31, v114
	v_lshlrev_b64 v[114:115], 11, v[114:115]
	v_lshl_add_u64 v[122:123], v[114:115], 0, v[158:159]
	v_lshl_add_u64 v[124:125], v[122:123], 2, s[0:1]
	global_load_dwordx4 v[114:117], v[124:125], off offset:16
	global_load_dwordx4 v[118:121], v[124:125], off
	s_waitcnt vmcnt(1)
	v_pk_mul_f32 v[116:117], v[116:117], s[60:61] op_sel_hi:[1,0]
	s_waitcnt vmcnt(0)
	v_pk_mul_f32 v[120:121], v[120:121], s[60:61] op_sel_hi:[1,0]
	v_pk_mul_f32 v[118:119], v[118:119], s[60:61] op_sel_hi:[1,0]
	v_pk_mul_f32 v[114:115], v[114:115], s[60:61] op_sel_hi:[1,0]
	v_pk_fma_f32 v[112:113], v[112:113], v[152:153], v[120:121]
	v_pk_fma_f32 v[110:111], v[110:111], v[154:155], v[118:119]
	v_pk_fma_f32 v[116:117], v[108:109], v[148:149], v[116:117]
	v_pk_fma_f32 v[108:109], v[106:107], v[150:151], v[114:115]
	v_lshlrev_b64 v[114:115], 1, v[122:123]
	v_cvt_pk_bf16_f32 v106, v110, v111
	v_cvt_pk_bf16_f32 v107, v112, v113
	v_cvt_pk_bf16_f32 v108, v108, v109
	v_cvt_pk_bf16_f32 v109, v116, v117
	v_lshl_add_u64 v[110:111], s[50:51], 0, v[114:115]
	global_store_dwordx4 v[110:111], v[106:109], off sc0 sc1
	global_load_dwordx4 v[106:109], v[124:125], off offset:528
	s_nop 0
	global_load_dwordx4 v[110:113], v[124:125], off offset:512
	v_or_b32_e32 v114, 0x100, v114
	s_waitcnt vmcnt(1)
	v_pk_mul_f32 v[108:109], v[108:109], s[60:61] op_sel_hi:[1,0]
	s_waitcnt vmcnt(0)
	v_pk_mul_f32 v[112:113], v[112:113], s[60:61] op_sel_hi:[1,0]
	v_pk_mul_f32 v[110:111], v[110:111], s[60:61] op_sel_hi:[1,0]
	v_pk_mul_f32 v[106:107], v[106:107], s[60:61] op_sel_hi:[1,0]
	v_pk_fma_f32 v[104:105], v[104:105], v[144:145], v[112:113]
	v_pk_fma_f32 v[102:103], v[102:103], v[146:147], v[110:111]
	v_pk_fma_f32 v[108:109], v[100:101], v[140:141], v[108:109]
	v_pk_fma_f32 v[100:101], v[98:99], v[142:143], v[106:107]
	v_cvt_pk_bf16_f32 v98, v102, v103
	v_cvt_pk_bf16_f32 v99, v104, v105
	v_cvt_pk_bf16_f32 v100, v100, v101
	v_cvt_pk_bf16_f32 v101, v108, v109
	v_lshl_add_u64 v[102:103], s[50:51], 0, v[114:115]
	global_store_dwordx4 v[102:103], v[98:101], off sc0 sc1
	s_nop 1
	v_or_b32_e32 v98, 32, v160
	v_ashrrev_i32_e32 v99, 31, v98
	v_lshlrev_b64 v[98:99], 11, v[98:99]
	v_lshl_add_u64 v[106:107], v[98:99], 0, v[158:159]
	v_lshl_add_u64 v[108:109], v[106:107], 2, s[0:1]
	global_load_dwordx4 v[98:101], v[108:109], off offset:16
	global_load_dwordx4 v[102:105], v[108:109], off
	s_waitcnt vmcnt(1)
	v_pk_mul_f32 v[100:101], v[100:101], s[60:61] op_sel_hi:[1,0]
	s_waitcnt vmcnt(0)
	v_pk_mul_f32 v[104:105], v[104:105], s[60:61] op_sel_hi:[1,0]
	v_pk_mul_f32 v[102:103], v[102:103], s[60:61] op_sel_hi:[1,0]
	v_pk_mul_f32 v[98:99], v[98:99], s[60:61] op_sel_hi:[1,0]
	v_pk_fma_f32 v[96:97], v[96:97], v[152:153], v[104:105]
	v_pk_fma_f32 v[94:95], v[94:95], v[154:155], v[102:103]
	v_pk_fma_f32 v[100:101], v[92:93], v[148:149], v[100:101]
	v_pk_fma_f32 v[92:93], v[90:91], v[150:151], v[98:99]
	v_lshlrev_b64 v[98:99], 1, v[106:107]
	v_cvt_pk_bf16_f32 v90, v94, v95
	v_cvt_pk_bf16_f32 v91, v96, v97
	v_cvt_pk_bf16_f32 v92, v92, v93
	v_cvt_pk_bf16_f32 v93, v100, v101
	v_lshl_add_u64 v[94:95], s[50:51], 0, v[98:99]
	global_store_dwordx4 v[94:95], v[90:93], off sc0 sc1
	global_load_dwordx4 v[90:93], v[108:109], off offset:528
	s_nop 0
	global_load_dwordx4 v[94:97], v[108:109], off offset:512
	v_or_b32_e32 v98, 0x100, v98
	s_waitcnt vmcnt(1)
	v_pk_mul_f32 v[92:93], v[92:93], s[60:61] op_sel_hi:[1,0]
	s_waitcnt vmcnt(0)
	v_pk_mul_f32 v[96:97], v[96:97], s[60:61] op_sel_hi:[1,0]
	v_pk_mul_f32 v[94:95], v[94:95], s[60:61] op_sel_hi:[1,0]
	v_pk_mul_f32 v[90:91], v[90:91], s[60:61] op_sel_hi:[1,0]
	v_pk_fma_f32 v[88:89], v[88:89], v[144:145], v[96:97]
	v_pk_fma_f32 v[86:87], v[86:87], v[146:147], v[94:95]
	v_pk_fma_f32 v[92:93], v[84:85], v[140:141], v[92:93]
	v_pk_fma_f32 v[84:85], v[82:83], v[142:143], v[90:91]
	v_cvt_pk_bf16_f32 v82, v86, v87
	v_cvt_pk_bf16_f32 v83, v88, v89
	v_cvt_pk_bf16_f32 v84, v84, v85
	v_cvt_pk_bf16_f32 v85, v92, v93
	v_lshl_add_u64 v[86:87], s[50:51], 0, v[98:99]
	global_store_dwordx4 v[86:87], v[82:85], off sc0 sc1
	s_nop 1
	v_or_b32_e32 v82, 48, v160
	v_ashrrev_i32_e32 v83, 31, v82
	v_lshlrev_b64 v[82:83], 11, v[82:83]
	v_lshl_add_u64 v[90:91], v[82:83], 0, v[158:159]
	v_lshl_add_u64 v[92:93], v[90:91], 2, s[0:1]
	global_load_dwordx4 v[82:85], v[92:93], off offset:16
	global_load_dwordx4 v[86:89], v[92:93], off
	s_waitcnt vmcnt(1)
	v_pk_mul_f32 v[84:85], v[84:85], s[60:61] op_sel_hi:[1,0]
	s_waitcnt vmcnt(0)
	v_pk_mul_f32 v[88:89], v[88:89], s[60:61] op_sel_hi:[1,0]
	v_pk_mul_f32 v[86:87], v[86:87], s[60:61] op_sel_hi:[1,0]
	v_pk_mul_f32 v[82:83], v[82:83], s[60:61] op_sel_hi:[1,0]
	v_pk_fma_f32 v[80:81], v[80:81], v[152:153], v[88:89]
	v_pk_fma_f32 v[78:79], v[78:79], v[154:155], v[86:87]
	v_pk_fma_f32 v[84:85], v[76:77], v[148:149], v[84:85]
	v_pk_fma_f32 v[76:77], v[74:75], v[150:151], v[82:83]
	v_lshlrev_b64 v[82:83], 1, v[90:91]
	v_cvt_pk_bf16_f32 v74, v78, v79
	v_cvt_pk_bf16_f32 v75, v80, v81
	v_cvt_pk_bf16_f32 v76, v76, v77
	v_cvt_pk_bf16_f32 v77, v84, v85
	v_lshl_add_u64 v[78:79], s[50:51], 0, v[82:83]
	global_store_dwordx4 v[78:79], v[74:77], off sc0 sc1
	global_load_dwordx4 v[74:77], v[92:93], off offset:528
	s_nop 0
	global_load_dwordx4 v[78:81], v[92:93], off offset:512
	v_or_b32_e32 v82, 0x100, v82
	s_waitcnt vmcnt(1)
	v_pk_mul_f32 v[76:77], v[76:77], s[60:61] op_sel_hi:[1,0]
	s_waitcnt vmcnt(0)
	v_pk_mul_f32 v[80:81], v[80:81], s[60:61] op_sel_hi:[1,0]
	v_pk_mul_f32 v[78:79], v[78:79], s[60:61] op_sel_hi:[1,0]
	v_pk_mul_f32 v[74:75], v[74:75], s[60:61] op_sel_hi:[1,0]
	v_pk_fma_f32 v[72:73], v[72:73], v[144:145], v[80:81]
	v_pk_fma_f32 v[70:71], v[70:71], v[146:147], v[78:79]
	v_pk_fma_f32 v[76:77], v[68:69], v[140:141], v[76:77]
	v_pk_fma_f32 v[68:69], v[66:67], v[142:143], v[74:75]
	v_cvt_pk_bf16_f32 v66, v70, v71
	v_cvt_pk_bf16_f32 v67, v72, v73
	v_cvt_pk_bf16_f32 v68, v68, v69
	v_cvt_pk_bf16_f32 v69, v76, v77
	v_lshl_add_u64 v[70:71], s[50:51], 0, v[82:83]
	v_lshl_add_u64 v[74:75], v[156:157], 0, s[18:19]
	global_store_dwordx4 v[70:71], v[66:69], off sc0 sc1
	v_lshl_add_u64 v[76:77], v[74:75], 2, s[0:1]
	global_load_dwordx4 v[66:69], v[76:77], off offset:16
	global_load_dwordx4 v[70:73], v[76:77], off
	s_mov_b64 s[18:19], 0x48000
	s_waitcnt vmcnt(1)
	v_pk_mul_f32 v[68:69], v[68:69], s[60:61] op_sel_hi:[1,0]
	s_waitcnt vmcnt(0)
	v_pk_mul_f32 v[72:73], v[72:73], s[60:61] op_sel_hi:[1,0]
	v_pk_mul_f32 v[70:71], v[70:71], s[60:61] op_sel_hi:[1,0]
	v_pk_mul_f32 v[66:67], v[66:67], s[60:61] op_sel_hi:[1,0]
	v_pk_fma_f32 v[64:65], v[64:65], v[152:153], v[72:73]
	v_pk_fma_f32 v[62:63], v[62:63], v[154:155], v[70:71]
	v_pk_fma_f32 v[68:69], v[60:61], v[148:149], v[68:69]
	v_pk_fma_f32 v[60:61], v[58:59], v[150:151], v[66:67]
	v_lshlrev_b64 v[66:67], 1, v[74:75]
	v_cvt_pk_bf16_f32 v58, v62, v63
	v_cvt_pk_bf16_f32 v59, v64, v65
	v_cvt_pk_bf16_f32 v60, v60, v61
	v_cvt_pk_bf16_f32 v61, v68, v69
	v_lshl_add_u64 v[62:63], s[50:51], 0, v[66:67]
	global_store_dwordx4 v[62:63], v[58:61], off sc0 sc1
	global_load_dwordx4 v[58:61], v[76:77], off offset:528
	s_nop 0
	global_load_dwordx4 v[62:65], v[76:77], off offset:512
	v_or_b32_e32 v66, 0x100, v66
	s_waitcnt vmcnt(1)
	v_pk_mul_f32 v[60:61], v[60:61], s[60:61] op_sel_hi:[1,0]
	s_waitcnt vmcnt(0)
	v_pk_mul_f32 v[64:65], v[64:65], s[60:61] op_sel_hi:[1,0]
	v_pk_mul_f32 v[62:63], v[62:63], s[60:61] op_sel_hi:[1,0]
	v_pk_mul_f32 v[58:59], v[58:59], s[60:61] op_sel_hi:[1,0]
	v_pk_fma_f32 v[56:57], v[56:57], v[144:145], v[64:65]
	v_pk_fma_f32 v[54:55], v[54:55], v[146:147], v[62:63]
	v_pk_fma_f32 v[60:61], v[52:53], v[140:141], v[60:61]
	v_pk_fma_f32 v[52:53], v[50:51], v[142:143], v[58:59]
	v_cvt_pk_bf16_f32 v50, v54, v55
	v_cvt_pk_bf16_f32 v51, v56, v57
	v_cvt_pk_bf16_f32 v52, v52, v53
	v_cvt_pk_bf16_f32 v53, v60, v61
	v_lshl_add_u64 v[54:55], s[50:51], 0, v[66:67]
	v_lshl_add_u64 v[58:59], v[156:157], 0, s[18:19]
	global_store_dwordx4 v[54:55], v[50:53], off sc0 sc1
	v_lshl_add_u64 v[60:61], v[58:59], 2, s[0:1]
	global_load_dwordx4 v[50:53], v[60:61], off offset:16
	global_load_dwordx4 v[54:57], v[60:61], off
	s_mov_b64 s[18:19], 0x50000
	s_waitcnt vmcnt(1)
	v_pk_mul_f32 v[52:53], v[52:53], s[60:61] op_sel_hi:[1,0]
	s_waitcnt vmcnt(0)
	v_pk_mul_f32 v[56:57], v[56:57], s[60:61] op_sel_hi:[1,0]
	v_pk_mul_f32 v[54:55], v[54:55], s[60:61] op_sel_hi:[1,0]
	v_pk_mul_f32 v[50:51], v[50:51], s[60:61] op_sel_hi:[1,0]
	v_pk_fma_f32 v[48:49], v[48:49], v[152:153], v[56:57]
	v_pk_fma_f32 v[46:47], v[46:47], v[154:155], v[54:55]
	v_pk_fma_f32 v[52:53], v[44:45], v[148:149], v[52:53]
	v_pk_fma_f32 v[44:45], v[42:43], v[150:151], v[50:51]
	v_lshlrev_b64 v[50:51], 1, v[58:59]
	v_cvt_pk_bf16_f32 v42, v46, v47
	v_cvt_pk_bf16_f32 v43, v48, v49
	v_cvt_pk_bf16_f32 v44, v44, v45
	v_cvt_pk_bf16_f32 v45, v52, v53
	v_lshl_add_u64 v[46:47], s[50:51], 0, v[50:51]
	global_store_dwordx4 v[46:47], v[42:45], off sc0 sc1
	global_load_dwordx4 v[42:45], v[60:61], off offset:528
	s_nop 0
	global_load_dwordx4 v[46:49], v[60:61], off offset:512
	v_or_b32_e32 v50, 0x100, v50
	s_waitcnt vmcnt(1)
	v_pk_mul_f32 v[44:45], v[44:45], s[60:61] op_sel_hi:[1,0]
	s_waitcnt vmcnt(0)
	v_pk_mul_f32 v[48:49], v[48:49], s[60:61] op_sel_hi:[1,0]
	v_pk_mul_f32 v[46:47], v[46:47], s[60:61] op_sel_hi:[1,0]
	v_pk_mul_f32 v[42:43], v[42:43], s[60:61] op_sel_hi:[1,0]
	v_pk_fma_f32 v[40:41], v[40:41], v[144:145], v[48:49]
	v_pk_fma_f32 v[38:39], v[38:39], v[146:147], v[46:47]
	v_pk_fma_f32 v[44:45], v[36:37], v[140:141], v[44:45]
	v_pk_fma_f32 v[36:37], v[34:35], v[142:143], v[42:43]
	v_cvt_pk_bf16_f32 v34, v38, v39
	v_cvt_pk_bf16_f32 v35, v40, v41
	v_cvt_pk_bf16_f32 v36, v36, v37
	v_cvt_pk_bf16_f32 v37, v44, v45
	v_lshl_add_u64 v[38:39], s[50:51], 0, v[50:51]
	v_lshl_add_u64 v[42:43], v[156:157], 0, s[18:19]
	global_store_dwordx4 v[38:39], v[34:37], off sc0 sc1
	v_lshl_add_u64 v[44:45], v[42:43], 2, s[0:1]
	global_load_dwordx4 v[34:37], v[44:45], off offset:16
	global_load_dwordx4 v[38:41], v[44:45], off
	s_mov_b64 s[18:19], 0x58000
	s_waitcnt vmcnt(1)
	v_pk_mul_f32 v[36:37], v[36:37], s[60:61] op_sel_hi:[1,0]
	s_waitcnt vmcnt(0)
	v_pk_mul_f32 v[40:41], v[40:41], s[60:61] op_sel_hi:[1,0]
	v_pk_mul_f32 v[38:39], v[38:39], s[60:61] op_sel_hi:[1,0]
	v_pk_mul_f32 v[34:35], v[34:35], s[60:61] op_sel_hi:[1,0]
	v_pk_fma_f32 v[32:33], v[32:33], v[152:153], v[40:41]
	v_pk_fma_f32 v[30:31], v[30:31], v[154:155], v[38:39]
	v_pk_fma_f32 v[36:37], v[28:29], v[148:149], v[36:37]
	v_pk_fma_f32 v[28:29], v[26:27], v[150:151], v[34:35]
	v_lshlrev_b64 v[34:35], 1, v[42:43]
	v_cvt_pk_bf16_f32 v26, v30, v31
	v_cvt_pk_bf16_f32 v27, v32, v33
	v_cvt_pk_bf16_f32 v28, v28, v29
	v_cvt_pk_bf16_f32 v29, v36, v37
	v_lshl_add_u64 v[30:31], s[50:51], 0, v[34:35]
	global_store_dwordx4 v[30:31], v[26:29], off sc0 sc1
	global_load_dwordx4 v[26:29], v[44:45], off offset:528
	s_nop 0
	global_load_dwordx4 v[30:33], v[44:45], off offset:512
	v_or_b32_e32 v34, 0x100, v34
	s_waitcnt vmcnt(1)
	v_pk_mul_f32 v[28:29], v[28:29], s[60:61] op_sel_hi:[1,0]
	s_waitcnt vmcnt(0)
	v_pk_mul_f32 v[32:33], v[32:33], s[60:61] op_sel_hi:[1,0]
	v_pk_mul_f32 v[30:31], v[30:31], s[60:61] op_sel_hi:[1,0]
	v_pk_mul_f32 v[26:27], v[26:27], s[60:61] op_sel_hi:[1,0]
	v_pk_fma_f32 v[24:25], v[24:25], v[144:145], v[32:33]
	v_pk_fma_f32 v[22:23], v[22:23], v[146:147], v[30:31]
	v_pk_fma_f32 v[28:29], v[20:21], v[140:141], v[28:29]
	v_pk_fma_f32 v[20:21], v[18:19], v[142:143], v[26:27]
	v_cvt_pk_bf16_f32 v18, v22, v23
	v_cvt_pk_bf16_f32 v19, v24, v25
	v_cvt_pk_bf16_f32 v20, v20, v21
	v_cvt_pk_bf16_f32 v21, v28, v29
	v_lshl_add_u64 v[22:23], s[50:51], 0, v[34:35]
	v_lshl_add_u64 v[26:27], v[156:157], 0, s[18:19]
	global_store_dwordx4 v[22:23], v[18:21], off sc0 sc1
	v_lshl_add_u64 v[28:29], v[26:27], 2, s[0:1]
	global_load_dwordx4 v[18:21], v[28:29], off offset:16
	global_load_dwordx4 v[22:25], v[28:29], off
	s_mov_b64 s[0:1], -1
	s_waitcnt vmcnt(1)
	v_pk_mul_f32 v[20:21], v[20:21], s[60:61] op_sel_hi:[1,0]
	s_waitcnt vmcnt(0)
	v_pk_mul_f32 v[24:25], v[24:25], s[60:61] op_sel_hi:[1,0]
	v_pk_mul_f32 v[22:23], v[22:23], s[60:61] op_sel_hi:[1,0]
	v_pk_mul_f32 v[18:19], v[18:19], s[60:61] op_sel_hi:[1,0]
	v_pk_fma_f32 v[16:17], v[16:17], v[152:153], v[24:25]
	v_pk_fma_f32 v[14:15], v[14:15], v[154:155], v[22:23]
	v_pk_fma_f32 v[20:21], v[12:13], v[148:149], v[20:21]
	v_pk_fma_f32 v[12:13], v[10:11], v[150:151], v[18:19]
	v_lshlrev_b64 v[18:19], 1, v[26:27]
	v_cvt_pk_bf16_f32 v10, v14, v15
	v_cvt_pk_bf16_f32 v11, v16, v17
	v_cvt_pk_bf16_f32 v12, v12, v13
	v_cvt_pk_bf16_f32 v13, v20, v21
	v_lshl_add_u64 v[14:15], s[50:51], 0, v[18:19]
	global_store_dwordx4 v[14:15], v[10:13], off sc0 sc1
	global_load_dwordx4 v[10:13], v[28:29], off offset:528
	s_nop 0
	global_load_dwordx4 v[14:17], v[28:29], off offset:512
	v_or_b32_e32 v18, 0x100, v18
	s_waitcnt vmcnt(1)
	v_pk_mul_f32 v[12:13], v[12:13], s[60:61] op_sel_hi:[1,0]
	s_waitcnt vmcnt(0)
	v_pk_mul_f32 v[16:17], v[16:17], s[60:61] op_sel_hi:[1,0]
	v_pk_mul_f32 v[14:15], v[14:15], s[60:61] op_sel_hi:[1,0]
	v_pk_mul_f32 v[10:11], v[10:11], s[60:61] op_sel_hi:[1,0]
	v_pk_fma_f32 v[8:9], v[8:9], v[144:145], v[16:17]
	v_pk_fma_f32 v[6:7], v[6:7], v[146:147], v[14:15]
	v_pk_fma_f32 v[12:13], v[4:5], v[140:141], v[12:13]
	v_pk_fma_f32 v[4:5], v[2:3], v[142:143], v[10:11]
	v_cvt_pk_bf16_f32 v2, v6, v7
	v_cvt_pk_bf16_f32 v3, v8, v9
	v_cvt_pk_bf16_f32 v4, v4, v5
	v_cvt_pk_bf16_f32 v5, v12, v13
	v_lshl_add_u64 v[6:7], s[50:51], 0, v[18:19]
	global_store_dwordx4 v[6:7], v[2:5], off sc0 sc1
	s_cbranch_vccnz .LBB0_838
	s_andn2_b64 vcc, exec, s[6:7]
	s_cbranch_vccnz .LBB0_837
	s_barrier
	s_branch .LBB0_837

.LBB0_962:
	v_lshl_add_u32 v146, s35, 8, v142
	v_lshl_or_b32 v140, s34, 8, v144
	v_ashrrev_i32_e32 v147, 31, v146
	v_ashrrev_i32_e32 v141, 31, v140
	v_lshlrev_b64 v[148:149], 14, v[146:147]
	v_max_f32_e32 v122, v122, v122
	v_max_f32_e32 v123, v123, v123
	v_lshl_add_u64 v[148:149], s[48:49], 0, v[148:149]
	v_lshlrev_b64 v[150:151], 1, v[140:141]
	v_max_f32_e32 v122, 0, v122
	v_max_f32_e32 v123, 0, v123
	v_lshl_add_u64 v[140:141], v[148:149], 0, v[150:151]
	v_pk_mul_f32 v[148:149], v[122:123], v[122:123]
	v_max_f32_e32 v123, v124, v124
	v_max_f32_e32 v126, v126, v126
	v_max_f32_e32 v127, v127, v127
	v_max_f32_e32 v122, v128, v128
	v_max_f32_e32 v124, 0, v123
	v_max_f32_e32 v123, v129, v129
	v_max_f32_e32 v125, v125, v125
	v_max_f32_e32 v126, 0, v126
	v_max_f32_e32 v127, 0, v127
	v_max_f32_e32 v122, 0, v122
	v_max_f32_e32 v123, 0, v123
	v_max_f32_e32 v125, 0, v125
	v_pk_mul_f32 v[126:127], v[126:127], v[126:127]
	v_pk_mul_f32 v[128:129], v[122:123], v[122:123]
	v_pk_mul_f32 v[152:153], v[124:125], v[124:125]
	v_max_f32_e32 v114, v114, v114
	v_max_f32_e32 v115, v115, v115
	v_cvt_pk_bf16_f32 v122, v126, v127
	v_cvt_pk_bf16_f32 v123, v128, v129
	v_cvt_pk_bf16_f32 v124, v148, v149
	v_cvt_pk_bf16_f32 v125, v152, v153
	v_max_f32_e32 v114, 0, v114
	v_max_f32_e32 v115, 0, v115
	global_store_dwordx4 v[140:141], v[122:125], off sc0 sc1
	v_max_f32_e32 v118, v118, v118
	v_max_f32_e32 v119, v119, v119
	v_pk_mul_f32 v[122:123], v[114:115], v[114:115]
	v_max_f32_e32 v115, v116, v116
	v_max_f32_e32 v114, v120, v120
	v_max_f32_e32 v116, 0, v115
	v_max_f32_e32 v115, v121, v121
	v_max_f32_e32 v117, v117, v117
	v_max_f32_e32 v118, 0, v118
	v_max_f32_e32 v119, 0, v119
	v_max_f32_e32 v114, 0, v114
	v_max_f32_e32 v115, 0, v115
	v_max_f32_e32 v117, 0, v117
	v_pk_mul_f32 v[118:119], v[118:119], v[118:119]
	v_pk_mul_f32 v[120:121], v[114:115], v[114:115]
	v_pk_mul_f32 v[124:125], v[116:117], v[116:117]
	v_max_f32_e32 v106, v106, v106
	v_max_f32_e32 v107, v107, v107
	v_cvt_pk_bf16_f32 v114, v118, v119
	v_cvt_pk_bf16_f32 v115, v120, v121
	v_cvt_pk_bf16_f32 v116, v122, v123
	v_cvt_pk_bf16_f32 v117, v124, v125
	v_max_f32_e32 v106, 0, v106
	v_max_f32_e32 v107, 0, v107
	global_store_dwordx4 v[140:141], v[114:117], off offset:256 sc0 sc1
	v_max_f32_e32 v110, v110, v110
	v_max_f32_e32 v111, v111, v111
	v_or_b32_e32 v114, 16, v146
	v_pk_mul_f32 v[116:117], v[106:107], v[106:107]
	v_max_f32_e32 v107, v108, v108
	v_ashrrev_i32_e32 v115, 31, v114
	v_max_f32_e32 v106, v112, v112
	v_max_f32_e32 v108, 0, v107
	v_max_f32_e32 v107, v113, v113
	v_max_f32_e32 v109, v109, v109
	v_lshlrev_b64 v[114:115], 14, v[114:115]
	v_max_f32_e32 v110, 0, v110
	v_max_f32_e32 v111, 0, v111
	v_max_f32_e32 v106, 0, v106
	v_max_f32_e32 v107, 0, v107
	v_max_f32_e32 v109, 0, v109
	v_lshl_add_u64 v[114:115], s[48:49], 0, v[114:115]
	v_pk_mul_f32 v[110:111], v[110:111], v[110:111]
	v_pk_mul_f32 v[112:113], v[106:107], v[106:107]
	v_pk_mul_f32 v[118:119], v[108:109], v[108:109]
	v_max_f32_e32 v98, v98, v98
	v_max_f32_e32 v99, v99, v99
	v_lshl_add_u64 v[114:115], v[114:115], 0, v[150:151]
	v_cvt_pk_bf16_f32 v106, v110, v111
	v_cvt_pk_bf16_f32 v107, v112, v113
	v_cvt_pk_bf16_f32 v108, v116, v117
	v_cvt_pk_bf16_f32 v109, v118, v119
	v_max_f32_e32 v98, 0, v98
	v_max_f32_e32 v99, 0, v99
	global_store_dwordx4 v[114:115], v[106:109], off sc0 sc1
	v_max_f32_e32 v102, v102, v102
	v_max_f32_e32 v103, v103, v103
	v_pk_mul_f32 v[106:107], v[98:99], v[98:99]
	v_max_f32_e32 v99, v100, v100
	v_max_f32_e32 v98, v104, v104
	v_max_f32_e32 v100, 0, v99
	v_max_f32_e32 v99, v105, v105
	v_max_f32_e32 v101, v101, v101
	v_max_f32_e32 v102, 0, v102
	v_max_f32_e32 v103, 0, v103
	v_max_f32_e32 v98, 0, v98
	v_max_f32_e32 v99, 0, v99
	v_max_f32_e32 v101, 0, v101
	v_pk_mul_f32 v[102:103], v[102:103], v[102:103]
	v_pk_mul_f32 v[104:105], v[98:99], v[98:99]
	v_pk_mul_f32 v[108:109], v[100:101], v[100:101]
	v_max_f32_e32 v90, v90, v90
	v_max_f32_e32 v91, v91, v91
	v_cvt_pk_bf16_f32 v98, v102, v103
	v_cvt_pk_bf16_f32 v99, v104, v105
	v_cvt_pk_bf16_f32 v100, v106, v107
	v_cvt_pk_bf16_f32 v101, v108, v109
	v_max_f32_e32 v90, 0, v90
	v_max_f32_e32 v91, 0, v91
	global_store_dwordx4 v[114:115], v[98:101], off offset:256 sc0 sc1
	v_max_f32_e32 v94, v94, v94
	v_max_f32_e32 v95, v95, v95
	v_or_b32_e32 v98, 32, v146
	v_pk_mul_f32 v[100:101], v[90:91], v[90:91]
	v_max_f32_e32 v91, v92, v92
	v_ashrrev_i32_e32 v99, 31, v98
	v_max_f32_e32 v90, v96, v96
	v_max_f32_e32 v92, 0, v91
	v_max_f32_e32 v91, v97, v97
	v_max_f32_e32 v93, v93, v93
	v_lshlrev_b64 v[98:99], 14, v[98:99]
	v_max_f32_e32 v94, 0, v94
	v_max_f32_e32 v95, 0, v95
	v_max_f32_e32 v90, 0, v90
	v_max_f32_e32 v91, 0, v91
	v_max_f32_e32 v93, 0, v93
	v_lshl_add_u64 v[98:99], s[48:49], 0, v[98:99]
	v_pk_mul_f32 v[94:95], v[94:95], v[94:95]
	v_pk_mul_f32 v[96:97], v[90:91], v[90:91]
	v_pk_mul_f32 v[102:103], v[92:93], v[92:93]
	v_max_f32_e32 v82, v82, v82
	v_max_f32_e32 v83, v83, v83
	v_lshl_add_u64 v[98:99], v[98:99], 0, v[150:151]
	v_cvt_pk_bf16_f32 v90, v94, v95
	v_cvt_pk_bf16_f32 v91, v96, v97
	v_cvt_pk_bf16_f32 v92, v100, v101
	v_cvt_pk_bf16_f32 v93, v102, v103
	v_max_f32_e32 v82, 0, v82
	v_max_f32_e32 v83, 0, v83
	global_store_dwordx4 v[98:99], v[90:93], off sc0 sc1
	v_max_f32_e32 v86, v86, v86
	v_max_f32_e32 v87, v87, v87
	v_pk_mul_f32 v[90:91], v[82:83], v[82:83]
	v_max_f32_e32 v83, v84, v84
	v_max_f32_e32 v82, v88, v88
	v_max_f32_e32 v84, 0, v83
	v_max_f32_e32 v83, v89, v89
	v_max_f32_e32 v85, v85, v85
	v_max_f32_e32 v86, 0, v86
	v_max_f32_e32 v87, 0, v87
	v_max_f32_e32 v82, 0, v82
	v_max_f32_e32 v83, 0, v83
	v_max_f32_e32 v85, 0, v85
	v_pk_mul_f32 v[86:87], v[86:87], v[86:87]
	v_pk_mul_f32 v[88:89], v[82:83], v[82:83]
	v_pk_mul_f32 v[92:93], v[84:85], v[84:85]
	v_max_f32_e32 v74, v74, v74
	v_max_f32_e32 v75, v75, v75
	v_cvt_pk_bf16_f32 v82, v86, v87
	v_cvt_pk_bf16_f32 v83, v88, v89
	v_cvt_pk_bf16_f32 v84, v90, v91
	v_cvt_pk_bf16_f32 v85, v92, v93
	v_max_f32_e32 v74, 0, v74
	v_max_f32_e32 v75, 0, v75
	global_store_dwordx4 v[98:99], v[82:85], off offset:256 sc0 sc1
	v_max_f32_e32 v78, v78, v78
	v_max_f32_e32 v79, v79, v79
	v_or_b32_e32 v82, 48, v146
	v_pk_mul_f32 v[84:85], v[74:75], v[74:75]
	v_max_f32_e32 v75, v76, v76
	v_ashrrev_i32_e32 v83, 31, v82
	v_max_f32_e32 v74, v80, v80
	v_max_f32_e32 v76, 0, v75
	v_max_f32_e32 v75, v81, v81
	v_max_f32_e32 v77, v77, v77
	v_lshlrev_b64 v[82:83], 14, v[82:83]
	v_max_f32_e32 v78, 0, v78
	v_max_f32_e32 v79, 0, v79
	v_max_f32_e32 v74, 0, v74
	v_max_f32_e32 v75, 0, v75
	v_max_f32_e32 v77, 0, v77
	v_lshl_add_u64 v[82:83], s[48:49], 0, v[82:83]
	v_pk_mul_f32 v[78:79], v[78:79], v[78:79]
	v_pk_mul_f32 v[80:81], v[74:75], v[74:75]
	v_pk_mul_f32 v[86:87], v[76:77], v[76:77]
	v_max_f32_e32 v66, v66, v66
	v_max_f32_e32 v67, v67, v67
	v_lshl_add_u64 v[82:83], v[82:83], 0, v[150:151]
	v_cvt_pk_bf16_f32 v74, v78, v79
	v_cvt_pk_bf16_f32 v75, v80, v81
	v_cvt_pk_bf16_f32 v76, v84, v85
	v_cvt_pk_bf16_f32 v77, v86, v87
	v_max_f32_e32 v66, 0, v66
	v_max_f32_e32 v67, 0, v67
	global_store_dwordx4 v[82:83], v[74:77], off sc0 sc1
	v_max_f32_e32 v70, v70, v70
	v_max_f32_e32 v71, v71, v71
	v_pk_mul_f32 v[74:75], v[66:67], v[66:67]
	v_max_f32_e32 v67, v68, v68
	v_max_f32_e32 v66, v72, v72
	v_max_f32_e32 v68, 0, v67
	v_max_f32_e32 v67, v73, v73
	v_max_f32_e32 v69, v69, v69
	v_max_f32_e32 v70, 0, v70
	v_max_f32_e32 v71, 0, v71
	v_max_f32_e32 v66, 0, v66
	v_max_f32_e32 v67, 0, v67
	v_max_f32_e32 v69, 0, v69
	v_pk_mul_f32 v[70:71], v[70:71], v[70:71]
	v_pk_mul_f32 v[72:73], v[66:67], v[66:67]
	v_pk_mul_f32 v[76:77], v[68:69], v[68:69]
	v_max_f32_e32 v58, v58, v58
	v_max_f32_e32 v59, v59, v59
	v_cvt_pk_bf16_f32 v66, v70, v71
	v_cvt_pk_bf16_f32 v67, v72, v73
	v_cvt_pk_bf16_f32 v68, v74, v75
	v_cvt_pk_bf16_f32 v69, v76, v77
	v_max_f32_e32 v58, 0, v58
	v_max_f32_e32 v59, 0, v59
	global_store_dwordx4 v[82:83], v[66:69], off offset:256 sc0 sc1
	v_max_f32_e32 v62, v62, v62
	v_max_f32_e32 v63, v63, v63
	v_pk_mul_f32 v[68:69], v[58:59], v[58:59]
	v_max_f32_e32 v59, v60, v60
	v_max_f32_e32 v62, 0, v62
	v_max_f32_e32 v63, 0, v63
	v_max_f32_e32 v58, v64, v64
	v_max_f32_e32 v60, 0, v59
	v_max_f32_e32 v59, v65, v65
	v_max_f32_e32 v61, v61, v61
	v_pk_mul_f32 v[62:63], v[62:63], v[62:63]
	v_max_f32_e32 v58, 0, v58
	v_max_f32_e32 v59, 0, v59
	v_max_f32_e32 v61, 0, v61
	s_mov_b32 s3, 0x200000
	v_pk_mul_f32 v[64:65], v[58:59], v[58:59]
	v_pk_mul_f32 v[70:71], v[60:61], v[60:61]
	v_cvt_pk_bf16_f32 v58, v62, v63
	v_add_co_u32_e32 v62, vcc, s3, v140
	v_max_f32_e32 v50, v50, v50
	v_max_f32_e32 v51, v51, v51
	v_cvt_pk_bf16_f32 v59, v64, v65
	v_cvt_pk_bf16_f32 v60, v68, v69
	v_cvt_pk_bf16_f32 v61, v70, v71
	v_addc_co_u32_e32 v63, vcc, 0, v141, vcc
	v_max_f32_e32 v50, 0, v50
	v_max_f32_e32 v51, 0, v51
	global_store_dwordx4 v[62:63], v[58:61], off sc0 sc1
	v_max_f32_e32 v54, v54, v54
	v_max_f32_e32 v55, v55, v55
	v_pk_mul_f32 v[58:59], v[50:51], v[50:51]
	v_max_f32_e32 v51, v52, v52
	v_max_f32_e32 v50, v56, v56
	v_max_f32_e32 v52, 0, v51
	v_max_f32_e32 v51, v57, v57
	v_max_f32_e32 v53, v53, v53
	v_max_f32_e32 v54, 0, v54
	v_max_f32_e32 v55, 0, v55
	v_max_f32_e32 v50, 0, v50
	v_max_f32_e32 v51, 0, v51
	v_max_f32_e32 v53, 0, v53
	s_mov_b64 s[16:17], 0x200000
	v_pk_mul_f32 v[54:55], v[54:55], v[54:55]
	v_pk_mul_f32 v[56:57], v[50:51], v[50:51]
	v_pk_mul_f32 v[60:61], v[52:53], v[52:53]
	v_max_f32_e32 v42, v42, v42
	v_max_f32_e32 v43, v43, v43
	v_lshl_add_u64 v[66:67], v[140:141], 0, s[16:17]
	v_cvt_pk_bf16_f32 v50, v54, v55
	v_cvt_pk_bf16_f32 v51, v56, v57
	v_cvt_pk_bf16_f32 v52, v58, v59
	v_cvt_pk_bf16_f32 v53, v60, v61
	v_max_f32_e32 v42, 0, v42
	v_max_f32_e32 v43, 0, v43
	global_store_dwordx4 v[66:67], v[50:53], off offset:256 sc0 sc1
	v_max_f32_e32 v46, v46, v46
	v_max_f32_e32 v47, v47, v47
	v_pk_mul_f32 v[52:53], v[42:43], v[42:43]
	v_max_f32_e32 v43, v44, v44
	v_max_f32_e32 v46, 0, v46
	v_max_f32_e32 v47, 0, v47
	v_max_f32_e32 v42, v48, v48
	v_max_f32_e32 v44, 0, v43
	v_max_f32_e32 v43, v49, v49
	v_max_f32_e32 v45, v45, v45
	v_pk_mul_f32 v[46:47], v[46:47], v[46:47]
	v_max_f32_e32 v42, 0, v42
	v_max_f32_e32 v43, 0, v43
	v_max_f32_e32 v45, 0, v45
	s_mov_b32 s3, 0x240000
	v_pk_mul_f32 v[48:49], v[42:43], v[42:43]
	v_pk_mul_f32 v[54:55], v[44:45], v[44:45]
	v_cvt_pk_bf16_f32 v42, v46, v47
	v_add_co_u32_e32 v46, vcc, s3, v140
	v_max_f32_e32 v34, v34, v34
	v_max_f32_e32 v35, v35, v35
	v_cvt_pk_bf16_f32 v43, v48, v49
	v_cvt_pk_bf16_f32 v44, v52, v53
	v_cvt_pk_bf16_f32 v45, v54, v55
	v_addc_co_u32_e32 v47, vcc, 0, v141, vcc
	v_max_f32_e32 v34, 0, v34
	v_max_f32_e32 v35, 0, v35
	global_store_dwordx4 v[46:47], v[42:45], off sc0 sc1
	v_max_f32_e32 v38, v38, v38
	v_max_f32_e32 v39, v39, v39
	v_pk_mul_f32 v[42:43], v[34:35], v[34:35]
	v_max_f32_e32 v35, v36, v36
	v_max_f32_e32 v34, v40, v40
	v_max_f32_e32 v36, 0, v35
	v_max_f32_e32 v35, v41, v41
	v_max_f32_e32 v37, v37, v37
	v_max_f32_e32 v38, 0, v38
	v_max_f32_e32 v39, 0, v39
	v_max_f32_e32 v34, 0, v34
	v_max_f32_e32 v35, 0, v35
	v_max_f32_e32 v37, 0, v37
	s_mov_b64 s[16:17], 0x240000
	v_pk_mul_f32 v[38:39], v[38:39], v[38:39]
	v_pk_mul_f32 v[40:41], v[34:35], v[34:35]
	v_pk_mul_f32 v[44:45], v[36:37], v[36:37]
	v_max_f32_e32 v26, v26, v26
	v_max_f32_e32 v27, v27, v27
	v_lshl_add_u64 v[50:51], v[140:141], 0, s[16:17]
	v_cvt_pk_bf16_f32 v34, v38, v39
	v_cvt_pk_bf16_f32 v35, v40, v41
	v_cvt_pk_bf16_f32 v36, v42, v43
	v_cvt_pk_bf16_f32 v37, v44, v45
	v_max_f32_e32 v26, 0, v26
	v_max_f32_e32 v27, 0, v27
	global_store_dwordx4 v[50:51], v[34:37], off offset:256 sc0 sc1
	v_max_f32_e32 v30, v30, v30
	v_max_f32_e32 v31, v31, v31
	v_pk_mul_f32 v[36:37], v[26:27], v[26:27]
	v_max_f32_e32 v27, v28, v28
	v_max_f32_e32 v30, 0, v30
	v_max_f32_e32 v31, 0, v31
	v_max_f32_e32 v26, v32, v32
	v_max_f32_e32 v28, 0, v27
	v_max_f32_e32 v27, v33, v33
	v_max_f32_e32 v29, v29, v29
	v_pk_mul_f32 v[30:31], v[30:31], v[30:31]
	v_max_f32_e32 v26, 0, v26
	v_max_f32_e32 v27, 0, v27
	v_max_f32_e32 v29, 0, v29
	s_mov_b32 s3, 0x280000
	v_pk_mul_f32 v[32:33], v[26:27], v[26:27]
	v_pk_mul_f32 v[38:39], v[28:29], v[28:29]
	v_cvt_pk_bf16_f32 v26, v30, v31
	v_add_co_u32_e32 v30, vcc, s3, v140
	v_max_f32_e32 v18, v18, v18
	v_max_f32_e32 v19, v19, v19
	v_cvt_pk_bf16_f32 v27, v32, v33
	v_cvt_pk_bf16_f32 v28, v36, v37
	v_cvt_pk_bf16_f32 v29, v38, v39
	v_addc_co_u32_e32 v31, vcc, 0, v141, vcc
	v_max_f32_e32 v18, 0, v18
	v_max_f32_e32 v19, 0, v19
	global_store_dwordx4 v[30:31], v[26:29], off sc0 sc1
	v_max_f32_e32 v22, v22, v22
	v_max_f32_e32 v23, v23, v23
	v_pk_mul_f32 v[26:27], v[18:19], v[18:19]
	v_max_f32_e32 v19, v20, v20
	v_max_f32_e32 v18, v24, v24
	v_max_f32_e32 v20, 0, v19
	v_max_f32_e32 v19, v25, v25
	v_max_f32_e32 v21, v21, v21
	v_max_f32_e32 v22, 0, v22
	v_max_f32_e32 v23, 0, v23
	v_max_f32_e32 v18, 0, v18
	v_max_f32_e32 v19, 0, v19
	v_max_f32_e32 v21, 0, v21
	s_mov_b64 s[16:17], 0x280000
	v_pk_mul_f32 v[22:23], v[22:23], v[22:23]
	v_pk_mul_f32 v[24:25], v[18:19], v[18:19]
	v_pk_mul_f32 v[28:29], v[20:21], v[20:21]
	v_max_f32_e32 v10, v10, v10
	v_max_f32_e32 v11, v11, v11
	v_lshl_add_u64 v[34:35], v[140:141], 0, s[16:17]
	v_cvt_pk_bf16_f32 v18, v22, v23
	v_cvt_pk_bf16_f32 v19, v24, v25
	v_cvt_pk_bf16_f32 v20, v26, v27
	v_cvt_pk_bf16_f32 v21, v28, v29
	v_max_f32_e32 v10, 0, v10
	v_max_f32_e32 v11, 0, v11
	global_store_dwordx4 v[34:35], v[18:21], off offset:256 sc0 sc1
	v_max_f32_e32 v14, v14, v14
	v_max_f32_e32 v15, v15, v15
	v_pk_mul_f32 v[20:21], v[10:11], v[10:11]
	v_max_f32_e32 v11, v12, v12
	v_max_f32_e32 v14, 0, v14
	v_max_f32_e32 v15, 0, v15
	v_max_f32_e32 v10, v16, v16
	v_max_f32_e32 v12, 0, v11
	v_max_f32_e32 v11, v17, v17
	v_max_f32_e32 v13, v13, v13
	v_pk_mul_f32 v[14:15], v[14:15], v[14:15]
	v_max_f32_e32 v10, 0, v10
	v_max_f32_e32 v11, 0, v11
	v_max_f32_e32 v13, 0, v13
	s_mov_b32 s3, 0x2c0000
	v_pk_mul_f32 v[16:17], v[10:11], v[10:11]
	v_pk_mul_f32 v[22:23], v[12:13], v[12:13]
	v_cvt_pk_bf16_f32 v10, v14, v15
	v_add_co_u32_e32 v14, vcc, s3, v140
	v_max_f32_e32 v2, v2, v2
	v_max_f32_e32 v3, v3, v3
	v_cvt_pk_bf16_f32 v11, v16, v17
	v_cvt_pk_bf16_f32 v12, v20, v21
	v_cvt_pk_bf16_f32 v13, v22, v23
	v_addc_co_u32_e32 v15, vcc, 0, v141, vcc
	v_max_f32_e32 v2, 0, v2
	v_max_f32_e32 v3, 0, v3
	global_store_dwordx4 v[14:15], v[10:13], off sc0 sc1
	v_max_f32_e32 v6, v6, v6
	v_max_f32_e32 v7, v7, v7
	v_pk_mul_f32 v[10:11], v[2:3], v[2:3]
	v_max_f32_e32 v3, v4, v4
	v_max_f32_e32 v2, v8, v8
	v_max_f32_e32 v4, 0, v3
	v_max_f32_e32 v3, v9, v9
	v_max_f32_e32 v5, v5, v5
	v_max_f32_e32 v6, 0, v6
	v_max_f32_e32 v7, 0, v7
	v_max_f32_e32 v2, 0, v2
	v_max_f32_e32 v3, 0, v3
	v_max_f32_e32 v5, 0, v5
	s_mov_b64 s[16:17], 0x2c0000
	v_pk_mul_f32 v[6:7], v[6:7], v[6:7]
	v_pk_mul_f32 v[8:9], v[2:3], v[2:3]
	v_pk_mul_f32 v[12:13], v[4:5], v[4:5]
	v_lshl_add_u64 v[18:19], v[140:141], 0, s[16:17]
	v_cvt_pk_bf16_f32 v2, v6, v7
	v_cvt_pk_bf16_f32 v3, v8, v9
	v_cvt_pk_bf16_f32 v4, v10, v11
	v_cvt_pk_bf16_f32 v5, v12, v13
	s_andn2_b64 vcc, exec, s[0:1]
	s_mov_b64 s[0:1], -1
	s_mov_b32 s42, 0xc000
	global_store_dwordx4 v[18:19], v[2:5], off offset:256 sc0 sc1
	s_cbranch_vccnz .LBB0_951
	s_andn2_b64 vcc, exec, s[4:5]
	s_cbranch_vccnz .LBB0_950
	s_barrier
	s_branch .LBB0_950

.LBB0_1027:
	v_lshl_or_b32 v158, s44, 8, v164
	v_ashrrev_i32_e32 v159, 31, v158
	v_lshl_add_u64 v[156:157], v[158:159], 2, s[6:7]
	global_load_dwordx4 v[140:143], v[156:157], off offset:16
	global_load_dwordx4 v[144:147], v[156:157], off
	v_lshl_add_u32 v160, s41, 8, v162
	v_ashrrev_i32_e32 v161, 31, v160
	s_mov_b64 s[20:21], 0x40000
	s_andn2_b64 vcc, exec, s[4:5]
	s_mov_b32 s42, 0xc000
	s_waitcnt vmcnt(0)
	v_pk_add_f32 v[148:149], v[142:143], 1.0 op_sel_hi:[1,0]
	v_pk_add_f32 v[150:151], v[140:141], 1.0 op_sel_hi:[1,0]
	global_load_dwordx4 v[166:169], v[156:157], off offset:528
	global_load_dwordx4 v[140:143], v[156:157], off offset:512
	v_lshlrev_b64 v[156:157], 11, v[160:161]
	v_lshl_add_u64 v[156:157], v[156:157], 0, v[158:159]
	v_lshlrev_b64 v[170:171], 1, v[156:157]
	v_pk_add_f32 v[154:155], v[144:145], 1.0 op_sel_hi:[1,0]
	v_pk_add_f32 v[152:153], v[146:147], 1.0 op_sel_hi:[1,0]
	s_waitcnt vmcnt(0)
	v_pk_add_f32 v[144:145], v[142:143], 1.0 op_sel_hi:[1,0]
	v_pk_add_f32 v[142:143], v[166:167], 1.0 op_sel_hi:[1,0]
	v_lshl_add_u64 v[166:167], s[50:51], 0, v[170:171]
	v_pk_add_f32 v[146:147], v[140:141], 1.0 op_sel_hi:[1,0]
	v_pk_add_f32 v[140:141], v[168:169], 1.0 op_sel_hi:[1,0]
	global_load_dwordx4 v[166:169], v[166:167], off
	v_or_b32_e32 v170, 0x100, v170
	s_waitcnt vmcnt(0)
	v_lshlrev_b32_e32 v172, 16, v166
	v_and_b32_e32 v173, 0xffff0000, v166
	v_lshlrev_b32_e32 v166, 16, v167
	v_and_b32_e32 v167, 0xffff0000, v167
	v_lshlrev_b32_e32 v174, 16, v168
	v_and_b32_e32 v175, 0xffff0000, v168
	v_pk_mul_f32 v[166:167], v[166:167], s[60:61] op_sel_hi:[1,0]
	v_lshlrev_b32_e32 v168, 16, v169
	v_and_b32_e32 v169, 0xffff0000, v169
	v_pk_mul_f32 v[172:173], v[172:173], s[60:61] op_sel_hi:[1,0]
	v_pk_fma_f32 v[128:129], v[128:129], v[152:153], v[166:167]
	v_pk_mul_f32 v[166:167], v[174:175], s[60:61] op_sel_hi:[1,0]
	v_pk_fma_f32 v[126:127], v[126:127], v[154:155], v[172:173]
	v_pk_mul_f32 v[168:169], v[168:169], s[60:61] op_sel_hi:[1,0]
	v_pk_fma_f32 v[122:123], v[122:123], v[150:151], v[166:167]
	v_lshl_add_u64 v[166:167], v[156:157], 2, s[36:37]
	v_pk_fma_f32 v[124:125], v[124:125], v[148:149], v[168:169]
	global_store_dwordx4 v[166:167], v[126:129], off sc0 sc1
	global_store_dwordx4 v[166:167], v[122:125], off offset:16 sc0 sc1
	s_nop 1
	v_lshl_add_u64 v[122:123], s[50:51], 0, v[170:171]
	global_load_dwordx4 v[122:125], v[122:123], off
	s_waitcnt vmcnt(0)
	v_lshlrev_b32_e32 v126, 16, v122
	v_and_b32_e32 v127, 0xffff0000, v122
	v_lshlrev_b32_e32 v122, 16, v123
	v_and_b32_e32 v123, 0xffff0000, v123
	v_lshlrev_b32_e32 v128, 16, v124
	v_and_b32_e32 v129, 0xffff0000, v124
	v_pk_mul_f32 v[122:123], v[122:123], s[60:61] op_sel_hi:[1,0]
	v_lshlrev_b32_e32 v124, 16, v125
	v_and_b32_e32 v125, 0xffff0000, v125
	v_pk_mul_f32 v[126:127], v[126:127], s[60:61] op_sel_hi:[1,0]
	v_pk_fma_f32 v[120:121], v[120:121], v[144:145], v[122:123]
	v_pk_mul_f32 v[122:123], v[128:129], s[60:61] op_sel_hi:[1,0]
	v_pk_fma_f32 v[118:119], v[118:119], v[146:147], v[126:127]
	v_pk_mul_f32 v[124:125], v[124:125], s[60:61] op_sel_hi:[1,0]
	v_pk_fma_f32 v[114:115], v[114:115], v[142:143], v[122:123]
	v_pk_fma_f32 v[116:117], v[116:117], v[140:141], v[124:125]
	global_store_dwordx4 v[166:167], v[118:121], off offset:512 sc0 sc1
	global_store_dwordx4 v[166:167], v[114:117], off offset:528 sc0 sc1
	s_nop 1
	v_or_b32_e32 v114, 16, v160
	v_ashrrev_i32_e32 v115, 31, v114
	v_lshlrev_b64 v[114:115], 11, v[114:115]
	v_lshl_add_u64 v[118:119], v[114:115], 0, v[158:159]
	v_lshlrev_b64 v[120:121], 1, v[118:119]
	v_lshl_add_u64 v[114:115], s[50:51], 0, v[120:121]
	global_load_dwordx4 v[114:117], v[114:115], off
	v_or_b32_e32 v120, 0x100, v120
	s_waitcnt vmcnt(0)
	v_lshlrev_b32_e32 v122, 16, v114
	v_and_b32_e32 v123, 0xffff0000, v114
	v_lshlrev_b32_e32 v114, 16, v115
	v_and_b32_e32 v115, 0xffff0000, v115
	v_lshlrev_b32_e32 v124, 16, v116
	v_and_b32_e32 v125, 0xffff0000, v116
	v_pk_mul_f32 v[114:115], v[114:115], s[60:61] op_sel_hi:[1,0]
	v_lshlrev_b32_e32 v116, 16, v117
	v_and_b32_e32 v117, 0xffff0000, v117
	v_pk_mul_f32 v[122:123], v[122:123], s[60:61] op_sel_hi:[1,0]
	v_pk_fma_f32 v[112:113], v[112:113], v[152:153], v[114:115]
	v_pk_mul_f32 v[114:115], v[124:125], s[60:61] op_sel_hi:[1,0]
	v_pk_fma_f32 v[110:111], v[110:111], v[154:155], v[122:123]
	v_pk_mul_f32 v[116:117], v[116:117], s[60:61] op_sel_hi:[1,0]
	v_pk_fma_f32 v[106:107], v[106:107], v[150:151], v[114:115]
	v_lshl_add_u64 v[114:115], v[118:119], 2, s[36:37]
	v_pk_fma_f32 v[108:109], v[108:109], v[148:149], v[116:117]
	global_store_dwordx4 v[114:115], v[110:113], off sc0 sc1
	global_store_dwordx4 v[114:115], v[106:109], off offset:16 sc0 sc1
	s_nop 1
	v_lshl_add_u64 v[106:107], s[50:51], 0, v[120:121]
	global_load_dwordx4 v[106:109], v[106:107], off
	s_waitcnt vmcnt(0)
	v_lshlrev_b32_e32 v110, 16, v106
	v_and_b32_e32 v111, 0xffff0000, v106
	v_lshlrev_b32_e32 v106, 16, v107
	v_and_b32_e32 v107, 0xffff0000, v107
	v_lshlrev_b32_e32 v112, 16, v108
	v_and_b32_e32 v113, 0xffff0000, v108
	v_pk_mul_f32 v[106:107], v[106:107], s[60:61] op_sel_hi:[1,0]
	v_lshlrev_b32_e32 v108, 16, v109
	v_and_b32_e32 v109, 0xffff0000, v109
	v_pk_mul_f32 v[110:111], v[110:111], s[60:61] op_sel_hi:[1,0]
	v_pk_fma_f32 v[104:105], v[104:105], v[144:145], v[106:107]
	v_pk_mul_f32 v[106:107], v[112:113], s[60:61] op_sel_hi:[1,0]
	v_pk_fma_f32 v[102:103], v[102:103], v[146:147], v[110:111]
	v_pk_mul_f32 v[108:109], v[108:109], s[60:61] op_sel_hi:[1,0]
	v_pk_fma_f32 v[98:99], v[98:99], v[142:143], v[106:107]
	v_pk_fma_f32 v[100:101], v[100:101], v[140:141], v[108:109]
	global_store_dwordx4 v[114:115], v[102:105], off offset:512 sc0 sc1
	global_store_dwordx4 v[114:115], v[98:101], off offset:528 sc0 sc1
	s_nop 1
	v_or_b32_e32 v98, 32, v160
	v_ashrrev_i32_e32 v99, 31, v98
	v_lshlrev_b64 v[98:99], 11, v[98:99]
	v_lshl_add_u64 v[102:103], v[98:99], 0, v[158:159]
	v_lshlrev_b64 v[104:105], 1, v[102:103]
	v_lshl_add_u64 v[98:99], s[50:51], 0, v[104:105]
	global_load_dwordx4 v[98:101], v[98:99], off
	v_or_b32_e32 v104, 0x100, v104
	s_waitcnt vmcnt(0)
	v_lshlrev_b32_e32 v106, 16, v98
	v_and_b32_e32 v107, 0xffff0000, v98
	v_lshlrev_b32_e32 v98, 16, v99
	v_and_b32_e32 v99, 0xffff0000, v99
	v_lshlrev_b32_e32 v108, 16, v100
	v_and_b32_e32 v109, 0xffff0000, v100
	v_pk_mul_f32 v[98:99], v[98:99], s[60:61] op_sel_hi:[1,0]
	v_lshlrev_b32_e32 v100, 16, v101
	v_and_b32_e32 v101, 0xffff0000, v101
	v_pk_mul_f32 v[106:107], v[106:107], s[60:61] op_sel_hi:[1,0]
	v_pk_fma_f32 v[96:97], v[96:97], v[152:153], v[98:99]
	v_pk_mul_f32 v[98:99], v[108:109], s[60:61] op_sel_hi:[1,0]
	v_pk_fma_f32 v[94:95], v[94:95], v[154:155], v[106:107]
	v_pk_mul_f32 v[100:101], v[100:101], s[60:61] op_sel_hi:[1,0]
	v_pk_fma_f32 v[90:91], v[90:91], v[150:151], v[98:99]
	v_lshl_add_u64 v[98:99], v[102:103], 2, s[36:37]
	v_pk_fma_f32 v[92:93], v[92:93], v[148:149], v[100:101]
	global_store_dwordx4 v[98:99], v[94:97], off sc0 sc1
	global_store_dwordx4 v[98:99], v[90:93], off offset:16 sc0 sc1
	s_nop 1
	v_lshl_add_u64 v[90:91], s[50:51], 0, v[104:105]
	global_load_dwordx4 v[90:93], v[90:91], off
	s_waitcnt vmcnt(0)
	v_lshlrev_b32_e32 v94, 16, v90
	v_and_b32_e32 v95, 0xffff0000, v90
	v_lshlrev_b32_e32 v90, 16, v91
	v_and_b32_e32 v91, 0xffff0000, v91
	v_lshlrev_b32_e32 v96, 16, v92
	v_and_b32_e32 v97, 0xffff0000, v92
	v_pk_mul_f32 v[90:91], v[90:91], s[60:61] op_sel_hi:[1,0]
	v_lshlrev_b32_e32 v92, 16, v93
	v_and_b32_e32 v93, 0xffff0000, v93
	v_pk_mul_f32 v[94:95], v[94:95], s[60:61] op_sel_hi:[1,0]
	v_pk_fma_f32 v[88:89], v[88:89], v[144:145], v[90:91]
	v_pk_mul_f32 v[90:91], v[96:97], s[60:61] op_sel_hi:[1,0]
	v_pk_fma_f32 v[86:87], v[86:87], v[146:147], v[94:95]
	v_pk_mul_f32 v[92:93], v[92:93], s[60:61] op_sel_hi:[1,0]
	v_pk_fma_f32 v[82:83], v[82:83], v[142:143], v[90:91]
	v_pk_fma_f32 v[84:85], v[84:85], v[140:141], v[92:93]
	global_store_dwordx4 v[98:99], v[86:89], off offset:512 sc0 sc1
	global_store_dwordx4 v[98:99], v[82:85], off offset:528 sc0 sc1
	s_nop 1
	v_or_b32_e32 v82, 48, v160
	v_ashrrev_i32_e32 v83, 31, v82
	v_lshlrev_b64 v[82:83], 11, v[82:83]
	v_lshl_add_u64 v[86:87], v[82:83], 0, v[158:159]
	v_lshlrev_b64 v[88:89], 1, v[86:87]
	v_lshl_add_u64 v[82:83], s[50:51], 0, v[88:89]
	global_load_dwordx4 v[82:85], v[82:83], off
	v_or_b32_e32 v88, 0x100, v88
	s_waitcnt vmcnt(0)
	v_lshlrev_b32_e32 v90, 16, v82
	v_and_b32_e32 v91, 0xffff0000, v82
	v_lshlrev_b32_e32 v82, 16, v83
	v_and_b32_e32 v83, 0xffff0000, v83
	v_lshlrev_b32_e32 v92, 16, v84
	v_and_b32_e32 v93, 0xffff0000, v84
	v_pk_mul_f32 v[82:83], v[82:83], s[60:61] op_sel_hi:[1,0]
	v_lshlrev_b32_e32 v84, 16, v85
	v_and_b32_e32 v85, 0xffff0000, v85
	v_pk_mul_f32 v[90:91], v[90:91], s[60:61] op_sel_hi:[1,0]
	v_pk_fma_f32 v[80:81], v[80:81], v[152:153], v[82:83]
	v_pk_mul_f32 v[82:83], v[92:93], s[60:61] op_sel_hi:[1,0]
	v_pk_fma_f32 v[78:79], v[78:79], v[154:155], v[90:91]
	v_pk_mul_f32 v[84:85], v[84:85], s[60:61] op_sel_hi:[1,0]
	v_pk_fma_f32 v[74:75], v[74:75], v[150:151], v[82:83]
	v_lshl_add_u64 v[82:83], v[86:87], 2, s[36:37]
	v_pk_fma_f32 v[76:77], v[76:77], v[148:149], v[84:85]
	global_store_dwordx4 v[82:83], v[78:81], off sc0 sc1
	global_store_dwordx4 v[82:83], v[74:77], off offset:16 sc0 sc1
	s_nop 1
	v_lshl_add_u64 v[74:75], s[50:51], 0, v[88:89]
	global_load_dwordx4 v[74:77], v[74:75], off
	s_waitcnt vmcnt(0)
	v_lshlrev_b32_e32 v78, 16, v74
	v_and_b32_e32 v79, 0xffff0000, v74
	v_lshlrev_b32_e32 v74, 16, v75
	v_and_b32_e32 v75, 0xffff0000, v75
	v_lshlrev_b32_e32 v80, 16, v76
	v_and_b32_e32 v81, 0xffff0000, v76
	v_lshlrev_b32_e32 v76, 16, v77
	v_and_b32_e32 v77, 0xffff0000, v77
	v_pk_mul_f32 v[78:79], v[78:79], s[60:61] op_sel_hi:[1,0]
	v_pk_mul_f32 v[74:75], v[74:75], s[60:61] op_sel_hi:[1,0]
	v_pk_fma_f32 v[70:71], v[70:71], v[146:147], v[78:79]
	v_pk_fma_f32 v[72:73], v[72:73], v[144:145], v[74:75]
	v_pk_mul_f32 v[74:75], v[80:81], s[60:61] op_sel_hi:[1,0]
	v_pk_mul_f32 v[76:77], v[76:77], s[60:61] op_sel_hi:[1,0]
	v_pk_fma_f32 v[66:67], v[66:67], v[142:143], v[74:75]
	v_pk_fma_f32 v[68:69], v[68:69], v[140:141], v[76:77]
	global_store_dwordx4 v[82:83], v[70:73], off offset:512 sc0 sc1
	global_store_dwordx4 v[82:83], v[66:69], off offset:528 sc0 sc1
	s_nop 0
	v_lshl_add_u64 v[70:71], v[156:157], 0, s[20:21]
	v_lshlrev_b64 v[72:73], 1, v[70:71]
	v_lshl_add_u64 v[66:67], s[50:51], 0, v[72:73]
	global_load_dwordx4 v[66:69], v[66:67], off
	v_or_b32_e32 v72, 0x100, v72
	s_mov_b64 s[20:21], 0x48000
	s_waitcnt vmcnt(0)
	v_lshlrev_b32_e32 v74, 16, v66
	v_and_b32_e32 v75, 0xffff0000, v66
	v_lshlrev_b32_e32 v66, 16, v67
	v_and_b32_e32 v67, 0xffff0000, v67
	v_lshlrev_b32_e32 v76, 16, v68
	v_and_b32_e32 v77, 0xffff0000, v68
	v_pk_mul_f32 v[66:67], v[66:67], s[60:61] op_sel_hi:[1,0]
	v_lshlrev_b32_e32 v68, 16, v69
	v_and_b32_e32 v69, 0xffff0000, v69
	v_pk_mul_f32 v[74:75], v[74:75], s[60:61] op_sel_hi:[1,0]
	v_pk_fma_f32 v[64:65], v[64:65], v[152:153], v[66:67]
	v_pk_mul_f32 v[66:67], v[76:77], s[60:61] op_sel_hi:[1,0]
	v_pk_fma_f32 v[62:63], v[62:63], v[154:155], v[74:75]
	v_pk_mul_f32 v[68:69], v[68:69], s[60:61] op_sel_hi:[1,0]
	v_pk_fma_f32 v[58:59], v[58:59], v[150:151], v[66:67]
	v_lshl_add_u64 v[66:67], v[70:71], 2, s[36:37]
	v_pk_fma_f32 v[60:61], v[60:61], v[148:149], v[68:69]
	global_store_dwordx4 v[66:67], v[62:65], off sc0 sc1
	global_store_dwordx4 v[66:67], v[58:61], off offset:16 sc0 sc1
	s_nop 1
	v_lshl_add_u64 v[58:59], s[50:51], 0, v[72:73]
	global_load_dwordx4 v[58:61], v[58:59], off
	s_waitcnt vmcnt(0)
	v_lshlrev_b32_e32 v62, 16, v58
	v_and_b32_e32 v63, 0xffff0000, v58
	v_lshlrev_b32_e32 v58, 16, v59
	v_and_b32_e32 v59, 0xffff0000, v59
	v_lshlrev_b32_e32 v64, 16, v60
	v_and_b32_e32 v65, 0xffff0000, v60
	v_lshlrev_b32_e32 v60, 16, v61
	v_and_b32_e32 v61, 0xffff0000, v61
	v_pk_mul_f32 v[62:63], v[62:63], s[60:61] op_sel_hi:[1,0]
	v_pk_mul_f32 v[58:59], v[58:59], s[60:61] op_sel_hi:[1,0]
	v_pk_fma_f32 v[54:55], v[54:55], v[146:147], v[62:63]
	v_pk_fma_f32 v[56:57], v[56:57], v[144:145], v[58:59]
	v_pk_mul_f32 v[58:59], v[64:65], s[60:61] op_sel_hi:[1,0]
	v_pk_mul_f32 v[60:61], v[60:61], s[60:61] op_sel_hi:[1,0]
	v_pk_fma_f32 v[50:51], v[50:51], v[142:143], v[58:59]
	v_pk_fma_f32 v[52:53], v[52:53], v[140:141], v[60:61]
	global_store_dwordx4 v[66:67], v[54:57], off offset:512 sc0 sc1
	global_store_dwordx4 v[66:67], v[50:53], off offset:528 sc0 sc1
	s_nop 0
	v_lshl_add_u64 v[54:55], v[156:157], 0, s[20:21]
	v_lshlrev_b64 v[56:57], 1, v[54:55]
	v_lshl_add_u64 v[50:51], s[50:51], 0, v[56:57]
	global_load_dwordx4 v[50:53], v[50:51], off
	v_or_b32_e32 v56, 0x100, v56
	s_mov_b64 s[20:21], 0x50000
	s_waitcnt vmcnt(0)
	v_lshlrev_b32_e32 v58, 16, v50
	v_and_b32_e32 v59, 0xffff0000, v50
	v_lshlrev_b32_e32 v50, 16, v51
	v_and_b32_e32 v51, 0xffff0000, v51
	v_lshlrev_b32_e32 v60, 16, v52
	v_and_b32_e32 v61, 0xffff0000, v52
	v_pk_mul_f32 v[50:51], v[50:51], s[60:61] op_sel_hi:[1,0]
	v_lshlrev_b32_e32 v52, 16, v53
	v_and_b32_e32 v53, 0xffff0000, v53
	v_pk_mul_f32 v[58:59], v[58:59], s[60:61] op_sel_hi:[1,0]
	v_pk_fma_f32 v[48:49], v[48:49], v[152:153], v[50:51]
	v_pk_mul_f32 v[50:51], v[60:61], s[60:61] op_sel_hi:[1,0]
	v_pk_fma_f32 v[46:47], v[46:47], v[154:155], v[58:59]
	v_pk_mul_f32 v[52:53], v[52:53], s[60:61] op_sel_hi:[1,0]
	v_pk_fma_f32 v[42:43], v[42:43], v[150:151], v[50:51]
	v_lshl_add_u64 v[50:51], v[54:55], 2, s[36:37]
	v_pk_fma_f32 v[44:45], v[44:45], v[148:149], v[52:53]
	global_store_dwordx4 v[50:51], v[46:49], off sc0 sc1
	global_store_dwordx4 v[50:51], v[42:45], off offset:16 sc0 sc1
	s_nop 1
	v_lshl_add_u64 v[42:43], s[50:51], 0, v[56:57]
	global_load_dwordx4 v[42:45], v[42:43], off
	s_waitcnt vmcnt(0)
	v_lshlrev_b32_e32 v46, 16, v42
	v_and_b32_e32 v47, 0xffff0000, v42
	v_lshlrev_b32_e32 v42, 16, v43
	v_and_b32_e32 v43, 0xffff0000, v43
	v_lshlrev_b32_e32 v48, 16, v44
	v_and_b32_e32 v49, 0xffff0000, v44
	v_lshlrev_b32_e32 v44, 16, v45
	v_and_b32_e32 v45, 0xffff0000, v45
	v_pk_mul_f32 v[46:47], v[46:47], s[60:61] op_sel_hi:[1,0]
	v_pk_mul_f32 v[42:43], v[42:43], s[60:61] op_sel_hi:[1,0]
	v_pk_fma_f32 v[38:39], v[38:39], v[146:147], v[46:47]
	v_pk_fma_f32 v[40:41], v[40:41], v[144:145], v[42:43]
	v_pk_mul_f32 v[42:43], v[48:49], s[60:61] op_sel_hi:[1,0]
	v_pk_mul_f32 v[44:45], v[44:45], s[60:61] op_sel_hi:[1,0]
	v_pk_fma_f32 v[34:35], v[34:35], v[142:143], v[42:43]
	v_pk_fma_f32 v[36:37], v[36:37], v[140:141], v[44:45]
	global_store_dwordx4 v[50:51], v[38:41], off offset:512 sc0 sc1
	global_store_dwordx4 v[50:51], v[34:37], off offset:528 sc0 sc1
	s_nop 0
	v_lshl_add_u64 v[38:39], v[156:157], 0, s[20:21]
	v_lshlrev_b64 v[40:41], 1, v[38:39]
	v_lshl_add_u64 v[34:35], s[50:51], 0, v[40:41]
	global_load_dwordx4 v[34:37], v[34:35], off
	v_or_b32_e32 v40, 0x100, v40
	s_mov_b64 s[20:21], 0x58000
	s_waitcnt vmcnt(0)
	v_lshlrev_b32_e32 v42, 16, v34
	v_and_b32_e32 v43, 0xffff0000, v34
	v_lshlrev_b32_e32 v34, 16, v35
	v_and_b32_e32 v35, 0xffff0000, v35
	v_lshlrev_b32_e32 v44, 16, v36
	v_and_b32_e32 v45, 0xffff0000, v36
	v_pk_mul_f32 v[34:35], v[34:35], s[60:61] op_sel_hi:[1,0]
	v_lshlrev_b32_e32 v36, 16, v37
	v_and_b32_e32 v37, 0xffff0000, v37
	v_pk_mul_f32 v[42:43], v[42:43], s[60:61] op_sel_hi:[1,0]
	v_pk_fma_f32 v[32:33], v[32:33], v[152:153], v[34:35]
	v_pk_mul_f32 v[34:35], v[44:45], s[60:61] op_sel_hi:[1,0]
	v_pk_fma_f32 v[30:31], v[30:31], v[154:155], v[42:43]
	v_pk_mul_f32 v[36:37], v[36:37], s[60:61] op_sel_hi:[1,0]
	v_pk_fma_f32 v[26:27], v[26:27], v[150:151], v[34:35]
	v_lshl_add_u64 v[34:35], v[38:39], 2, s[36:37]
	v_pk_fma_f32 v[28:29], v[28:29], v[148:149], v[36:37]
	global_store_dwordx4 v[34:35], v[30:33], off sc0 sc1
	global_store_dwordx4 v[34:35], v[26:29], off offset:16 sc0 sc1
	s_nop 1
	v_lshl_add_u64 v[26:27], s[50:51], 0, v[40:41]
	global_load_dwordx4 v[26:29], v[26:27], off
	s_waitcnt vmcnt(0)
	v_lshlrev_b32_e32 v30, 16, v26
	v_and_b32_e32 v31, 0xffff0000, v26
	v_lshlrev_b32_e32 v26, 16, v27
	v_and_b32_e32 v27, 0xffff0000, v27
	v_lshlrev_b32_e32 v32, 16, v28
	v_and_b32_e32 v33, 0xffff0000, v28
	v_lshlrev_b32_e32 v28, 16, v29
	v_and_b32_e32 v29, 0xffff0000, v29
	v_pk_mul_f32 v[30:31], v[30:31], s[60:61] op_sel_hi:[1,0]
	v_pk_mul_f32 v[26:27], v[26:27], s[60:61] op_sel_hi:[1,0]
	v_pk_fma_f32 v[22:23], v[22:23], v[146:147], v[30:31]
	v_pk_fma_f32 v[24:25], v[24:25], v[144:145], v[26:27]
	v_pk_mul_f32 v[26:27], v[32:33], s[60:61] op_sel_hi:[1,0]
	v_pk_mul_f32 v[28:29], v[28:29], s[60:61] op_sel_hi:[1,0]
	v_pk_fma_f32 v[18:19], v[18:19], v[142:143], v[26:27]
	v_pk_fma_f32 v[20:21], v[20:21], v[140:141], v[28:29]
	global_store_dwordx4 v[34:35], v[22:25], off offset:512 sc0 sc1
	global_store_dwordx4 v[34:35], v[18:21], off offset:528 sc0 sc1
	s_nop 0
	v_lshl_add_u64 v[22:23], v[156:157], 0, s[20:21]
	v_lshlrev_b64 v[24:25], 1, v[22:23]
	v_lshl_add_u64 v[18:19], s[50:51], 0, v[24:25]
	global_load_dwordx4 v[18:21], v[18:19], off
	v_or_b32_e32 v24, 0x100, v24
	s_mov_b64 s[20:21], -1
	s_waitcnt vmcnt(0)
	v_lshlrev_b32_e32 v26, 16, v18
	v_and_b32_e32 v27, 0xffff0000, v18
	v_lshlrev_b32_e32 v18, 16, v19
	v_and_b32_e32 v19, 0xffff0000, v19
	v_lshlrev_b32_e32 v28, 16, v20
	v_and_b32_e32 v29, 0xffff0000, v20
	v_pk_mul_f32 v[18:19], v[18:19], s[60:61] op_sel_hi:[1,0]
	v_lshlrev_b32_e32 v20, 16, v21
	v_and_b32_e32 v21, 0xffff0000, v21
	v_pk_mul_f32 v[26:27], v[26:27], s[60:61] op_sel_hi:[1,0]
	v_pk_fma_f32 v[16:17], v[16:17], v[152:153], v[18:19]
	v_pk_mul_f32 v[18:19], v[28:29], s[60:61] op_sel_hi:[1,0]
	v_pk_fma_f32 v[14:15], v[14:15], v[154:155], v[26:27]
	v_pk_mul_f32 v[20:21], v[20:21], s[60:61] op_sel_hi:[1,0]
	v_pk_fma_f32 v[10:11], v[10:11], v[150:151], v[18:19]
	v_lshl_add_u64 v[18:19], v[22:23], 2, s[36:37]
	v_pk_fma_f32 v[12:13], v[12:13], v[148:149], v[20:21]
	global_store_dwordx4 v[18:19], v[14:17], off sc0 sc1
	global_store_dwordx4 v[18:19], v[10:13], off offset:16 sc0 sc1
	s_nop 1
	v_lshl_add_u64 v[10:11], s[50:51], 0, v[24:25]
	global_load_dwordx4 v[10:13], v[10:11], off
	s_waitcnt vmcnt(0)
	v_lshlrev_b32_e32 v14, 16, v10
	v_and_b32_e32 v15, 0xffff0000, v10
	v_lshlrev_b32_e32 v10, 16, v11
	v_and_b32_e32 v11, 0xffff0000, v11
	v_lshlrev_b32_e32 v16, 16, v12
	v_and_b32_e32 v17, 0xffff0000, v12
	v_lshlrev_b32_e32 v12, 16, v13
	v_and_b32_e32 v13, 0xffff0000, v13
	v_pk_mul_f32 v[14:15], v[14:15], s[60:61] op_sel_hi:[1,0]
	v_pk_mul_f32 v[10:11], v[10:11], s[60:61] op_sel_hi:[1,0]
	v_pk_fma_f32 v[6:7], v[6:7], v[146:147], v[14:15]
	v_pk_fma_f32 v[8:9], v[8:9], v[144:145], v[10:11]
	v_pk_mul_f32 v[10:11], v[16:17], s[60:61] op_sel_hi:[1,0]
	v_pk_mul_f32 v[12:13], v[12:13], s[60:61] op_sel_hi:[1,0]
	v_pk_fma_f32 v[2:3], v[2:3], v[142:143], v[10:11]
	v_pk_fma_f32 v[4:5], v[4:5], v[140:141], v[12:13]
	global_store_dwordx4 v[18:19], v[6:9], off offset:512 sc0 sc1
	global_store_dwordx4 v[18:19], v[2:5], off offset:528 sc0 sc1
	s_cbranch_vccnz .LBB0_1016
	s_andn2_b64 vcc, exec, s[8:9]
	s_cbranch_vccnz .LBB0_1015
	s_barrier
	s_branch .LBB0_1015

.LBB0_1049:
	v_lshl_or_b32 v160, s40, 8, v164
	v_ashrrev_i32_e32 v161, 31, v160
	v_lshl_add_u64 v[166:167], v[160:161], 2, s[6:7]
	global_load_dwordx4 v[140:143], v[166:167], off offset:16
	global_load_dwordx4 v[144:147], v[166:167], off
	v_lshlrev_b64 v[160:161], 1, v[160:161]
	s_mov_b32 s3, 0x80000
	s_mov_b64 s[18:19], 0x80000
	s_mov_b32 s42, 0xc000
	s_waitcnt vmcnt(0)
	v_pk_add_f32 v[148:149], v[142:143], 1.0 op_sel_hi:[1,0]
	v_pk_add_f32 v[150:151], v[140:141], 1.0 op_sel_hi:[1,0]
	global_load_dwordx4 v[156:159], v[166:167], off offset:528
	global_load_dwordx4 v[140:143], v[166:167], off offset:512
	v_pk_add_f32 v[152:153], v[146:147], 1.0 op_sel_hi:[1,0]
	v_pk_add_f32 v[154:155], v[144:145], 1.0 op_sel_hi:[1,0]
	s_waitcnt vmcnt(0)
	v_pk_add_f32 v[146:147], v[140:141], 1.0 op_sel_hi:[1,0]
	v_pk_add_f32 v[140:141], v[158:159], 1.0 op_sel_hi:[1,0]
	v_lshl_add_u32 v158, s35, 8, v162
	v_ashrrev_i32_e32 v159, 31, v158
	v_pk_add_f32 v[144:145], v[142:143], 1.0 op_sel_hi:[1,0]
	v_pk_add_f32 v[142:143], v[156:157], 1.0 op_sel_hi:[1,0]
	v_lshlrev_b64 v[156:157], 12, v[158:159]
	v_lshl_add_u64 v[156:157], s[50:51], 0, v[156:157]
	v_lshl_add_u64 v[156:157], v[156:157], 0, v[160:161]
	global_load_dwordx4 v[166:169], v[156:157], off
	s_waitcnt vmcnt(0)
	v_lshlrev_b32_e32 v170, 16, v166
	v_and_b32_e32 v171, 0xffff0000, v166
	v_lshlrev_b32_e32 v166, 16, v167
	v_and_b32_e32 v167, 0xffff0000, v167
	v_lshlrev_b32_e32 v172, 16, v168
	v_and_b32_e32 v173, 0xffff0000, v168
	v_lshlrev_b32_e32 v168, 16, v169
	v_and_b32_e32 v169, 0xffff0000, v169
	v_pk_mul_f32 v[166:167], v[166:167], s[60:61] op_sel_hi:[1,0]
	v_pk_mul_f32 v[170:171], v[170:171], s[60:61] op_sel_hi:[1,0]
	v_pk_fma_f32 v[128:129], v[128:129], v[152:153], v[166:167]
	v_pk_mul_f32 v[166:167], v[172:173], s[60:61] op_sel_hi:[1,0]
	v_pk_mul_f32 v[168:169], v[168:169], s[60:61] op_sel_hi:[1,0]
	v_pk_fma_f32 v[126:127], v[126:127], v[154:155], v[170:171]
	v_pk_fma_f32 v[168:169], v[124:125], v[148:149], v[168:169]
	v_pk_fma_f32 v[124:125], v[122:123], v[150:151], v[166:167]
	v_cvt_pk_bf16_f32 v122, v126, v127
	v_cvt_pk_bf16_f32 v123, v128, v129
	v_cvt_pk_bf16_f32 v124, v124, v125
	v_cvt_pk_bf16_f32 v125, v168, v169
	global_store_dwordx4 v[156:157], v[122:125], off sc0 sc1
	global_load_dwordx4 v[122:125], v[156:157], off offset:256
	s_waitcnt vmcnt(0)
	v_lshlrev_b32_e32 v126, 16, v122
	v_and_b32_e32 v127, 0xffff0000, v122
	v_lshlrev_b32_e32 v122, 16, v123
	v_and_b32_e32 v123, 0xffff0000, v123
	v_lshlrev_b32_e32 v128, 16, v124
	v_and_b32_e32 v129, 0xffff0000, v124
	v_lshlrev_b32_e32 v124, 16, v125
	v_and_b32_e32 v125, 0xffff0000, v125
	v_pk_mul_f32 v[122:123], v[122:123], s[60:61] op_sel_hi:[1,0]
	v_pk_mul_f32 v[126:127], v[126:127], s[60:61] op_sel_hi:[1,0]
	v_pk_fma_f32 v[120:121], v[120:121], v[144:145], v[122:123]
	v_pk_mul_f32 v[122:123], v[128:129], s[60:61] op_sel_hi:[1,0]
	v_pk_mul_f32 v[124:125], v[124:125], s[60:61] op_sel_hi:[1,0]
	v_pk_fma_f32 v[118:119], v[118:119], v[146:147], v[126:127]
	v_pk_fma_f32 v[124:125], v[116:117], v[140:141], v[124:125]
	v_pk_fma_f32 v[116:117], v[114:115], v[142:143], v[122:123]
	v_cvt_pk_bf16_f32 v114, v118, v119
	v_cvt_pk_bf16_f32 v115, v120, v121
	v_cvt_pk_bf16_f32 v116, v116, v117
	v_cvt_pk_bf16_f32 v117, v124, v125
	global_store_dwordx4 v[156:157], v[114:117], off offset:256 sc0 sc1
	s_nop 1
	v_or_b32_e32 v114, 16, v158
	v_ashrrev_i32_e32 v115, 31, v114
	v_lshlrev_b64 v[114:115], 12, v[114:115]
	v_lshl_add_u64 v[114:115], s[50:51], 0, v[114:115]
	v_lshl_add_u64 v[118:119], v[114:115], 0, v[160:161]
	global_load_dwordx4 v[114:117], v[118:119], off
	s_waitcnt vmcnt(0)
	v_lshlrev_b32_e32 v120, 16, v114
	v_and_b32_e32 v121, 0xffff0000, v114
	v_lshlrev_b32_e32 v114, 16, v115
	v_and_b32_e32 v115, 0xffff0000, v115
	v_lshlrev_b32_e32 v122, 16, v116
	v_and_b32_e32 v123, 0xffff0000, v116
	v_lshlrev_b32_e32 v116, 16, v117
	v_and_b32_e32 v117, 0xffff0000, v117
	v_pk_mul_f32 v[114:115], v[114:115], s[60:61] op_sel_hi:[1,0]
	v_pk_mul_f32 v[120:121], v[120:121], s[60:61] op_sel_hi:[1,0]
	v_pk_fma_f32 v[112:113], v[112:113], v[152:153], v[114:115]
	v_pk_mul_f32 v[114:115], v[122:123], s[60:61] op_sel_hi:[1,0]
	v_pk_mul_f32 v[116:117], v[116:117], s[60:61] op_sel_hi:[1,0]
	v_pk_fma_f32 v[110:111], v[110:111], v[154:155], v[120:121]
	v_pk_fma_f32 v[116:117], v[108:109], v[148:149], v[116:117]
	v_pk_fma_f32 v[108:109], v[106:107], v[150:151], v[114:115]
	v_cvt_pk_bf16_f32 v106, v110, v111
	v_cvt_pk_bf16_f32 v107, v112, v113
	v_cvt_pk_bf16_f32 v108, v108, v109
	v_cvt_pk_bf16_f32 v109, v116, v117
	global_store_dwordx4 v[118:119], v[106:109], off sc0 sc1
	global_load_dwordx4 v[106:109], v[118:119], off offset:256
	s_waitcnt vmcnt(0)
	v_lshlrev_b32_e32 v110, 16, v106
	v_and_b32_e32 v111, 0xffff0000, v106
	v_lshlrev_b32_e32 v106, 16, v107
	v_and_b32_e32 v107, 0xffff0000, v107
	v_lshlrev_b32_e32 v112, 16, v108
	v_and_b32_e32 v113, 0xffff0000, v108
	v_lshlrev_b32_e32 v108, 16, v109
	v_and_b32_e32 v109, 0xffff0000, v109
	v_pk_mul_f32 v[106:107], v[106:107], s[60:61] op_sel_hi:[1,0]
	v_pk_mul_f32 v[110:111], v[110:111], s[60:61] op_sel_hi:[1,0]
	v_pk_fma_f32 v[104:105], v[104:105], v[144:145], v[106:107]
	v_pk_mul_f32 v[106:107], v[112:113], s[60:61] op_sel_hi:[1,0]
	v_pk_mul_f32 v[108:109], v[108:109], s[60:61] op_sel_hi:[1,0]
	v_pk_fma_f32 v[102:103], v[102:103], v[146:147], v[110:111]
	v_pk_fma_f32 v[108:109], v[100:101], v[140:141], v[108:109]
	v_pk_fma_f32 v[100:101], v[98:99], v[142:143], v[106:107]
	v_cvt_pk_bf16_f32 v98, v102, v103
	v_cvt_pk_bf16_f32 v99, v104, v105
	v_cvt_pk_bf16_f32 v100, v100, v101
	v_cvt_pk_bf16_f32 v101, v108, v109
	global_store_dwordx4 v[118:119], v[98:101], off offset:256 sc0 sc1
	s_nop 1
	v_or_b32_e32 v98, 32, v158
	v_ashrrev_i32_e32 v99, 31, v98
	v_lshlrev_b64 v[98:99], 12, v[98:99]
	v_lshl_add_u64 v[98:99], s[50:51], 0, v[98:99]
	v_lshl_add_u64 v[102:103], v[98:99], 0, v[160:161]
	global_load_dwordx4 v[98:101], v[102:103], off
	s_waitcnt vmcnt(0)
	v_lshlrev_b32_e32 v104, 16, v98
	v_and_b32_e32 v105, 0xffff0000, v98
	v_lshlrev_b32_e32 v98, 16, v99
	v_and_b32_e32 v99, 0xffff0000, v99
	v_lshlrev_b32_e32 v106, 16, v100
	v_and_b32_e32 v107, 0xffff0000, v100
	v_lshlrev_b32_e32 v100, 16, v101
	v_and_b32_e32 v101, 0xffff0000, v101
	v_pk_mul_f32 v[98:99], v[98:99], s[60:61] op_sel_hi:[1,0]
	v_pk_mul_f32 v[104:105], v[104:105], s[60:61] op_sel_hi:[1,0]
	v_pk_fma_f32 v[96:97], v[96:97], v[152:153], v[98:99]
	v_pk_mul_f32 v[98:99], v[106:107], s[60:61] op_sel_hi:[1,0]
	v_pk_mul_f32 v[100:101], v[100:101], s[60:61] op_sel_hi:[1,0]
	v_pk_fma_f32 v[94:95], v[94:95], v[154:155], v[104:105]
	v_pk_fma_f32 v[100:101], v[92:93], v[148:149], v[100:101]
	v_pk_fma_f32 v[92:93], v[90:91], v[150:151], v[98:99]
	v_cvt_pk_bf16_f32 v90, v94, v95
	v_cvt_pk_bf16_f32 v91, v96, v97
	v_cvt_pk_bf16_f32 v92, v92, v93
	v_cvt_pk_bf16_f32 v93, v100, v101
	global_store_dwordx4 v[102:103], v[90:93], off sc0 sc1
	global_load_dwordx4 v[90:93], v[102:103], off offset:256
	s_waitcnt vmcnt(0)
	v_lshlrev_b32_e32 v94, 16, v90
	v_and_b32_e32 v95, 0xffff0000, v90
	v_lshlrev_b32_e32 v90, 16, v91
	v_and_b32_e32 v91, 0xffff0000, v91
	v_lshlrev_b32_e32 v96, 16, v92
	v_and_b32_e32 v97, 0xffff0000, v92
	v_lshlrev_b32_e32 v92, 16, v93
	v_and_b32_e32 v93, 0xffff0000, v93
	v_pk_mul_f32 v[90:91], v[90:91], s[60:61] op_sel_hi:[1,0]
	v_pk_mul_f32 v[94:95], v[94:95], s[60:61] op_sel_hi:[1,0]
	v_pk_fma_f32 v[88:89], v[88:89], v[144:145], v[90:91]
	v_pk_mul_f32 v[90:91], v[96:97], s[60:61] op_sel_hi:[1,0]
	v_pk_mul_f32 v[92:93], v[92:93], s[60:61] op_sel_hi:[1,0]
	v_pk_fma_f32 v[86:87], v[86:87], v[146:147], v[94:95]
	v_pk_fma_f32 v[92:93], v[84:85], v[140:141], v[92:93]
	v_pk_fma_f32 v[84:85], v[82:83], v[142:143], v[90:91]
	v_cvt_pk_bf16_f32 v82, v86, v87
	v_cvt_pk_bf16_f32 v83, v88, v89
	v_cvt_pk_bf16_f32 v84, v84, v85
	v_cvt_pk_bf16_f32 v85, v92, v93
	global_store_dwordx4 v[102:103], v[82:85], off offset:256 sc0 sc1
	s_nop 1
	v_or_b32_e32 v82, 48, v158
	v_ashrrev_i32_e32 v83, 31, v82
	v_lshlrev_b64 v[82:83], 12, v[82:83]
	v_lshl_add_u64 v[82:83], s[50:51], 0, v[82:83]
	v_lshl_add_u64 v[86:87], v[82:83], 0, v[160:161]
	global_load_dwordx4 v[82:85], v[86:87], off
	s_waitcnt vmcnt(0)
	v_lshlrev_b32_e32 v88, 16, v82
	v_and_b32_e32 v89, 0xffff0000, v82
	v_lshlrev_b32_e32 v82, 16, v83
	v_and_b32_e32 v83, 0xffff0000, v83
	v_lshlrev_b32_e32 v90, 16, v84
	v_and_b32_e32 v91, 0xffff0000, v84
	v_lshlrev_b32_e32 v84, 16, v85
	v_and_b32_e32 v85, 0xffff0000, v85
	v_pk_mul_f32 v[82:83], v[82:83], s[60:61] op_sel_hi:[1,0]
	v_pk_mul_f32 v[88:89], v[88:89], s[60:61] op_sel_hi:[1,0]
	v_pk_fma_f32 v[80:81], v[80:81], v[152:153], v[82:83]
	v_pk_mul_f32 v[82:83], v[90:91], s[60:61] op_sel_hi:[1,0]
	v_pk_mul_f32 v[84:85], v[84:85], s[60:61] op_sel_hi:[1,0]
	v_pk_fma_f32 v[78:79], v[78:79], v[154:155], v[88:89]
	v_pk_fma_f32 v[84:85], v[76:77], v[148:149], v[84:85]
	v_pk_fma_f32 v[76:77], v[74:75], v[150:151], v[82:83]
	v_cvt_pk_bf16_f32 v74, v78, v79
	v_cvt_pk_bf16_f32 v75, v80, v81
	v_cvt_pk_bf16_f32 v76, v76, v77
	v_cvt_pk_bf16_f32 v77, v84, v85
	global_store_dwordx4 v[86:87], v[74:77], off sc0 sc1
	global_load_dwordx4 v[74:77], v[86:87], off offset:256
	s_waitcnt vmcnt(0)
	v_lshlrev_b32_e32 v78, 16, v74
	v_and_b32_e32 v79, 0xffff0000, v74
	v_lshlrev_b32_e32 v74, 16, v75
	v_and_b32_e32 v75, 0xffff0000, v75
	v_lshlrev_b32_e32 v80, 16, v76
	v_and_b32_e32 v81, 0xffff0000, v76
	v_lshlrev_b32_e32 v76, 16, v77
	v_and_b32_e32 v77, 0xffff0000, v77
	v_pk_mul_f32 v[74:75], v[74:75], s[60:61] op_sel_hi:[1,0]
	v_pk_mul_f32 v[78:79], v[78:79], s[60:61] op_sel_hi:[1,0]
	v_pk_fma_f32 v[72:73], v[72:73], v[144:145], v[74:75]
	v_pk_mul_f32 v[74:75], v[80:81], s[60:61] op_sel_hi:[1,0]
	v_pk_mul_f32 v[76:77], v[76:77], s[60:61] op_sel_hi:[1,0]
	v_pk_fma_f32 v[70:71], v[70:71], v[146:147], v[78:79]
	v_pk_fma_f32 v[76:77], v[68:69], v[140:141], v[76:77]
	v_pk_fma_f32 v[68:69], v[66:67], v[142:143], v[74:75]
	v_cvt_pk_bf16_f32 v67, v72, v73
	v_add_co_u32_e32 v72, vcc, s3, v156
	v_cvt_pk_bf16_f32 v66, v70, v71
	v_cvt_pk_bf16_f32 v68, v68, v69
	v_cvt_pk_bf16_f32 v69, v76, v77
	v_addc_co_u32_e32 v73, vcc, 0, v157, vcc
	global_store_dwordx4 v[86:87], v[66:69], off offset:256 sc0 sc1
	global_load_dwordx4 v[68:71], v[72:73], off
	s_mov_b32 s3, 0x90000
	v_lshl_add_u64 v[66:67], v[156:157], 0, s[18:19]
	s_mov_b64 s[18:19], 0x90000
	s_waitcnt vmcnt(0)
	v_lshlrev_b32_e32 v74, 16, v68
	v_and_b32_e32 v75, 0xffff0000, v68
	v_lshlrev_b32_e32 v68, 16, v69
	v_and_b32_e32 v69, 0xffff0000, v69
	v_lshlrev_b32_e32 v76, 16, v70
	v_and_b32_e32 v77, 0xffff0000, v70
	v_lshlrev_b32_e32 v70, 16, v71
	v_and_b32_e32 v71, 0xffff0000, v71
	v_pk_mul_f32 v[68:69], v[68:69], s[60:61] op_sel_hi:[1,0]
	v_pk_mul_f32 v[74:75], v[74:75], s[60:61] op_sel_hi:[1,0]
	v_pk_fma_f32 v[64:65], v[64:65], v[152:153], v[68:69]
	v_pk_mul_f32 v[68:69], v[76:77], s[60:61] op_sel_hi:[1,0]
	v_pk_mul_f32 v[70:71], v[70:71], s[60:61] op_sel_hi:[1,0]
	v_pk_fma_f32 v[62:63], v[62:63], v[154:155], v[74:75]
	v_pk_fma_f32 v[70:71], v[60:61], v[148:149], v[70:71]
	v_pk_fma_f32 v[60:61], v[58:59], v[150:151], v[68:69]
	v_cvt_pk_bf16_f32 v58, v62, v63
	v_cvt_pk_bf16_f32 v59, v64, v65
	v_cvt_pk_bf16_f32 v60, v60, v61
	v_cvt_pk_bf16_f32 v61, v70, v71
	global_store_dwordx4 v[72:73], v[58:61], off sc0 sc1
	global_load_dwordx4 v[58:61], v[66:67], off offset:256
	s_waitcnt vmcnt(0)
	v_lshlrev_b32_e32 v62, 16, v58
	v_and_b32_e32 v63, 0xffff0000, v58
	v_lshlrev_b32_e32 v58, 16, v59
	v_and_b32_e32 v59, 0xffff0000, v59
	v_lshlrev_b32_e32 v64, 16, v60
	v_and_b32_e32 v65, 0xffff0000, v60
	v_lshlrev_b32_e32 v60, 16, v61
	v_and_b32_e32 v61, 0xffff0000, v61
	v_pk_mul_f32 v[58:59], v[58:59], s[60:61] op_sel_hi:[1,0]
	v_pk_mul_f32 v[62:63], v[62:63], s[60:61] op_sel_hi:[1,0]
	v_pk_fma_f32 v[56:57], v[56:57], v[144:145], v[58:59]
	v_pk_mul_f32 v[58:59], v[64:65], s[60:61] op_sel_hi:[1,0]
	v_pk_mul_f32 v[60:61], v[60:61], s[60:61] op_sel_hi:[1,0]
	v_pk_fma_f32 v[54:55], v[54:55], v[146:147], v[62:63]
	v_pk_fma_f32 v[60:61], v[52:53], v[140:141], v[60:61]
	v_pk_fma_f32 v[52:53], v[50:51], v[142:143], v[58:59]
	v_cvt_pk_bf16_f32 v51, v56, v57
	v_add_co_u32_e32 v56, vcc, s3, v156
	v_cvt_pk_bf16_f32 v50, v54, v55
	v_cvt_pk_bf16_f32 v52, v52, v53
	v_cvt_pk_bf16_f32 v53, v60, v61
	v_addc_co_u32_e32 v57, vcc, 0, v157, vcc
	global_store_dwordx4 v[66:67], v[50:53], off offset:256 sc0 sc1
	global_load_dwordx4 v[52:55], v[56:57], off
	s_mov_b32 s3, 0xa0000
	v_lshl_add_u64 v[50:51], v[156:157], 0, s[18:19]
	s_mov_b64 s[18:19], 0xa0000
	s_waitcnt vmcnt(0)
	v_lshlrev_b32_e32 v58, 16, v52
	v_and_b32_e32 v59, 0xffff0000, v52
	v_lshlrev_b32_e32 v52, 16, v53
	v_and_b32_e32 v53, 0xffff0000, v53
	v_lshlrev_b32_e32 v60, 16, v54
	v_and_b32_e32 v61, 0xffff0000, v54
	v_lshlrev_b32_e32 v54, 16, v55
	v_and_b32_e32 v55, 0xffff0000, v55
	v_pk_mul_f32 v[52:53], v[52:53], s[60:61] op_sel_hi:[1,0]
	v_pk_mul_f32 v[58:59], v[58:59], s[60:61] op_sel_hi:[1,0]
	v_pk_fma_f32 v[48:49], v[48:49], v[152:153], v[52:53]
	v_pk_mul_f32 v[52:53], v[60:61], s[60:61] op_sel_hi:[1,0]
	v_pk_mul_f32 v[54:55], v[54:55], s[60:61] op_sel_hi:[1,0]
	v_pk_fma_f32 v[46:47], v[46:47], v[154:155], v[58:59]
	v_pk_fma_f32 v[54:55], v[44:45], v[148:149], v[54:55]
	v_pk_fma_f32 v[44:45], v[42:43], v[150:151], v[52:53]
	v_cvt_pk_bf16_f32 v42, v46, v47
	v_cvt_pk_bf16_f32 v43, v48, v49
	v_cvt_pk_bf16_f32 v44, v44, v45
	v_cvt_pk_bf16_f32 v45, v54, v55
	global_store_dwordx4 v[56:57], v[42:45], off sc0 sc1
	global_load_dwordx4 v[42:45], v[50:51], off offset:256
	s_waitcnt vmcnt(0)
	v_lshlrev_b32_e32 v46, 16, v42
	v_and_b32_e32 v47, 0xffff0000, v42
	v_lshlrev_b32_e32 v42, 16, v43
	v_and_b32_e32 v43, 0xffff0000, v43
	v_lshlrev_b32_e32 v48, 16, v44
	v_and_b32_e32 v49, 0xffff0000, v44
	v_lshlrev_b32_e32 v44, 16, v45
	v_and_b32_e32 v45, 0xffff0000, v45
	v_pk_mul_f32 v[42:43], v[42:43], s[60:61] op_sel_hi:[1,0]
	v_pk_mul_f32 v[46:47], v[46:47], s[60:61] op_sel_hi:[1,0]
	v_pk_fma_f32 v[40:41], v[40:41], v[144:145], v[42:43]
	v_pk_mul_f32 v[42:43], v[48:49], s[60:61] op_sel_hi:[1,0]
	v_pk_mul_f32 v[44:45], v[44:45], s[60:61] op_sel_hi:[1,0]
	v_pk_fma_f32 v[38:39], v[38:39], v[146:147], v[46:47]
	v_pk_fma_f32 v[44:45], v[36:37], v[140:141], v[44:45]
	v_pk_fma_f32 v[36:37], v[34:35], v[142:143], v[42:43]
	v_cvt_pk_bf16_f32 v35, v40, v41
	v_add_co_u32_e32 v40, vcc, s3, v156
	v_cvt_pk_bf16_f32 v34, v38, v39
	v_cvt_pk_bf16_f32 v36, v36, v37
	v_cvt_pk_bf16_f32 v37, v44, v45
	v_addc_co_u32_e32 v41, vcc, 0, v157, vcc
	global_store_dwordx4 v[50:51], v[34:37], off offset:256 sc0 sc1
	global_load_dwordx4 v[36:39], v[40:41], off
	s_mov_b32 s3, 0xb0000
	v_lshl_add_u64 v[34:35], v[156:157], 0, s[18:19]
	s_mov_b64 s[18:19], 0xb0000
	s_waitcnt vmcnt(0)
	v_lshlrev_b32_e32 v42, 16, v36
	v_and_b32_e32 v43, 0xffff0000, v36
	v_lshlrev_b32_e32 v36, 16, v37
	v_and_b32_e32 v37, 0xffff0000, v37
	v_lshlrev_b32_e32 v44, 16, v38
	v_and_b32_e32 v45, 0xffff0000, v38
	v_lshlrev_b32_e32 v38, 16, v39
	v_and_b32_e32 v39, 0xffff0000, v39
	v_pk_mul_f32 v[36:37], v[36:37], s[60:61] op_sel_hi:[1,0]
	v_pk_mul_f32 v[42:43], v[42:43], s[60:61] op_sel_hi:[1,0]
	v_pk_fma_f32 v[32:33], v[32:33], v[152:153], v[36:37]
	v_pk_mul_f32 v[36:37], v[44:45], s[60:61] op_sel_hi:[1,0]
	v_pk_mul_f32 v[38:39], v[38:39], s[60:61] op_sel_hi:[1,0]
	v_pk_fma_f32 v[30:31], v[30:31], v[154:155], v[42:43]
	v_pk_fma_f32 v[38:39], v[28:29], v[148:149], v[38:39]
	v_pk_fma_f32 v[28:29], v[26:27], v[150:151], v[36:37]
	v_cvt_pk_bf16_f32 v26, v30, v31
	v_cvt_pk_bf16_f32 v27, v32, v33
	v_cvt_pk_bf16_f32 v28, v28, v29
	v_cvt_pk_bf16_f32 v29, v38, v39
	global_store_dwordx4 v[40:41], v[26:29], off sc0 sc1
	global_load_dwordx4 v[26:29], v[34:35], off offset:256
	s_waitcnt vmcnt(0)
	v_lshlrev_b32_e32 v30, 16, v26
	v_and_b32_e32 v31, 0xffff0000, v26
	v_lshlrev_b32_e32 v26, 16, v27
	v_and_b32_e32 v27, 0xffff0000, v27
	v_lshlrev_b32_e32 v32, 16, v28
	v_and_b32_e32 v33, 0xffff0000, v28
	v_lshlrev_b32_e32 v28, 16, v29
	v_and_b32_e32 v29, 0xffff0000, v29
	v_pk_mul_f32 v[26:27], v[26:27], s[60:61] op_sel_hi:[1,0]
	v_pk_mul_f32 v[30:31], v[30:31], s[60:61] op_sel_hi:[1,0]
	v_pk_fma_f32 v[24:25], v[24:25], v[144:145], v[26:27]
	v_pk_mul_f32 v[26:27], v[32:33], s[60:61] op_sel_hi:[1,0]
	v_pk_mul_f32 v[28:29], v[28:29], s[60:61] op_sel_hi:[1,0]
	v_pk_fma_f32 v[22:23], v[22:23], v[146:147], v[30:31]
	v_pk_fma_f32 v[28:29], v[20:21], v[140:141], v[28:29]
	v_pk_fma_f32 v[20:21], v[18:19], v[142:143], v[26:27]
	v_cvt_pk_bf16_f32 v19, v24, v25
	v_add_co_u32_e32 v24, vcc, s3, v156
	v_cvt_pk_bf16_f32 v18, v22, v23
	v_cvt_pk_bf16_f32 v20, v20, v21
	v_cvt_pk_bf16_f32 v21, v28, v29
	v_addc_co_u32_e32 v25, vcc, 0, v157, vcc
	global_store_dwordx4 v[34:35], v[18:21], off offset:256 sc0 sc1
	global_load_dwordx4 v[20:23], v[24:25], off
	s_andn2_b64 vcc, exec, s[0:1]
	v_lshl_add_u64 v[18:19], v[156:157], 0, s[18:19]
	s_mov_b64 s[18:19], -1
	s_waitcnt vmcnt(0)
	v_lshlrev_b32_e32 v26, 16, v20
	v_and_b32_e32 v27, 0xffff0000, v20
	v_lshlrev_b32_e32 v20, 16, v21
	v_and_b32_e32 v21, 0xffff0000, v21
	v_lshlrev_b32_e32 v28, 16, v22
	v_and_b32_e32 v29, 0xffff0000, v22
	v_lshlrev_b32_e32 v22, 16, v23
	v_and_b32_e32 v23, 0xffff0000, v23
	v_pk_mul_f32 v[20:21], v[20:21], s[60:61] op_sel_hi:[1,0]
	v_pk_mul_f32 v[26:27], v[26:27], s[60:61] op_sel_hi:[1,0]
	v_pk_fma_f32 v[16:17], v[16:17], v[152:153], v[20:21]
	v_pk_mul_f32 v[20:21], v[28:29], s[60:61] op_sel_hi:[1,0]
	v_pk_mul_f32 v[22:23], v[22:23], s[60:61] op_sel_hi:[1,0]
	v_pk_fma_f32 v[14:15], v[14:15], v[154:155], v[26:27]
	v_pk_fma_f32 v[22:23], v[12:13], v[148:149], v[22:23]
	v_pk_fma_f32 v[12:13], v[10:11], v[150:151], v[20:21]
	v_cvt_pk_bf16_f32 v10, v14, v15
	v_cvt_pk_bf16_f32 v11, v16, v17
	v_cvt_pk_bf16_f32 v12, v12, v13
	v_cvt_pk_bf16_f32 v13, v22, v23
	global_store_dwordx4 v[24:25], v[10:13], off sc0 sc1
	global_load_dwordx4 v[10:13], v[18:19], off offset:256
	s_waitcnt vmcnt(0)
	v_lshlrev_b32_e32 v14, 16, v10
	v_and_b32_e32 v15, 0xffff0000, v10
	v_lshlrev_b32_e32 v10, 16, v11
	v_and_b32_e32 v11, 0xffff0000, v11
	v_lshlrev_b32_e32 v16, 16, v12
	v_and_b32_e32 v17, 0xffff0000, v12
	v_lshlrev_b32_e32 v12, 16, v13
	v_and_b32_e32 v13, 0xffff0000, v13
	v_pk_mul_f32 v[10:11], v[10:11], s[60:61] op_sel_hi:[1,0]
	v_pk_mul_f32 v[14:15], v[14:15], s[60:61] op_sel_hi:[1,0]
	v_pk_fma_f32 v[8:9], v[8:9], v[144:145], v[10:11]
	v_pk_mul_f32 v[10:11], v[16:17], s[60:61] op_sel_hi:[1,0]
	v_pk_mul_f32 v[12:13], v[12:13], s[60:61] op_sel_hi:[1,0]
	v_pk_fma_f32 v[6:7], v[6:7], v[146:147], v[14:15]
	v_pk_fma_f32 v[12:13], v[4:5], v[140:141], v[12:13]
	v_pk_fma_f32 v[4:5], v[2:3], v[142:143], v[10:11]
	v_cvt_pk_bf16_f32 v2, v6, v7
	v_cvt_pk_bf16_f32 v3, v8, v9
	v_cvt_pk_bf16_f32 v4, v4, v5
	v_cvt_pk_bf16_f32 v5, v12, v13
	global_store_dwordx4 v[18:19], v[2:5], off offset:256 sc0 sc1
	s_cbranch_vccnz .LBB0_1038
	s_andn2_b64 vcc, exec, s[4:5]
	s_cbranch_vccnz .LBB0_1037
	s_barrier
	s_branch .LBB0_1037
